# fp8 row scales su/sv stored interleaved (8 bytes per expert): U pass finish fetches both with one 8-byte gather
# speedup vs baseline: 1.0053x; 1.0020x over previous
; DI int vb_id() { return (int)blockIdx.x + half_id() * (int)gridDim.x; }
; DI int vb_n() { return (int)gridDim.x * 2; }
; DI void phase_prep(const Params& p, char* smem, int part, int vb) {
;     ...
;   } else {
;     const int NITEMS = 1024 + 1024 + 128 + 128 + 256 + 512 + 32;
;     for (int it0 = vb; it0 < NITEMS; it0 += vb_n()) {
;       int it = it0;
;       if (it < 1024) {
;         int row = it * 16 + wave * 4;
;         fp8_rows<4>(p.pu + (size_t)row * 1024, (unsigned char*)(ws + WS_UBF) + (size_t)row * 1024, (float*)(ws + WS_SU) + row, lane);
;         continue;
;       }
;       it -= 1024;
;       if (it < 1024) {
;         int row = it * 16 + wave * 4;
;         fp8_rows<4>(p.pv + (size_t)row * 1024, (unsigned char*)(ws + WS_VBF) + (size_t)row * 1024, (float*)(ws + WS_SV) + row, lane);
;         continue;
;       }
;       it -= 1024;
; __global__ void __launch_bounds__(512) fwd_megakernel(Params p) {
;     ...
;   phase_prep(p, hsm, 1, (vb_id() + vb_n() - 128) % vb_n());
.LBB0_529:
	v_writelane_b32 v253, s58, 32
	s_nop 1
	v_writelane_b32 v253, s59, 33
	v_writelane_b32 v253, s72, 34
	s_nop 1
	v_writelane_b32 v253, s73, 35
	v_writelane_b32 v253, s74, 36
	v_writelane_b32 v253, s75, 37
	v_writelane_b32 v253, s76, 38
	v_writelane_b32 v253, s77, 39
	v_writelane_b32 v253, s78, 40
	v_writelane_b32 v253, s79, 41
	v_writelane_b32 v253, s80, 42
	v_writelane_b32 v253, s81, 43
	v_writelane_b32 v253, s82, 44
	v_writelane_b32 v253, s83, 45
	v_writelane_b32 v253, s84, 46
	v_writelane_b32 v253, s85, 47
	v_writelane_b32 v253, s86, 48
	v_writelane_b32 v253, s87, 49
	s_or_b64 exec, exec, s[0:1]
	v_writelane_b32 v253, s60, 50
	v_writelane_b32 v253, s53, 51
	v_writelane_b32 v253, s56, 52
	v_readfirstlane_b32 s0, v211
	s_lshr_b32 s0, s0, 8
	v_writelane_b32 v253, s57, 53
	v_writelane_b32 v253, s54, 54
	s_mul_i32 s0, s0, s54
	s_add_i32 s94, s0, s52
	v_writelane_b32 v253, s55, 55
	s_cmpk_gt_i32 s94, 0x3ff
	s_waitcnt lgkmcnt(0)
	s_barrier
	v_writelane_b32 v253, s52, 56
	v_readfirstlane_b32 s0, v211
	s_nop 0
	s_lshr_b32 s0, s0, 8
	s_cmp_lg_u32 s0, 0
	s_cbranch_scc1 .Lp1a_exit
	v_readlane_b32 s74, v253, 36
	v_readlane_b32 s75, v253, 37
	v_readlane_b32 s76, v253, 38
	v_readlane_b32 s77, v253, 39
	v_readlane_b32 s78, v253, 40
	v_readlane_b32 s79, v253, 41
	v_readlane_b32 s80, v253, 42
	v_readlane_b32 s81, v253, 43
	v_readlane_b32 s86, v253, 48
	v_readlane_b32 s87, v253, 49
	s_nop 3
	s_abs_i32 s1, s88
	v_cvt_f32_u32_e32 v0, s1
	v_readfirstlane_b32 s0, v211
	s_lshr_b32 s0, s0, 8
	s_mul_i32 s0, s0, s54
	v_rcp_iflag_f32_e32 v0, v0
	s_add_i32 s2, s52, s88
	s_sub_i32 s4, 0, s1
	s_add_i32 s0, s2, s0
	v_mul_f32_e32 v0, 0x4f7ffffe, v0
	v_cvt_u32_f32_e32 v0, v0
	s_addk_i32 s0, 0xff80
	s_ashr_i32 s2, s0, 31
	s_abs_i32 s0, s0
	v_readfirstlane_b32 s5, v0
	s_mul_i32 s4, s4, s5
	s_mul_hi_u32 s4, s5, s4
	s_add_i32 s5, s5, s4
	s_mul_hi_u32 s4, s0, s5
	s_mul_i32 s4, s4, s1
	s_sub_i32 s0, s0, s4
	s_sub_i32 s4, s0, s1
	s_cmp_ge_u32 s0, s1
	s_cselect_b32 s0, s4, s0
	s_sub_i32 s4, s0, s1
	s_cmp_ge_u32 s0, s1
	s_cselect_b32 s0, s4, s0
	s_xor_b32 s0, s0, s2
	s_sub_i32 s20, s0, s2
	s_mov_b32 s3, 0
	v_mov_b32_e32 v0, v210
	s_cmpk_gt_i32 s20, 0xc1f
	s_cbranch_scc1 .Lp1a_exit
	s_add_u32 s6, s86, 0x1180000
	s_addc_u32 s7, s87, 0
	s_add_u32 s21, s86, 0xd00000
	s_addc_u32 s22, s87, 0
	s_add_u32 s23, s86, 0xb00000
	s_addc_u32 s24, s87, 0
	s_add_u32 s25, s86, 0xa00000
	s_addc_u32 s26, s87, 0
	s_add_u32 s27, s86, 0x900000
	s_addc_u32 s28, s87, 0
	v_and_b32_e32 v2, 63, v0
	s_add_u32 s8, s86, 0x2200204
	v_ashrrev_i32_e32 v0, 4, v0
	s_addc_u32 s9, s87, 0
	v_lshlrev_b32_e32 v48, 4, v2
	v_mov_b32_e32 v49, 0
	v_and_b32_e32 v62, -4, v0
	v_lshl_add_u64 v[0:1], s[86:87], 0, v[48:49]
	s_mov_b64 s[4:5], 0x3200200
	s_add_u32 s10, s86, 0x2200200
	s_mov_b64 s[12:13], 0x1200200
	v_cmp_eq_u32_e64 s[0:1], 0, v213
	v_add_u32_e32 v63, 0xffffc000, v62
	v_lshl_add_u64 v[50:51], v[0:1], 0, s[4:5]
	v_cmp_eq_u32_e64 s[4:5], 0, v2
	s_addc_u32 s11, s87, 0
	v_lshl_add_u64 v[52:53], v[0:1], 0, s[12:13]
	v_lshl_add_u64 v[54:55], s[80:81], 0, v[48:49]
	v_lshl_add_u64 v[56:57], s[78:79], 0, v[48:49]
	s_movk_i32 s29, 0x104
	s_movk_i32 s30, 0x7fff
	s_movk_i32 s31, 0x1000
	s_movk_i32 s34, 0x2000
	s_movk_i32 s35, 0x3000
	v_mov_b32_e32 v64, 1
	v_mbcnt_hi_u32_b32 v65, -1, v212
	s_branch .Lp1a_354

; template <int NR>
; DI void fp8_rows(const float* __restrict__ src, unsigned char* __restrict__ dst, float* __restrict__ scale_out, int lane) {
;   float4 v[NR][4];
; #pragma unroll
;   for (int r = 0; r < NR; ++r)
; #pragma unroll
;     for (int i = 0; i < 4; ++i) v[r][i] = *(const float4*)(src + (size_t)r * 1024 + 256 * i + lane * 4);
; #pragma unroll
;   for (int r = 0; r < NR; ++r) {
;     float amax = 0.f;
; #pragma unroll
;     for (int i = 0; i < 4; ++i)
;       amax = fmaxf(amax, fmaxf(fmaxf(fabsf(v[r][i].x), fabsf(v[r][i].y)), fmaxf(fabsf(v[r][i].z), fabsf(v[r][i].w))));
; #pragma unroll
;     for (int o = 32; o > 0; o >>= 1) amax = fmaxf(amax, __shfl_xor(amax, o));
;     const float scale = amax > 0.f ? amax * (1.f / 440.f) : 1.f;
;     const float inv = 1.f / scale;
;     u32x4 w;
; #pragma unroll
;     for (int i = 0; i < 4; ++i) {
;       int t = 0;
;       t = __builtin_amdgcn_cvt_pk_fp8_f32(v[r][i].x * inv, v[r][i].y * inv, t, false);
;       t = __builtin_amdgcn_cvt_pk_fp8_f32(v[r][i].z * inv, v[r][i].w * inv, t, true);
;       w[i] = (unsigned)t;
;     }
;     *(u32x4*)(dst + (size_t)r * 1024 + lane * 16) = w;
;     if (lane == 0) scale_out[r] = scale;
.Lp1a_457:
	s_andn2_b64 vcc, exec, s[12:13]
	s_cbranch_vccnz .Lp1a_467
	v_lshl_add_u32 v88, s20, 4, v63
	v_ashrrev_i32_e32 v89, 31, v88
	v_lshlrev_b64 v[0:1], 12, v[88:89]
	v_lshl_add_u64 v[0:1], v[54:55], 0, v[0:1]
	global_load_dwordx4 v[58:61], v[0:1], off
	global_load_dwordx4 v[72:75], v[0:1], off offset:1024
	global_load_dwordx4 v[76:79], v[0:1], off offset:2048
	global_load_dwordx4 v[80:83], v[0:1], off offset:3072
	v_and_b32_e32 v2, 64, v65
	v_xor_b32_e32 v3, 32, v65
	v_add_u32_e32 v70, 64, v2
	v_xor_b32_e32 v4, 16, v65
	v_cmp_lt_i32_e32 vcc, v3, v70
	v_xor_b32_e32 v67, 8, v65
	s_waitcnt vmcnt(4)
	v_xor_b32_e32 v85, 1, v65
	v_cndmask_b32_e32 v2, v65, v3, vcc
	v_cmp_lt_i32_e32 vcc, v4, v70
	v_lshlrev_b32_e32 v66, 2, v2
	v_mov_b32_e32 v86, 0
	v_cndmask_b32_e32 v3, v65, v4, vcc
	v_add_co_u32_e32 v2, vcc, s31, v0
	v_lshlrev_b32_e32 v48, 2, v3
	s_nop 0
	v_addc_co_u32_e32 v3, vcc, 0, v1, vcc
	v_add_co_u32_e32 v44, vcc, s34, v0
	global_load_dwordx4 v[36:39], v[2:3], off offset:1024
	global_load_dwordx4 v[32:35], v[2:3], off offset:2048
	v_addc_co_u32_e32 v45, vcc, 0, v1, vcc
	v_add_co_u32_e32 v0, vcc, s35, v0
	global_load_dwordx4 v[28:31], v[44:45], off
	global_load_dwordx4 v[24:27], v[44:45], off offset:1024
	global_load_dwordx4 v[20:23], v[44:45], off offset:2048
	global_load_dwordx4 v[16:19], v[44:45], off offset:3072
	v_addc_co_u32_e32 v1, vcc, 0, v1, vcc
	v_cmp_lt_i32_e32 vcc, v67, v70
	s_waitcnt vmcnt(9)
	v_max_f32_e64 v4, |v61|, |v61|
	v_max_f32_e64 v5, |v60|, |v60|
	s_waitcnt vmcnt(8)
	v_max_f32_e64 v6, |v75|, |v75|
	v_max_f32_e64 v7, |v74|, |v74|
	s_waitcnt vmcnt(7)
	v_max_f32_e64 v8, |v79|, |v79|
	v_max_f32_e64 v9, |v78|, |v78|
	s_waitcnt vmcnt(6)
	v_max_f32_e64 v10, |v83|, |v83|
	v_max_f32_e64 v11, |v82|, |v82|
	v_max_f32_e32 v4, v5, v4
	v_max_f32_e32 v5, v7, v6
	v_max_f32_e32 v6, v9, v8
	v_max_f32_e32 v7, v11, v10
	v_max3_f32 v4, |v58|, |v59|, v4
	v_max3_f32 v5, |v72|, |v73|, v5
	v_max3_f32 v6, |v76|, |v77|, v6
	v_max3_f32 v7, |v80|, |v81|, v7
	v_max3_f32 v4, v4, 0, v5
	v_max3_f32 v46, v4, v6, v7
	ds_bpermute_b32 v47, v66, v46
	global_load_dwordx4 v[40:43], v[2:3], off offset:3072
	global_load_dwordx4 v[12:15], v[0:1], off
	global_load_dwordx4 v[8:11], v[0:1], off offset:1024
	global_load_dwordx4 v[4:7], v[0:1], off offset:2048
	v_cndmask_b32_e32 v67, v65, v67, vcc
	v_lshlrev_b32_e32 v67, 2, v67
	s_waitcnt lgkmcnt(0)
	v_max_f32_e32 v2, v47, v47
	v_max_f32_e32 v68, v46, v2
	global_load_dwordx4 v[44:47], v[44:45], off offset:-4096
	s_nop 0
	global_load_dwordx4 v[0:3], v[0:1], off offset:3072
	ds_bpermute_b32 v69, v48, v68
	s_waitcnt lgkmcnt(0)
	v_max_f32_e32 v69, v69, v69
	v_max_f32_e32 v69, v68, v69
	ds_bpermute_b32 v71, v67, v69
	v_xor_b32_e32 v68, 4, v65
	v_cmp_lt_i32_e32 vcc, v68, v70
	s_waitcnt lgkmcnt(0)
	v_max_f32_e32 v71, v71, v71
	v_cndmask_b32_e32 v68, v65, v68, vcc
	v_lshlrev_b32_e32 v68, 2, v68
	v_max_f32_e32 v71, v69, v71
	ds_bpermute_b32 v84, v68, v71
	v_xor_b32_e32 v69, 2, v65
	v_cmp_lt_i32_e32 vcc, v69, v70
	s_waitcnt lgkmcnt(0)
	v_max_f32_e32 v84, v84, v84
	v_cndmask_b32_e32 v69, v65, v69, vcc
	v_lshlrev_b32_e32 v69, 2, v69
	v_max_f32_e32 v71, v71, v84
	ds_bpermute_b32 v84, v69, v71
	v_cmp_lt_i32_e32 vcc, v85, v70
	s_waitcnt lgkmcnt(0)
	v_max_f32_e32 v84, v84, v84
	v_cndmask_b32_e32 v70, v65, v85, vcc
	v_lshlrev_b32_e32 v70, 2, v70
	v_max_f32_e32 v71, v71, v84
	ds_bpermute_b32 v87, v70, v71
	v_mov_b32_e32 v84, 0
	v_mov_b32_e32 v85, 0
	s_waitcnt lgkmcnt(0)
	v_max_f32_e32 v87, v87, v87
	v_max_f32_e32 v71, v71, v87
	v_mul_f32_e32 v87, 0x3b14f209, v71
	v_cmp_lt_f32_e32 vcc, 0, v71
	s_nop 1
	v_cndmask_b32_e32 v71, 1.0, v87, vcc
	v_div_scale_f32 v90, s[12:13], v71, v71, 1.0
	v_rcp_f32_e32 v91, v90
	v_div_scale_f32 v92, vcc, 1.0, v71, 1.0
	v_mov_b32_e32 v87, 0
	v_fma_f32 v93, -v90, v91, 1.0
	v_fmac_f32_e32 v91, v93, v91
	v_mul_f32_e32 v93, v92, v91
	v_fma_f32 v94, -v90, v93, v92
	v_fmac_f32_e32 v93, v94, v91
	v_fma_f32 v90, -v90, v93, v92
	v_div_fmas_f32 v90, v90, v91, v93
	v_div_fixup_f32 v90, v90, v71, 1.0
	v_mul_f32_e32 v58, v58, v90
	v_mul_f32_e32 v59, v59, v90
	v_mul_f32_e32 v72, v72, v90
	v_mul_f32_e32 v73, v73, v90
	v_mul_f32_e32 v76, v76, v90
	v_mul_f32_e32 v77, v77, v90
	v_mul_f32_e32 v80, v80, v90
	v_mul_f32_e32 v81, v81, v90
	v_cvt_pk_fp8_f32 v84, v58, v59
	v_cvt_pk_fp8_f32 v85, v72, v73
	v_cvt_pk_fp8_f32 v86, v76, v77
	v_cvt_pk_fp8_f32 v87, v80, v81
	v_mul_f32_e32 v60, v60, v90
	v_mul_f32_e32 v61, v61, v90
	v_mul_f32_e32 v74, v74, v90
	v_mul_f32_e32 v75, v75, v90
	v_mul_f32_e32 v78, v78, v90
	v_mul_f32_e32 v79, v79, v90
	v_mul_f32_e32 v82, v82, v90
	v_mul_f32_e32 v83, v83, v90
	v_cvt_pk_fp8_f32 v84, v60, v61 op_sel:[0,0,1]
	v_cvt_pk_fp8_f32 v85, v74, v75 op_sel:[0,0,1]
	v_cvt_pk_fp8_f32 v86, v78, v79 op_sel:[0,0,1]
	v_cvt_pk_fp8_f32 v87, v82, v83 op_sel:[0,0,1]
	v_lshlrev_b64 v[60:61], 10, v[88:89]
	v_lshl_add_u64 v[58:59], v[88:89], 3, s[8:9]
	v_lshl_add_u64 v[60:61], v[50:51], 0, v[60:61]
	global_store_dwordx4 v[60:61], v[84:87], off
	s_and_saveexec_b64 s[12:13], s[4:5]
	s_cbranch_execz .Lp1a_460
	global_store_dword v[58:59], v71, off
; template <int NR>
; DI void fp8_rows(const float* __restrict__ src, unsigned char* __restrict__ dst, float* __restrict__ scale_out, int lane) {
;     ...
;   for (int r = 0; r < NR; ++r) {
;     float amax = 0.f;
; #pragma unroll
;     for (int i = 0; i < 4; ++i)
;       amax = fmaxf(amax, fmaxf(fmaxf(fabsf(v[r][i].x), fabsf(v[r][i].y)), fmaxf(fabsf(v[r][i].z), fabsf(v[r][i].w))));
; #pragma unroll
;     for (int o = 32; o > 0; o >>= 1) amax = fmaxf(amax, __shfl_xor(amax, o));
;     const float scale = amax > 0.f ? amax * (1.f / 440.f) : 1.f;
;     const float inv = 1.f / scale;
;     u32x4 w;
; #pragma unroll
;     for (int i = 0; i < 4; ++i) {
;       int t = 0;
;       t = __builtin_amdgcn_cvt_pk_fp8_f32(v[r][i].x * inv, v[r][i].y * inv, t, false);
;       t = __builtin_amdgcn_cvt_pk_fp8_f32(v[r][i].z * inv, v[r][i].w * inv, t, true);
;       w[i] = (unsigned)t;
;     }
;     *(u32x4*)(dst + (size_t)r * 1024 + lane * 16) = w;
;     if (lane == 0) scale_out[r] = scale;
.Lp1a_460:
	s_or_b64 exec, exec, s[12:13]
	s_waitcnt vmcnt(2)
	v_max_f32_e64 v71, |v47|, |v47|
	v_max_f32_e64 v72, |v46|, |v46|
	v_max_f32_e32 v71, v72, v71
	v_max_f32_e64 v72, |v39|, |v39|
	v_max_f32_e64 v73, |v38|, |v38|
	v_max_f32_e32 v72, v73, v72
	v_max3_f32 v71, |v44|, |v45|, v71
	v_max3_f32 v72, |v36|, |v37|, v72
	v_max3_f32 v71, v71, 0, v72
	v_max_f32_e64 v72, |v35|, |v35|
	v_max_f32_e64 v73, |v34|, |v34|
	v_max_f32_e32 v72, v73, v72
	v_max_f32_e64 v73, |v43|, |v43|
	v_max_f32_e64 v74, |v42|, |v42|
	v_max_f32_e32 v73, v74, v73
	v_max3_f32 v72, |v32|, |v33|, v72
	v_max3_f32 v73, |v40|, |v41|, v73
	v_max3_f32 v71, v71, v72, v73
	ds_bpermute_b32 v72, v66, v71
	s_waitcnt lgkmcnt(0)
	v_max_f32_e32 v72, v72, v72
	v_max_f32_e32 v71, v71, v72
	ds_bpermute_b32 v72, v48, v71
	s_waitcnt lgkmcnt(0)
	v_max_f32_e32 v72, v72, v72
	v_max_f32_e32 v71, v71, v72
	ds_bpermute_b32 v72, v67, v71
	s_waitcnt lgkmcnt(0)
	v_max_f32_e32 v72, v72, v72
	v_max_f32_e32 v71, v71, v72
	ds_bpermute_b32 v72, v68, v71
	s_waitcnt lgkmcnt(0)
	v_max_f32_e32 v72, v72, v72
	v_max_f32_e32 v71, v71, v72
	ds_bpermute_b32 v72, v69, v71
	s_waitcnt lgkmcnt(0)
	v_max_f32_e32 v72, v72, v72
	v_max_f32_e32 v71, v71, v72
	ds_bpermute_b32 v73, v70, v71
	v_mov_b32_e32 v72, 0
	s_waitcnt lgkmcnt(0)
	v_max_f32_e32 v73, v73, v73
	v_max_f32_e32 v71, v71, v73
	v_mul_f32_e32 v73, 0x3b14f209, v71
	v_cmp_lt_f32_e32 vcc, 0, v71
	s_nop 1
	v_cndmask_b32_e32 v71, 1.0, v73, vcc
	v_div_scale_f32 v74, s[12:13], v71, v71, 1.0
	v_rcp_f32_e32 v75, v74
	v_div_scale_f32 v76, vcc, 1.0, v71, 1.0
	v_mov_b32_e32 v73, 0
	v_fma_f32 v77, -v74, v75, 1.0
	v_fmac_f32_e32 v75, v77, v75
	v_mul_f32_e32 v77, v76, v75
	v_fma_f32 v78, -v74, v77, v76
	v_fmac_f32_e32 v77, v78, v75
	v_fma_f32 v74, -v74, v77, v76
	v_div_fmas_f32 v74, v74, v75, v77
	v_div_fixup_f32 v76, v74, v71, 1.0
	v_mul_f32_e32 v32, v32, v76
	v_mul_f32_e32 v33, v33, v76
	v_mov_b32_e32 v74, 0
	v_mul_f32_e32 v44, v44, v76
	v_mul_f32_e32 v45, v45, v76
	v_mul_f32_e32 v36, v36, v76
	v_mul_f32_e32 v37, v37, v76
	v_cvt_pk_fp8_f32 v74, v32, v33
	v_mul_f32_e32 v32, v34, v76
	v_mul_f32_e32 v33, v35, v76
	v_mul_f32_e32 v34, v40, v76
	v_mul_f32_e32 v35, v41, v76
	v_mov_b32_e32 v75, 0
	v_cvt_pk_fp8_f32 v72, v44, v45
	v_cvt_pk_fp8_f32 v73, v36, v37
	v_cvt_pk_fp8_f32 v75, v34, v35
	v_mul_f32_e32 v46, v46, v76
	v_mul_f32_e32 v47, v47, v76
	v_mul_f32_e32 v38, v38, v76
	v_mul_f32_e32 v36, v39, v76
	v_cvt_pk_fp8_f32 v74, v32, v33 op_sel:[0,0,1]
	v_mul_f32_e32 v32, v42, v76
	v_mul_f32_e32 v33, v43, v76
	v_cvt_pk_fp8_f32 v72, v46, v47 op_sel:[0,0,1]
	v_cvt_pk_fp8_f32 v73, v38, v36 op_sel:[0,0,1]
	v_cvt_pk_fp8_f32 v75, v32, v33 op_sel:[0,0,1]
	global_store_dwordx4 v[60:61], v[72:75], off offset:1024
	s_and_saveexec_b64 s[12:13], s[4:5]
	s_cbranch_execz .Lp1a_462
	global_store_dword v[58:59], v71, off offset:8
; template <int NR>
; DI void fp8_rows(const float* __restrict__ src, unsigned char* __restrict__ dst, float* __restrict__ scale_out, int lane) {
;     ...
;   for (int r = 0; r < NR; ++r) {
;     float amax = 0.f;
; #pragma unroll
;     for (int i = 0; i < 4; ++i)
;       amax = fmaxf(amax, fmaxf(fmaxf(fabsf(v[r][i].x), fabsf(v[r][i].y)), fmaxf(fabsf(v[r][i].z), fabsf(v[r][i].w))));
; #pragma unroll
;     for (int o = 32; o > 0; o >>= 1) amax = fmaxf(amax, __shfl_xor(amax, o));
;     const float scale = amax > 0.f ? amax * (1.f / 440.f) : 1.f;
;     const float inv = 1.f / scale;
;     u32x4 w;
; #pragma unroll
;     for (int i = 0; i < 4; ++i) {
;       int t = 0;
;       t = __builtin_amdgcn_cvt_pk_fp8_f32(v[r][i].x * inv, v[r][i].y * inv, t, false);
;       t = __builtin_amdgcn_cvt_pk_fp8_f32(v[r][i].z * inv, v[r][i].w * inv, t, true);
;       w[i] = (unsigned)t;
;     }
;     *(u32x4*)(dst + (size_t)r * 1024 + lane * 16) = w;
;     if (lane == 0) scale_out[r] = scale;
.Lp1a_462:
	s_or_b64 exec, exec, s[12:13]
	v_max_f32_e64 v32, |v31|, |v31|
	v_max_f32_e64 v33, |v30|, |v30|
	v_max_f32_e32 v32, v33, v32
	v_max_f32_e64 v33, |v27|, |v27|
	v_max_f32_e64 v34, |v26|, |v26|
	v_max_f32_e32 v33, v34, v33
	v_max3_f32 v32, |v28|, |v29|, v32
	v_max3_f32 v33, |v24|, |v25|, v33
	v_max3_f32 v32, v32, 0, v33
	v_max_f32_e64 v33, |v23|, |v23|
	v_max_f32_e64 v34, |v22|, |v22|
	v_max_f32_e32 v33, v34, v33
	v_max_f32_e64 v34, |v19|, |v19|
	v_max_f32_e64 v35, |v18|, |v18|
	v_max_f32_e32 v34, v35, v34
	v_max3_f32 v33, |v20|, |v21|, v33
	v_max3_f32 v34, |v16|, |v17|, v34
	v_max3_f32 v32, v32, v33, v34
	ds_bpermute_b32 v33, v66, v32
	v_mov_b32_e32 v34, 0
	v_mov_b32_e32 v35, 0
	s_waitcnt lgkmcnt(0)
	v_max_f32_e32 v33, v33, v33
	v_max_f32_e32 v32, v32, v33
	ds_bpermute_b32 v33, v48, v32
	s_waitcnt lgkmcnt(0)
	v_max_f32_e32 v33, v33, v33
	v_max_f32_e32 v32, v32, v33
	ds_bpermute_b32 v33, v67, v32
	s_waitcnt lgkmcnt(0)
	v_max_f32_e32 v33, v33, v33
	v_max_f32_e32 v32, v32, v33
	ds_bpermute_b32 v33, v68, v32
	s_waitcnt lgkmcnt(0)
	v_max_f32_e32 v33, v33, v33
	v_max_f32_e32 v32, v32, v33
	ds_bpermute_b32 v33, v69, v32
	s_waitcnt lgkmcnt(0)
	v_max_f32_e32 v33, v33, v33
	v_max_f32_e32 v32, v32, v33
	ds_bpermute_b32 v33, v70, v32
	s_waitcnt lgkmcnt(0)
	v_max_f32_e32 v33, v33, v33
	v_max_f32_e32 v32, v32, v33
	v_mul_f32_e32 v33, 0x3b14f209, v32
	v_cmp_lt_f32_e32 vcc, 0, v32
	s_nop 1
	v_cndmask_b32_e32 v32, 1.0, v33, vcc
	v_div_scale_f32 v33, s[12:13], v32, v32, 1.0
	v_rcp_f32_e32 v36, v33
	v_div_scale_f32 v37, vcc, 1.0, v32, 1.0
	v_fma_f32 v38, -v33, v36, 1.0
	v_fmac_f32_e32 v36, v38, v36
	v_mul_f32_e32 v38, v37, v36
	v_fma_f32 v39, -v33, v38, v37
	v_fmac_f32_e32 v38, v39, v36
	v_fma_f32 v33, -v33, v38, v37
	v_div_fmas_f32 v33, v33, v36, v38
	v_div_fixup_f32 v33, v33, v32, 1.0
	v_mul_f32_e32 v28, v28, v33
	v_mul_f32_e32 v29, v29, v33
	v_mul_f32_e32 v24, v24, v33
	v_mul_f32_e32 v25, v25, v33
	v_mul_f32_e32 v20, v20, v33
	v_mul_f32_e32 v21, v21, v33
	v_mov_b32_e32 v36, 0
	v_mul_f32_e32 v16, v16, v33
	v_mul_f32_e32 v17, v17, v33
	v_mov_b32_e32 v37, 0
	v_cvt_pk_fp8_f32 v34, v28, v29
	v_cvt_pk_fp8_f32 v35, v24, v25
	v_cvt_pk_fp8_f32 v36, v20, v21
	v_cvt_pk_fp8_f32 v37, v16, v17
	v_mul_f32_e32 v30, v30, v33
	v_mul_f32_e32 v31, v31, v33
	v_mul_f32_e32 v26, v26, v33
	v_mul_f32_e32 v24, v27, v33
	v_mul_f32_e32 v20, v22, v33
	v_mul_f32_e32 v21, v23, v33
	v_mul_f32_e32 v16, v18, v33
	v_mul_f32_e32 v17, v19, v33
	v_cvt_pk_fp8_f32 v34, v30, v31 op_sel:[0,0,1]
	v_cvt_pk_fp8_f32 v35, v26, v24 op_sel:[0,0,1]
	v_cvt_pk_fp8_f32 v36, v20, v21 op_sel:[0,0,1]
	v_cvt_pk_fp8_f32 v37, v16, v17 op_sel:[0,0,1]
	global_store_dwordx4 v[60:61], v[34:37], off offset:2048
	s_and_saveexec_b64 s[12:13], s[4:5]
	s_cbranch_execz .Lp1a_464
	global_store_dword v[58:59], v32, off offset:16
.Lp1a_464:
	s_or_b64 exec, exec, s[12:13]
	v_max_f32_e64 v16, |v15|, |v15|
	v_max_f32_e64 v17, |v14|, |v14|
	v_max_f32_e32 v16, v17, v16
	v_max_f32_e64 v17, |v11|, |v11|
	v_max_f32_e64 v18, |v10|, |v10|
	v_max_f32_e32 v17, v18, v17
	v_max3_f32 v16, |v12|, |v13|, v16
	v_max3_f32 v17, |v8|, |v9|, v17
	v_max3_f32 v16, v16, 0, v17
	v_max_f32_e64 v17, |v7|, |v7|
	v_max_f32_e64 v18, |v6|, |v6|
	v_max_f32_e32 v17, v18, v17
	s_waitcnt vmcnt(3)
	v_max_f32_e64 v18, |v3|, |v3|
	v_max_f32_e64 v19, |v2|, |v2|
	v_max_f32_e32 v18, v19, v18
	v_max3_f32 v17, |v4|, |v5|, v17
	v_max3_f32 v18, |v0|, |v1|, v18
	v_max3_f32 v16, v16, v17, v18
	ds_bpermute_b32 v17, v66, v16
	v_mov_b32_e32 v18, 0
	v_mov_b32_e32 v19, 0
	s_waitcnt lgkmcnt(0)
	v_max_f32_e32 v17, v17, v17
	v_max_f32_e32 v16, v16, v17
	ds_bpermute_b32 v17, v48, v16
	s_waitcnt lgkmcnt(0)
	v_max_f32_e32 v17, v17, v17
	v_max_f32_e32 v16, v16, v17
	ds_bpermute_b32 v17, v67, v16
	s_waitcnt lgkmcnt(0)
	v_max_f32_e32 v17, v17, v17
	v_max_f32_e32 v16, v16, v17
	ds_bpermute_b32 v17, v68, v16
	s_waitcnt lgkmcnt(0)
	v_max_f32_e32 v17, v17, v17
	v_max_f32_e32 v16, v16, v17
	ds_bpermute_b32 v17, v69, v16
	s_waitcnt lgkmcnt(0)
	v_max_f32_e32 v17, v17, v17
	v_max_f32_e32 v16, v16, v17
	ds_bpermute_b32 v17, v70, v16
	s_waitcnt lgkmcnt(0)
	v_max_f32_e32 v17, v17, v17
	v_max_f32_e32 v16, v16, v17
	v_mul_f32_e32 v17, 0x3b14f209, v16
	v_cmp_lt_f32_e32 vcc, 0, v16
	s_nop 1
	v_cndmask_b32_e32 v16, 1.0, v17, vcc
	v_div_scale_f32 v17, s[12:13], v16, v16, 1.0
	v_rcp_f32_e32 v20, v17
	v_div_scale_f32 v21, vcc, 1.0, v16, 1.0
	v_fma_f32 v22, -v17, v20, 1.0
	v_fmac_f32_e32 v20, v22, v20
	v_mul_f32_e32 v22, v21, v20
	v_fma_f32 v23, -v17, v22, v21
	v_fmac_f32_e32 v22, v23, v20
	v_fma_f32 v17, -v17, v22, v21
	v_div_fmas_f32 v17, v17, v20, v22
	v_div_fixup_f32 v17, v17, v16, 1.0
	v_mul_f32_e32 v12, v12, v17
	v_mul_f32_e32 v13, v13, v17
	v_mul_f32_e32 v8, v8, v17
	v_mul_f32_e32 v9, v9, v17
	v_mul_f32_e32 v4, v4, v17
	v_mul_f32_e32 v5, v5, v17
	v_mov_b32_e32 v20, 0
	v_mul_f32_e32 v0, v0, v17
	v_mul_f32_e32 v1, v1, v17
	v_mov_b32_e32 v21, 0
	v_cvt_pk_fp8_f32 v18, v12, v13
	v_cvt_pk_fp8_f32 v19, v8, v9
	v_cvt_pk_fp8_f32 v20, v4, v5
	v_cvt_pk_fp8_f32 v21, v0, v1
	v_mul_f32_e32 v14, v14, v17
	v_mul_f32_e32 v15, v15, v17
	v_mul_f32_e32 v10, v10, v17
	v_mul_f32_e32 v8, v11, v17
	v_mul_f32_e32 v4, v6, v17
	v_mul_f32_e32 v5, v7, v17
	v_mul_f32_e32 v0, v2, v17
	v_mul_f32_e32 v1, v3, v17
	v_cvt_pk_fp8_f32 v18, v14, v15 op_sel:[0,0,1]
	v_cvt_pk_fp8_f32 v19, v10, v8 op_sel:[0,0,1]
	v_cvt_pk_fp8_f32 v20, v4, v5 op_sel:[0,0,1]
	v_cvt_pk_fp8_f32 v21, v0, v1 op_sel:[0,0,1]
	global_store_dwordx4 v[60:61], v[18:21], off offset:3072
	s_and_saveexec_b64 s[12:13], s[4:5]
	s_cbranch_execz .Lp1a_466
	global_store_dword v[58:59], v16, off offset:24

; template <int NR>
; DI void fp8_rows(const float* __restrict__ src, unsigned char* __restrict__ dst, float* __restrict__ scale_out, int lane) {
;   float4 v[NR][4];
; #pragma unroll
;   for (int r = 0; r < NR; ++r)
; #pragma unroll
;     for (int i = 0; i < 4; ++i) v[r][i] = *(const float4*)(src + (size_t)r * 1024 + 256 * i + lane * 4);
; #pragma unroll
;   for (int r = 0; r < NR; ++r) {
;     float amax = 0.f;
; #pragma unroll
;     for (int i = 0; i < 4; ++i)
;       amax = fmaxf(amax, fmaxf(fmaxf(fabsf(v[r][i].x), fabsf(v[r][i].y)), fmaxf(fabsf(v[r][i].z), fabsf(v[r][i].w))));
; #pragma unroll
;     for (int o = 32; o > 0; o >>= 1) amax = fmaxf(amax, __shfl_xor(amax, o));
;     const float scale = amax > 0.f ? amax * (1.f / 440.f) : 1.f;
;     const float inv = 1.f / scale;
;     u32x4 w;
; #pragma unroll
;     for (int i = 0; i < 4; ++i) {
;       int t = 0;
;       t = __builtin_amdgcn_cvt_pk_fp8_f32(v[r][i].x * inv, v[r][i].y * inv, t, false);
;       t = __builtin_amdgcn_cvt_pk_fp8_f32(v[r][i].z * inv, v[r][i].w * inv, t, true);
;       w[i] = (unsigned)t;
;     }
;     *(u32x4*)(dst + (size_t)r * 1024 + lane * 16) = w;
;     if (lane == 0) scale_out[r] = scale;
.Lp1a_469:
	v_lshl_add_u32 v88, s20, 4, v62
	v_ashrrev_i32_e32 v89, 31, v88
	v_lshlrev_b64 v[0:1], 12, v[88:89]
	v_lshl_add_u64 v[0:1], v[56:57], 0, v[0:1]
	global_load_dwordx4 v[58:61], v[0:1], off
	global_load_dwordx4 v[72:75], v[0:1], off offset:1024
	global_load_dwordx4 v[76:79], v[0:1], off offset:2048
	global_load_dwordx4 v[80:83], v[0:1], off offset:3072
	v_and_b32_e32 v2, 64, v65
	v_xor_b32_e32 v3, 32, v65
	v_add_u32_e32 v70, 64, v2
	v_xor_b32_e32 v4, 16, v65
	v_cmp_lt_i32_e32 vcc, v3, v70
	v_xor_b32_e32 v67, 8, v65
	s_waitcnt vmcnt(4)
	v_xor_b32_e32 v85, 1, v65
	v_cndmask_b32_e32 v2, v65, v3, vcc
	v_cmp_lt_i32_e32 vcc, v4, v70
	v_lshlrev_b32_e32 v66, 2, v2
	v_mov_b32_e32 v86, 0
	v_cndmask_b32_e32 v3, v65, v4, vcc
	v_add_co_u32_e32 v2, vcc, s31, v0
	v_lshlrev_b32_e32 v48, 2, v3
	s_nop 0
	v_addc_co_u32_e32 v3, vcc, 0, v1, vcc
	v_add_co_u32_e32 v44, vcc, s34, v0
	global_load_dwordx4 v[36:39], v[2:3], off offset:1024
	global_load_dwordx4 v[32:35], v[2:3], off offset:2048
	v_addc_co_u32_e32 v45, vcc, 0, v1, vcc
	v_add_co_u32_e32 v0, vcc, s35, v0
	global_load_dwordx4 v[28:31], v[44:45], off
	global_load_dwordx4 v[24:27], v[44:45], off offset:1024
	global_load_dwordx4 v[20:23], v[44:45], off offset:2048
	global_load_dwordx4 v[16:19], v[44:45], off offset:3072
	v_addc_co_u32_e32 v1, vcc, 0, v1, vcc
	v_cmp_lt_i32_e32 vcc, v67, v70
	s_waitcnt vmcnt(9)
	v_max_f32_e64 v4, |v61|, |v61|
	v_max_f32_e64 v5, |v60|, |v60|
	s_waitcnt vmcnt(8)
	v_max_f32_e64 v6, |v75|, |v75|
	v_max_f32_e64 v7, |v74|, |v74|
	s_waitcnt vmcnt(7)
	v_max_f32_e64 v8, |v79|, |v79|
	v_max_f32_e64 v9, |v78|, |v78|
	s_waitcnt vmcnt(6)
	v_max_f32_e64 v10, |v83|, |v83|
	v_max_f32_e64 v11, |v82|, |v82|
	v_max_f32_e32 v4, v5, v4
	v_max_f32_e32 v5, v7, v6
	v_max_f32_e32 v6, v9, v8
	v_max_f32_e32 v7, v11, v10
	v_max3_f32 v4, |v58|, |v59|, v4
	v_max3_f32 v5, |v72|, |v73|, v5
	v_max3_f32 v6, |v76|, |v77|, v6
	v_max3_f32 v7, |v80|, |v81|, v7
	v_max3_f32 v4, v4, 0, v5
	v_max3_f32 v46, v4, v6, v7
	ds_bpermute_b32 v47, v66, v46
	global_load_dwordx4 v[40:43], v[2:3], off offset:3072
	global_load_dwordx4 v[12:15], v[0:1], off
	global_load_dwordx4 v[8:11], v[0:1], off offset:1024
	global_load_dwordx4 v[4:7], v[0:1], off offset:2048
	v_cndmask_b32_e32 v67, v65, v67, vcc
	v_lshlrev_b32_e32 v67, 2, v67
	s_waitcnt lgkmcnt(0)
	v_max_f32_e32 v2, v47, v47
	v_max_f32_e32 v68, v46, v2
	global_load_dwordx4 v[44:47], v[44:45], off offset:-4096
	s_nop 0
	global_load_dwordx4 v[0:3], v[0:1], off offset:3072
	ds_bpermute_b32 v69, v48, v68
	s_waitcnt lgkmcnt(0)
	v_max_f32_e32 v69, v69, v69
	v_max_f32_e32 v69, v68, v69
	ds_bpermute_b32 v71, v67, v69
	v_xor_b32_e32 v68, 4, v65
	v_cmp_lt_i32_e32 vcc, v68, v70
	s_waitcnt lgkmcnt(0)
	v_max_f32_e32 v71, v71, v71
	v_cndmask_b32_e32 v68, v65, v68, vcc
	v_lshlrev_b32_e32 v68, 2, v68
	v_max_f32_e32 v71, v69, v71
	ds_bpermute_b32 v84, v68, v71
	v_xor_b32_e32 v69, 2, v65
	v_cmp_lt_i32_e32 vcc, v69, v70
	s_waitcnt lgkmcnt(0)
	v_max_f32_e32 v84, v84, v84
	v_cndmask_b32_e32 v69, v65, v69, vcc
	v_lshlrev_b32_e32 v69, 2, v69
	v_max_f32_e32 v71, v71, v84
	ds_bpermute_b32 v84, v69, v71
	v_cmp_lt_i32_e32 vcc, v85, v70
	s_waitcnt lgkmcnt(0)
	v_max_f32_e32 v84, v84, v84
	v_cndmask_b32_e32 v70, v65, v85, vcc
	v_lshlrev_b32_e32 v70, 2, v70
	v_max_f32_e32 v71, v71, v84
	ds_bpermute_b32 v87, v70, v71
	v_mov_b32_e32 v84, 0
	v_mov_b32_e32 v85, 0
	s_waitcnt lgkmcnt(0)
	v_max_f32_e32 v87, v87, v87
	v_max_f32_e32 v71, v71, v87
	v_mul_f32_e32 v87, 0x3b14f209, v71
	v_cmp_lt_f32_e32 vcc, 0, v71
	s_nop 1
	v_cndmask_b32_e32 v71, 1.0, v87, vcc
	v_div_scale_f32 v90, s[12:13], v71, v71, 1.0
	v_rcp_f32_e32 v91, v90
	v_div_scale_f32 v92, vcc, 1.0, v71, 1.0
	v_mov_b32_e32 v87, 0
	v_fma_f32 v93, -v90, v91, 1.0
	v_fmac_f32_e32 v91, v93, v91
	v_mul_f32_e32 v93, v92, v91
	v_fma_f32 v94, -v90, v93, v92
	v_fmac_f32_e32 v93, v94, v91
	v_fma_f32 v90, -v90, v93, v92
	v_div_fmas_f32 v90, v90, v91, v93
	v_div_fixup_f32 v90, v90, v71, 1.0
	v_mul_f32_e32 v58, v58, v90
	v_mul_f32_e32 v59, v59, v90
	v_mul_f32_e32 v72, v72, v90
	v_mul_f32_e32 v73, v73, v90
	v_mul_f32_e32 v76, v76, v90
	v_mul_f32_e32 v77, v77, v90
	v_mul_f32_e32 v80, v80, v90
	v_mul_f32_e32 v81, v81, v90
	v_cvt_pk_fp8_f32 v84, v58, v59
	v_cvt_pk_fp8_f32 v85, v72, v73
	v_cvt_pk_fp8_f32 v86, v76, v77
	v_cvt_pk_fp8_f32 v87, v80, v81
	v_mul_f32_e32 v60, v60, v90
	v_mul_f32_e32 v61, v61, v90
	v_mul_f32_e32 v74, v74, v90
	v_mul_f32_e32 v75, v75, v90
	v_mul_f32_e32 v78, v78, v90
	v_mul_f32_e32 v79, v79, v90
	v_mul_f32_e32 v82, v82, v90
	v_mul_f32_e32 v83, v83, v90
	v_cvt_pk_fp8_f32 v84, v60, v61 op_sel:[0,0,1]
	v_cvt_pk_fp8_f32 v85, v74, v75 op_sel:[0,0,1]
	v_cvt_pk_fp8_f32 v86, v78, v79 op_sel:[0,0,1]
	v_cvt_pk_fp8_f32 v87, v82, v83 op_sel:[0,0,1]
	v_lshlrev_b64 v[60:61], 10, v[88:89]
	v_lshl_add_u64 v[58:59], v[88:89], 3, s[10:11]
	v_lshl_add_u64 v[60:61], v[52:53], 0, v[60:61]
	global_store_dwordx4 v[60:61], v[84:87], off
	s_and_saveexec_b64 s[12:13], s[4:5]
	s_cbranch_execz .Lp1a_471
	global_store_dword v[58:59], v71, off

; template <int NR>
; DI void fp8_rows(const float* __restrict__ src, unsigned char* __restrict__ dst, float* __restrict__ scale_out, int lane) {
;     ...
;   for (int r = 0; r < NR; ++r) {
;     float amax = 0.f;
; #pragma unroll
;     for (int i = 0; i < 4; ++i)
;       amax = fmaxf(amax, fmaxf(fmaxf(fabsf(v[r][i].x), fabsf(v[r][i].y)), fmaxf(fabsf(v[r][i].z), fabsf(v[r][i].w))));
; #pragma unroll
;     for (int o = 32; o > 0; o >>= 1) amax = fmaxf(amax, __shfl_xor(amax, o));
;     const float scale = amax > 0.f ? amax * (1.f / 440.f) : 1.f;
;     const float inv = 1.f / scale;
;     u32x4 w;
; #pragma unroll
;     for (int i = 0; i < 4; ++i) {
;       int t = 0;
;       t = __builtin_amdgcn_cvt_pk_fp8_f32(v[r][i].x * inv, v[r][i].y * inv, t, false);
;       t = __builtin_amdgcn_cvt_pk_fp8_f32(v[r][i].z * inv, v[r][i].w * inv, t, true);
;       w[i] = (unsigned)t;
;     }
;     *(u32x4*)(dst + (size_t)r * 1024 + lane * 16) = w;
;     if (lane == 0) scale_out[r] = scale;
;   }
.Lp1a_475:
	s_or_b64 exec, exec, s[12:13]
	v_max_f32_e64 v16, |v15|, |v15|
	v_max_f32_e64 v17, |v14|, |v14|
	v_max_f32_e32 v16, v17, v16
	v_max_f32_e64 v17, |v11|, |v11|
	v_max_f32_e64 v18, |v10|, |v10|
	v_max_f32_e32 v17, v18, v17
	v_max3_f32 v16, |v12|, |v13|, v16
	v_max3_f32 v17, |v8|, |v9|, v17
	v_max3_f32 v16, v16, 0, v17
	v_max_f32_e64 v17, |v7|, |v7|
	v_max_f32_e64 v18, |v6|, |v6|
	v_max_f32_e32 v17, v18, v17
	s_waitcnt vmcnt(3)
	v_max_f32_e64 v18, |v3|, |v3|
	v_max_f32_e64 v19, |v2|, |v2|
	v_max_f32_e32 v18, v19, v18
	v_max3_f32 v17, |v4|, |v5|, v17
	v_max3_f32 v18, |v0|, |v1|, v18
	v_max3_f32 v16, v16, v17, v18
	ds_bpermute_b32 v17, v66, v16
	v_mov_b32_e32 v18, 0
	v_mov_b32_e32 v19, 0
	s_waitcnt lgkmcnt(0)
	v_max_f32_e32 v17, v17, v17
	v_max_f32_e32 v16, v16, v17
	ds_bpermute_b32 v17, v48, v16
	s_waitcnt lgkmcnt(0)
	v_max_f32_e32 v17, v17, v17
	v_max_f32_e32 v16, v16, v17
	ds_bpermute_b32 v17, v67, v16
	s_waitcnt lgkmcnt(0)
	v_max_f32_e32 v17, v17, v17
	v_max_f32_e32 v16, v16, v17
	ds_bpermute_b32 v17, v68, v16
	s_waitcnt lgkmcnt(0)
	v_max_f32_e32 v17, v17, v17
	v_max_f32_e32 v16, v16, v17
	ds_bpermute_b32 v17, v69, v16
	s_waitcnt lgkmcnt(0)
	v_max_f32_e32 v17, v17, v17
	v_max_f32_e32 v16, v16, v17
	ds_bpermute_b32 v17, v70, v16
	s_waitcnt lgkmcnt(0)
	v_max_f32_e32 v17, v17, v17
	v_max_f32_e32 v16, v16, v17
	v_mul_f32_e32 v17, 0x3b14f209, v16
	v_cmp_lt_f32_e32 vcc, 0, v16
	s_nop 1
	v_cndmask_b32_e32 v16, 1.0, v17, vcc
	v_div_scale_f32 v17, s[12:13], v16, v16, 1.0
	v_rcp_f32_e32 v20, v17
	v_div_scale_f32 v21, vcc, 1.0, v16, 1.0
	v_fma_f32 v22, -v17, v20, 1.0
	v_fmac_f32_e32 v20, v22, v20
	v_mul_f32_e32 v22, v21, v20
	v_fma_f32 v23, -v17, v22, v21
	v_fmac_f32_e32 v22, v23, v20
	v_fma_f32 v17, -v17, v22, v21
	v_div_fmas_f32 v17, v17, v20, v22
	v_div_fixup_f32 v17, v17, v16, 1.0
	v_mul_f32_e32 v12, v12, v17
	v_mul_f32_e32 v13, v13, v17
	v_mul_f32_e32 v8, v8, v17
	v_mul_f32_e32 v9, v9, v17
	v_mul_f32_e32 v4, v4, v17
	v_mul_f32_e32 v5, v5, v17
	v_mov_b32_e32 v20, 0
	v_mul_f32_e32 v0, v0, v17
	v_mul_f32_e32 v1, v1, v17
	v_mov_b32_e32 v21, 0
	v_cvt_pk_fp8_f32 v18, v12, v13
	v_cvt_pk_fp8_f32 v19, v8, v9
	v_cvt_pk_fp8_f32 v20, v4, v5
	v_cvt_pk_fp8_f32 v21, v0, v1
	v_mul_f32_e32 v14, v14, v17
	v_mul_f32_e32 v15, v15, v17
	v_mul_f32_e32 v10, v10, v17
	v_mul_f32_e32 v8, v11, v17
	v_mul_f32_e32 v4, v6, v17
	v_mul_f32_e32 v5, v7, v17
	v_mul_f32_e32 v0, v2, v17
	v_mul_f32_e32 v1, v3, v17
	v_cvt_pk_fp8_f32 v18, v14, v15 op_sel:[0,0,1]
	v_cvt_pk_fp8_f32 v19, v10, v8 op_sel:[0,0,1]
	v_cvt_pk_fp8_f32 v20, v4, v5 op_sel:[0,0,1]
	v_cvt_pk_fp8_f32 v21, v0, v1 op_sel:[0,0,1]
	global_store_dwordx4 v[60:61], v[18:21], off offset:3072
	s_and_saveexec_b64 s[12:13], s[4:5]
	s_cbranch_execz .Lp1a_352
	global_store_dword v[58:59], v16, off offset:24
	s_branch .Lp1a_352

; DI int vb_id() { return (int)blockIdx.x + half_id() * (int)gridDim.x; }
; DI int vb_n() { return (int)gridDim.x * 2; }
; DI void phase_prep(const Params& p, char* smem, int part, int vb) {
;     ...
;     const int NITEMS = 1024 + 1024 + 128 + 128 + 256 + 512 + 32;
;     for (int it0 = vb; it0 < NITEMS; it0 += vb_n()) {
;       int it = it0;
;       if (it < 1024) {
;         int row = it * 16 + wave * 4;
;         fp8_rows<4>(p.pu + (size_t)row * 1024, (unsigned char*)(ws + WS_UBF) + (size_t)row * 1024, (float*)(ws + WS_SU) + row, lane);
; __global__ void __launch_bounds__(512) fwd_megakernel(Params p) {
;     ...
;   phase_prep(p, hsm, 1, (vb_id() + vb_n() - 128) % vb_n());
.LBB0_752:
	v_readfirstlane_b32 s0, v211
	s_nop 0
	s_lshr_b32 s0, s0, 8
	s_cmp_eq_u32 s0, 0
	s_cbranch_scc1 .Lp1b_exit
	v_readlane_b32 s74, v253, 36
	v_readlane_b32 s75, v253, 37
	v_readlane_b32 s76, v253, 38
	v_readlane_b32 s77, v253, 39
	v_readlane_b32 s78, v253, 40
	v_readlane_b32 s79, v253, 41
	v_readlane_b32 s80, v253, 42
	v_readlane_b32 s81, v253, 43
	v_readlane_b32 s86, v253, 48
	v_readlane_b32 s87, v253, 49
	v_readlane_b32 s52, v253, 56
	v_readlane_b32 s54, v253, 54
	s_nop 3
	s_abs_i32 s1, s88
	v_cvt_f32_u32_e32 v0, s1
	v_readfirstlane_b32 s0, v211
	s_lshr_b32 s0, s0, 8
	s_mul_i32 s0, s0, s54
	v_rcp_iflag_f32_e32 v0, v0
	s_add_i32 s2, s52, s88
	s_sub_i32 s4, 0, s1
	s_add_i32 s0, s2, s0
	v_mul_f32_e32 v0, 0x4f7ffffe, v0
	v_cvt_u32_f32_e32 v0, v0
	s_addk_i32 s0, 0xff80
	s_ashr_i32 s2, s0, 31
	s_abs_i32 s0, s0
	v_readfirstlane_b32 s5, v0
	s_mul_i32 s4, s4, s5
	s_mul_hi_u32 s4, s5, s4
	s_add_i32 s5, s5, s4
	s_mul_hi_u32 s4, s0, s5
	s_mul_i32 s4, s4, s1
	s_sub_i32 s0, s0, s4
	s_sub_i32 s4, s0, s1
	s_cmp_ge_u32 s0, s1
	s_cselect_b32 s0, s4, s0
	s_sub_i32 s4, s0, s1
	s_cmp_ge_u32 s0, s1
	s_cselect_b32 s0, s4, s0
	s_xor_b32 s0, s0, s2
	s_sub_i32 s20, s0, s2
	s_mov_b32 s3, 0
	v_mov_b32_e32 v0, v210
	s_cmpk_gt_i32 s20, 0xc1f
	s_cbranch_scc1 .Lp1b_exit
	s_add_u32 s6, s86, 0x1180000
	s_addc_u32 s7, s87, 0
	s_add_u32 s21, s86, 0xd00000
	s_addc_u32 s22, s87, 0
	s_add_u32 s23, s86, 0xb00000
	s_addc_u32 s24, s87, 0
	s_add_u32 s25, s86, 0xa00000
	s_addc_u32 s26, s87, 0
	s_add_u32 s27, s86, 0x900000
	s_addc_u32 s28, s87, 0
	v_and_b32_e32 v2, 63, v0
	s_add_u32 s8, s86, 0x2200204
	v_ashrrev_i32_e32 v0, 4, v0
	s_addc_u32 s9, s87, 0
	v_lshlrev_b32_e32 v48, 4, v2
	v_mov_b32_e32 v49, 0
	v_and_b32_e32 v62, -4, v0
	v_lshl_add_u64 v[0:1], s[86:87], 0, v[48:49]
	s_mov_b64 s[4:5], 0x3200200
	s_add_u32 s10, s86, 0x2200200
	s_mov_b64 s[12:13], 0x1200200
	v_cmp_eq_u32_e64 s[0:1], 0, v213
	v_add_u32_e32 v63, 0xffffc000, v62
	v_lshl_add_u64 v[50:51], v[0:1], 0, s[4:5]
	v_cmp_eq_u32_e64 s[4:5], 0, v2
	s_addc_u32 s11, s87, 0
	v_lshl_add_u64 v[52:53], v[0:1], 0, s[12:13]
	v_lshl_add_u64 v[54:55], s[80:81], 0, v[48:49]
	v_lshl_add_u64 v[56:57], s[78:79], 0, v[48:49]
	s_movk_i32 s29, 0x104
	s_movk_i32 s30, 0x7fff
	s_movk_i32 s31, 0x1000
	s_movk_i32 s34, 0x2000
	s_movk_i32 s35, 0x3000
	v_mov_b32_e32 v64, 1
	v_mbcnt_hi_u32_b32 v65, -1, v212
	s_branch .Lp1b_354

; template <bool STORE>
; DI void peer_item(const Params& p, int item, char* smem) {
;     ...
; #pragma unroll 2
;     for (int k = 0; k < 128; k += 8) {
;       u32x4 uq[8];
;       const int emine = e_s[tl * 128 + k + (lane >> 3)];
;       const float gmine = g_s[tl * 128 + k + (lane >> 3)];
;       const float su = SU[emine], sv = SV[emine];
; #pragma unroll
;       for (int u = 0; u < 8; ++u) {
;         int e = e_s[tl * 128 + k + u];
;         uq[u] = *(const u32x4*)(U8 + (size_t)e * 1024 + lane * 16);
;       }
;       float part[8];
; #pragma unroll
;       for (int u = 0; u < 8; ++u) {
;         float d = 0.f;
; #pragma unroll
;         for (int i = 0; i < 4; ++i) {
;           f32x2_t lo = __builtin_amdgcn_cvt_pk_f32_fp8((int)uq[u][i], false);
;           f32x2_t hi = __builtin_amdgcn_cvt_pk_f32_fp8((int)uq[u][i], true);
;           d += xf[4 * i] * lo.x + xf[4 * i + 1] * lo.y + xf[4 * i + 2] * hi.x + xf[4 * i + 3] * hi.y;
;         }
;         part[u] = d;
;       }
.Lup_k:
	v_readlane_b32 s48, v130, s72
	v_readlane_b32 s49, v130, s73
	v_readlane_b32 s50, v130, s74
	v_readlane_b32 s51, v130, s75
	v_readlane_b32 s52, v130, s76
	v_readlane_b32 s53, v130, s77
	v_readlane_b32 s54, v130, s78
	v_readlane_b32 s55, v130, s79
	s_add_u32 s32, s0, s48
	s_addc_u32 s33, s1, 0
	s_add_u32 s34, s0, s49
	s_addc_u32 s35, s1, 0
	s_add_u32 s36, s0, s50
	s_addc_u32 s37, s1, 0
	s_add_u32 s38, s0, s51
	s_addc_u32 s39, s1, 0
	s_add_u32 s40, s0, s52
	s_addc_u32 s41, s1, 0
	s_add_u32 s42, s0, s53
	s_addc_u32 s43, s1, 0
	s_add_u32 s44, s0, s54
	s_addc_u32 s45, s1, 0
	s_add_u32 s46, s0, s55
	s_addc_u32 s47, s1, 0
	global_load_dwordx4 v[176:179], v234, s[32:33]
	global_load_dwordx4 v[180:183], v234, s[34:35]
	global_load_dwordx4 v[184:187], v234, s[36:37]
	global_load_dwordx4 v[188:191], v234, s[38:39]
	global_load_dwordx4 v[192:195], v234, s[40:41]
	global_load_dwordx4 v[196:199], v234, s[42:43]
	global_load_dwordx4 v[200:203], v234, s[44:45]
	global_load_dwordx4 v[204:207], v234, s[46:47]
	s_waitcnt vmcnt(8)
	v_cvt_pk_f32_fp8_e32 v[214:215], v144
	v_cvt_pk_f32_fp8_sdwa v[216:217], v144 src0_sel:WORD_1
	v_cvt_pk_f32_fp8_e32 v[218:219], v145
	v_cvt_pk_f32_fp8_sdwa v[220:221], v145 src0_sel:WORD_1
	v_pk_mul_f32 v[222:223], v[0:1], v[214:215]
	v_pk_mul_f32 v[224:225], v[2:3], v[216:217]
	v_cvt_pk_f32_fp8_e32 v[214:215], v146
	v_cvt_pk_f32_fp8_sdwa v[216:217], v146 src0_sel:WORD_1
	v_pk_fma_f32 v[222:223], v[4:5], v[218:219], v[222:223]
	v_pk_fma_f32 v[224:225], v[6:7], v[220:221], v[224:225]
	v_cvt_pk_f32_fp8_e32 v[218:219], v147
	v_cvt_pk_f32_fp8_sdwa v[220:221], v147 src0_sel:WORD_1
	v_pk_fma_f32 v[222:223], v[8:9], v[214:215], v[222:223]
	v_pk_fma_f32 v[224:225], v[10:11], v[216:217], v[224:225]
	v_pk_fma_f32 v[222:223], v[12:13], v[218:219], v[222:223]
	v_pk_fma_f32 v[224:225], v[14:15], v[220:221], v[224:225]
	v_pk_add_f32 v[222:223], v[222:223], v[224:225]
	s_nop 0
	v_add_f32_e32 v226, v222, v223
	v_cvt_pk_f32_fp8_e32 v[214:215], v148
	v_cvt_pk_f32_fp8_sdwa v[216:217], v148 src0_sel:WORD_1
	v_cvt_pk_f32_fp8_e32 v[218:219], v149
	v_cvt_pk_f32_fp8_sdwa v[220:221], v149 src0_sel:WORD_1
	v_pk_mul_f32 v[222:223], v[0:1], v[214:215]
	v_pk_mul_f32 v[224:225], v[2:3], v[216:217]
	v_cvt_pk_f32_fp8_e32 v[214:215], v150
	v_cvt_pk_f32_fp8_sdwa v[216:217], v150 src0_sel:WORD_1
	v_pk_fma_f32 v[222:223], v[4:5], v[218:219], v[222:223]
	v_pk_fma_f32 v[224:225], v[6:7], v[220:221], v[224:225]
	v_cvt_pk_f32_fp8_e32 v[218:219], v151
	v_cvt_pk_f32_fp8_sdwa v[220:221], v151 src0_sel:WORD_1
	v_pk_fma_f32 v[222:223], v[8:9], v[214:215], v[222:223]
	v_pk_fma_f32 v[224:225], v[10:11], v[216:217], v[224:225]
	v_pk_fma_f32 v[222:223], v[12:13], v[218:219], v[222:223]
	v_pk_fma_f32 v[224:225], v[14:15], v[220:221], v[224:225]
	v_pk_add_f32 v[222:223], v[222:223], v[224:225]
	s_nop 0
	v_add_f32_e32 v227, v222, v223
	v_cvt_pk_f32_fp8_e32 v[214:215], v152
	v_cvt_pk_f32_fp8_sdwa v[216:217], v152 src0_sel:WORD_1
	v_cvt_pk_f32_fp8_e32 v[218:219], v153
	v_cvt_pk_f32_fp8_sdwa v[220:221], v153 src0_sel:WORD_1
	v_pk_mul_f32 v[222:223], v[0:1], v[214:215]
	v_pk_mul_f32 v[224:225], v[2:3], v[216:217]
	v_cvt_pk_f32_fp8_e32 v[214:215], v154
	v_cvt_pk_f32_fp8_sdwa v[216:217], v154 src0_sel:WORD_1
	v_pk_fma_f32 v[222:223], v[4:5], v[218:219], v[222:223]
	v_pk_fma_f32 v[224:225], v[6:7], v[220:221], v[224:225]
	v_cvt_pk_f32_fp8_e32 v[218:219], v155
	v_cvt_pk_f32_fp8_sdwa v[220:221], v155 src0_sel:WORD_1
	v_pk_fma_f32 v[222:223], v[8:9], v[214:215], v[222:223]
	v_pk_fma_f32 v[224:225], v[10:11], v[216:217], v[224:225]
	v_pk_fma_f32 v[222:223], v[12:13], v[218:219], v[222:223]
	v_pk_fma_f32 v[224:225], v[14:15], v[220:221], v[224:225]
	v_pk_add_f32 v[222:223], v[222:223], v[224:225]
	s_nop 0
	v_add_f32_e32 v228, v222, v223
	v_cvt_pk_f32_fp8_e32 v[214:215], v156
	v_cvt_pk_f32_fp8_sdwa v[216:217], v156 src0_sel:WORD_1
	v_cvt_pk_f32_fp8_e32 v[218:219], v157
	v_cvt_pk_f32_fp8_sdwa v[220:221], v157 src0_sel:WORD_1
	v_pk_mul_f32 v[222:223], v[0:1], v[214:215]
	v_pk_mul_f32 v[224:225], v[2:3], v[216:217]
	v_cvt_pk_f32_fp8_e32 v[214:215], v158
	v_cvt_pk_f32_fp8_sdwa v[216:217], v158 src0_sel:WORD_1
	v_pk_fma_f32 v[222:223], v[4:5], v[218:219], v[222:223]
	v_pk_fma_f32 v[224:225], v[6:7], v[220:221], v[224:225]
	v_cvt_pk_f32_fp8_e32 v[218:219], v159
	v_cvt_pk_f32_fp8_sdwa v[220:221], v159 src0_sel:WORD_1
	v_pk_fma_f32 v[222:223], v[8:9], v[214:215], v[222:223]
	v_pk_fma_f32 v[224:225], v[10:11], v[216:217], v[224:225]
	v_pk_fma_f32 v[222:223], v[12:13], v[218:219], v[222:223]
	v_pk_fma_f32 v[224:225], v[14:15], v[220:221], v[224:225]
	v_pk_add_f32 v[222:223], v[222:223], v[224:225]
	s_nop 0
	v_add_f32_e32 v229, v222, v223
	v_cvt_pk_f32_fp8_e32 v[214:215], v160
	v_cvt_pk_f32_fp8_sdwa v[216:217], v160 src0_sel:WORD_1
	v_cvt_pk_f32_fp8_e32 v[218:219], v161
	v_cvt_pk_f32_fp8_sdwa v[220:221], v161 src0_sel:WORD_1
	v_pk_mul_f32 v[222:223], v[0:1], v[214:215]
	v_pk_mul_f32 v[224:225], v[2:3], v[216:217]
	v_cvt_pk_f32_fp8_e32 v[214:215], v162
	v_cvt_pk_f32_fp8_sdwa v[216:217], v162 src0_sel:WORD_1
	v_pk_fma_f32 v[222:223], v[4:5], v[218:219], v[222:223]
	v_pk_fma_f32 v[224:225], v[6:7], v[220:221], v[224:225]
	v_cvt_pk_f32_fp8_e32 v[218:219], v163
	v_cvt_pk_f32_fp8_sdwa v[220:221], v163 src0_sel:WORD_1
	v_pk_fma_f32 v[222:223], v[8:9], v[214:215], v[222:223]
	v_pk_fma_f32 v[224:225], v[10:11], v[216:217], v[224:225]
	v_pk_fma_f32 v[222:223], v[12:13], v[218:219], v[222:223]
	v_pk_fma_f32 v[224:225], v[14:15], v[220:221], v[224:225]
	v_pk_add_f32 v[222:223], v[222:223], v[224:225]
	s_nop 0
	v_add_f32_e32 v230, v222, v223
	v_cvt_pk_f32_fp8_e32 v[214:215], v164
; template <bool STORE>
; DI void peer_item(const Params& p, int item, char* smem) {
;     ...
;       float part[8];
; #pragma unroll
;       for (int u = 0; u < 8; ++u) {
;         float d = 0.f;
; #pragma unroll
;         for (int i = 0; i < 4; ++i) {
;           f32x2_t lo = __builtin_amdgcn_cvt_pk_f32_fp8((int)uq[u][i], false);
;           f32x2_t hi = __builtin_amdgcn_cvt_pk_f32_fp8((int)uq[u][i], true);
;           d += xf[4 * i] * lo.x + xf[4 * i + 1] * lo.y + xf[4 * i + 2] * hi.x + xf[4 * i + 3] * hi.y;
;         }
;         part[u] = d;
;       }
;       float q4[4], r2[2], h;
; #pragma unroll
;       for (int j = 0; j < 4; ++j) {
;         float mine = b5 ? part[j + 4] : part[j];
;         float other = b5 ? part[j] : part[j + 4];
;         q4[j] = mine + __shfl_xor(other, 32);
;       }
; #pragma unroll
;       for (int j = 0; j < 2; ++j) {
;         float mine = b4 ? q4[j + 2] : q4[j];
;         float other = b4 ? q4[j] : q4[j + 2];
;         r2[j] = mine + __shfl_xor(other, 16);
;       }
;       {
;         float mine = b3 ? r2[1] : r2[0];
;         float other = b3 ? r2[0] : r2[1];
;         h = mine + __shfl_xor(other, 8);
;       }
;       h += __shfl_xor(h, 4);
;       h += __shfl_xor(h, 2);
;       h += __shfl_xor(h, 1);
	v_cvt_pk_f32_fp8_sdwa v[216:217], v164 src0_sel:WORD_1
	v_cvt_pk_f32_fp8_e32 v[218:219], v165
	v_cvt_pk_f32_fp8_sdwa v[220:221], v165 src0_sel:WORD_1
	v_pk_mul_f32 v[222:223], v[0:1], v[214:215]
	v_pk_mul_f32 v[224:225], v[2:3], v[216:217]
	v_cvt_pk_f32_fp8_e32 v[214:215], v166
	v_cvt_pk_f32_fp8_sdwa v[216:217], v166 src0_sel:WORD_1
	v_pk_fma_f32 v[222:223], v[4:5], v[218:219], v[222:223]
	v_pk_fma_f32 v[224:225], v[6:7], v[220:221], v[224:225]
	v_cvt_pk_f32_fp8_e32 v[218:219], v167
	v_cvt_pk_f32_fp8_sdwa v[220:221], v167 src0_sel:WORD_1
	v_pk_fma_f32 v[222:223], v[8:9], v[214:215], v[222:223]
	v_pk_fma_f32 v[224:225], v[10:11], v[216:217], v[224:225]
	v_pk_fma_f32 v[222:223], v[12:13], v[218:219], v[222:223]
	v_pk_fma_f32 v[224:225], v[14:15], v[220:221], v[224:225]
	v_pk_add_f32 v[222:223], v[222:223], v[224:225]
	s_nop 0
	v_add_f32_e32 v231, v222, v223
	v_cvt_pk_f32_fp8_e32 v[214:215], v168
	v_cvt_pk_f32_fp8_sdwa v[216:217], v168 src0_sel:WORD_1
	v_cvt_pk_f32_fp8_e32 v[218:219], v169
	v_cvt_pk_f32_fp8_sdwa v[220:221], v169 src0_sel:WORD_1
	v_pk_mul_f32 v[222:223], v[0:1], v[214:215]
	v_pk_mul_f32 v[224:225], v[2:3], v[216:217]
	v_cvt_pk_f32_fp8_e32 v[214:215], v170
	v_cvt_pk_f32_fp8_sdwa v[216:217], v170 src0_sel:WORD_1
	v_pk_fma_f32 v[222:223], v[4:5], v[218:219], v[222:223]
	v_pk_fma_f32 v[224:225], v[6:7], v[220:221], v[224:225]
	v_cvt_pk_f32_fp8_e32 v[218:219], v171
	v_cvt_pk_f32_fp8_sdwa v[220:221], v171 src0_sel:WORD_1
	v_pk_fma_f32 v[222:223], v[8:9], v[214:215], v[222:223]
	v_pk_fma_f32 v[224:225], v[10:11], v[216:217], v[224:225]
	v_pk_fma_f32 v[222:223], v[12:13], v[218:219], v[222:223]
	v_pk_fma_f32 v[224:225], v[14:15], v[220:221], v[224:225]
	v_pk_add_f32 v[222:223], v[222:223], v[224:225]
	s_nop 0
	v_add_f32_e32 v232, v222, v223
	v_cvt_pk_f32_fp8_e32 v[214:215], v172
	v_cvt_pk_f32_fp8_sdwa v[216:217], v172 src0_sel:WORD_1
	v_cvt_pk_f32_fp8_e32 v[218:219], v173
	v_cvt_pk_f32_fp8_sdwa v[220:221], v173 src0_sel:WORD_1
	v_pk_mul_f32 v[222:223], v[0:1], v[214:215]
	v_pk_mul_f32 v[224:225], v[2:3], v[216:217]
	v_cvt_pk_f32_fp8_e32 v[214:215], v174
	v_cvt_pk_f32_fp8_sdwa v[216:217], v174 src0_sel:WORD_1
	v_pk_fma_f32 v[222:223], v[4:5], v[218:219], v[222:223]
	v_pk_fma_f32 v[224:225], v[6:7], v[220:221], v[224:225]
	v_cvt_pk_f32_fp8_e32 v[218:219], v175
	v_cvt_pk_f32_fp8_sdwa v[220:221], v175 src0_sel:WORD_1
	v_pk_fma_f32 v[222:223], v[8:9], v[214:215], v[222:223]
	v_pk_fma_f32 v[224:225], v[10:11], v[216:217], v[224:225]
	v_pk_fma_f32 v[222:223], v[12:13], v[218:219], v[222:223]
	v_pk_fma_f32 v[224:225], v[14:15], v[220:221], v[224:225]
	v_pk_add_f32 v[222:223], v[222:223], v[224:225]
	s_nop 0
	v_add_f32_e32 v233, v222, v223
	v_permlane32_swap_b32_e32 v226, v230
	v_permlane32_swap_b32_e32 v227, v231
	v_permlane32_swap_b32_e32 v228, v232
	v_permlane32_swap_b32_e32 v229, v233
	v_add_f32_e32 v226, v226, v230
	v_add_f32_e32 v228, v228, v232
	v_add_f32_e32 v227, v227, v231
	v_add_f32_e32 v229, v229, v233
	s_nop 1
	v_permlane16_swap_b32_e32 v226, v228
	v_permlane16_swap_b32_e32 v227, v229
	v_add_f32_e32 v226, v226, v228
	v_add_f32_e32 v227, v227, v229
	s_nop 0
	v_cndmask_b32_e64 v230, v226, v227, s[24:25]
	v_cndmask_b32_e64 v231, v227, v226, s[24:25]
	s_nop 1
	v_add_f32_dpp v232, v231, v230 row_ror:8 row_mask:0xf bank_mask:0xf
	s_nop 1
	v_add_f32_dpp v233, v232, v232 quad_perm:[1,0,3,2] row_mask:0xf bank_mask:0xf
	s_nop 1
	v_add_f32_dpp v232, v233, v233 quad_perm:[2,3,0,1] row_mask:0xf bank_mask:0xf
	s_nop 1
	v_add_f32_dpp v233, v232, v232 row_half_mirror row_mask:0xf bank_mask:0xf
	ds_write_b32 v235, v233 offset:32768
	v_readlane_b32 s48, v132, s72
	v_readlane_b32 s49, v132, s73
	v_readlane_b32 s50, v132, s74
	v_readlane_b32 s51, v132, s75
	v_readlane_b32 s52, v132, s76
	v_readlane_b32 s53, v132, s77
	v_readlane_b32 s54, v132, s78
	v_readlane_b32 s55, v132, s79
	s_add_u32 s32, s0, s48
	s_addc_u32 s33, s1, 0
	s_add_u32 s34, s0, s49
	s_addc_u32 s35, s1, 0
	s_add_u32 s36, s0, s50
	s_addc_u32 s37, s1, 0
	s_add_u32 s38, s0, s51
	s_addc_u32 s39, s1, 0
	s_add_u32 s40, s0, s52
	s_addc_u32 s41, s1, 0
	s_add_u32 s42, s0, s53
	s_addc_u32 s43, s1, 0
	s_add_u32 s44, s0, s54
	s_addc_u32 s45, s1, 0
	s_add_u32 s46, s0, s55
	s_addc_u32 s47, s1, 0
	global_load_dwordx4 v[144:147], v234, s[32:33]
	global_load_dwordx4 v[148:151], v234, s[34:35]
	global_load_dwordx4 v[152:155], v234, s[36:37]
	global_load_dwordx4 v[156:159], v234, s[38:39]
	global_load_dwordx4 v[160:163], v234, s[40:41]
	global_load_dwordx4 v[164:167], v234, s[42:43]
	global_load_dwordx4 v[168:171], v234, s[44:45]
	global_load_dwordx4 v[172:175], v234, s[46:47]
	s_waitcnt vmcnt(8)
; template <bool STORE>
; DI void peer_item(const Params& p, int item, char* smem) {
;     ...
;       float part[8];
; #pragma unroll
;       for (int u = 0; u < 8; ++u) {
;         float d = 0.f;
; #pragma unroll
;         for (int i = 0; i < 4; ++i) {
;           f32x2_t lo = __builtin_amdgcn_cvt_pk_f32_fp8((int)uq[u][i], false);
;           f32x2_t hi = __builtin_amdgcn_cvt_pk_f32_fp8((int)uq[u][i], true);
;           d += xf[4 * i] * lo.x + xf[4 * i + 1] * lo.y + xf[4 * i + 2] * hi.x + xf[4 * i + 3] * hi.y;
;         }
;         part[u] = d;
;       }
	v_cvt_pk_f32_fp8_e32 v[214:215], v176
	v_cvt_pk_f32_fp8_sdwa v[216:217], v176 src0_sel:WORD_1
	v_cvt_pk_f32_fp8_e32 v[218:219], v177
	v_cvt_pk_f32_fp8_sdwa v[220:221], v177 src0_sel:WORD_1
	v_pk_mul_f32 v[222:223], v[16:17], v[214:215]
	v_pk_mul_f32 v[224:225], v[18:19], v[216:217]
	v_cvt_pk_f32_fp8_e32 v[214:215], v178
	v_cvt_pk_f32_fp8_sdwa v[216:217], v178 src0_sel:WORD_1
	v_pk_fma_f32 v[222:223], v[20:21], v[218:219], v[222:223]
	v_pk_fma_f32 v[224:225], v[22:23], v[220:221], v[224:225]
	v_cvt_pk_f32_fp8_e32 v[218:219], v179
	v_cvt_pk_f32_fp8_sdwa v[220:221], v179 src0_sel:WORD_1
	v_pk_fma_f32 v[222:223], v[24:25], v[214:215], v[222:223]
	v_pk_fma_f32 v[224:225], v[26:27], v[216:217], v[224:225]
	v_pk_fma_f32 v[222:223], v[28:29], v[218:219], v[222:223]
	v_pk_fma_f32 v[224:225], v[30:31], v[220:221], v[224:225]
	v_pk_add_f32 v[222:223], v[222:223], v[224:225]
	s_nop 0
	v_add_f32_e32 v226, v222, v223
	v_cvt_pk_f32_fp8_e32 v[214:215], v180
	v_cvt_pk_f32_fp8_sdwa v[216:217], v180 src0_sel:WORD_1
	v_cvt_pk_f32_fp8_e32 v[218:219], v181
	v_cvt_pk_f32_fp8_sdwa v[220:221], v181 src0_sel:WORD_1
	v_pk_mul_f32 v[222:223], v[16:17], v[214:215]
	v_pk_mul_f32 v[224:225], v[18:19], v[216:217]
	v_cvt_pk_f32_fp8_e32 v[214:215], v182
	v_cvt_pk_f32_fp8_sdwa v[216:217], v182 src0_sel:WORD_1
	v_pk_fma_f32 v[222:223], v[20:21], v[218:219], v[222:223]
	v_pk_fma_f32 v[224:225], v[22:23], v[220:221], v[224:225]
	v_cvt_pk_f32_fp8_e32 v[218:219], v183
	v_cvt_pk_f32_fp8_sdwa v[220:221], v183 src0_sel:WORD_1
	v_pk_fma_f32 v[222:223], v[24:25], v[214:215], v[222:223]
	v_pk_fma_f32 v[224:225], v[26:27], v[216:217], v[224:225]
	v_pk_fma_f32 v[222:223], v[28:29], v[218:219], v[222:223]
	v_pk_fma_f32 v[224:225], v[30:31], v[220:221], v[224:225]
	v_pk_add_f32 v[222:223], v[222:223], v[224:225]
	s_nop 0
	v_add_f32_e32 v227, v222, v223
	v_cvt_pk_f32_fp8_e32 v[214:215], v184
	v_cvt_pk_f32_fp8_sdwa v[216:217], v184 src0_sel:WORD_1
	v_cvt_pk_f32_fp8_e32 v[218:219], v185
	v_cvt_pk_f32_fp8_sdwa v[220:221], v185 src0_sel:WORD_1
	v_pk_mul_f32 v[222:223], v[16:17], v[214:215]
	v_pk_mul_f32 v[224:225], v[18:19], v[216:217]
	v_cvt_pk_f32_fp8_e32 v[214:215], v186
	v_cvt_pk_f32_fp8_sdwa v[216:217], v186 src0_sel:WORD_1
	v_pk_fma_f32 v[222:223], v[20:21], v[218:219], v[222:223]
	v_pk_fma_f32 v[224:225], v[22:23], v[220:221], v[224:225]
	v_cvt_pk_f32_fp8_e32 v[218:219], v187
	v_cvt_pk_f32_fp8_sdwa v[220:221], v187 src0_sel:WORD_1
	v_pk_fma_f32 v[222:223], v[24:25], v[214:215], v[222:223]
	v_pk_fma_f32 v[224:225], v[26:27], v[216:217], v[224:225]
	v_pk_fma_f32 v[222:223], v[28:29], v[218:219], v[222:223]
	v_pk_fma_f32 v[224:225], v[30:31], v[220:221], v[224:225]
	v_pk_add_f32 v[222:223], v[222:223], v[224:225]
	s_nop 0
	v_add_f32_e32 v228, v222, v223
	v_cvt_pk_f32_fp8_e32 v[214:215], v188
	v_cvt_pk_f32_fp8_sdwa v[216:217], v188 src0_sel:WORD_1
	v_cvt_pk_f32_fp8_e32 v[218:219], v189
	v_cvt_pk_f32_fp8_sdwa v[220:221], v189 src0_sel:WORD_1
	v_pk_mul_f32 v[222:223], v[16:17], v[214:215]
	v_pk_mul_f32 v[224:225], v[18:19], v[216:217]
	v_cvt_pk_f32_fp8_e32 v[214:215], v190
	v_cvt_pk_f32_fp8_sdwa v[216:217], v190 src0_sel:WORD_1
	v_pk_fma_f32 v[222:223], v[20:21], v[218:219], v[222:223]
	v_pk_fma_f32 v[224:225], v[22:23], v[220:221], v[224:225]
	v_cvt_pk_f32_fp8_e32 v[218:219], v191
	v_cvt_pk_f32_fp8_sdwa v[220:221], v191 src0_sel:WORD_1
	v_pk_fma_f32 v[222:223], v[24:25], v[214:215], v[222:223]
	v_pk_fma_f32 v[224:225], v[26:27], v[216:217], v[224:225]
	v_pk_fma_f32 v[222:223], v[28:29], v[218:219], v[222:223]
	v_pk_fma_f32 v[224:225], v[30:31], v[220:221], v[224:225]
	v_pk_add_f32 v[222:223], v[222:223], v[224:225]
	s_nop 0
	v_add_f32_e32 v229, v222, v223
	v_cvt_pk_f32_fp8_e32 v[214:215], v192
	v_cvt_pk_f32_fp8_sdwa v[216:217], v192 src0_sel:WORD_1
	v_cvt_pk_f32_fp8_e32 v[218:219], v193
	v_cvt_pk_f32_fp8_sdwa v[220:221], v193 src0_sel:WORD_1
	v_pk_mul_f32 v[222:223], v[16:17], v[214:215]
	v_pk_mul_f32 v[224:225], v[18:19], v[216:217]
	v_cvt_pk_f32_fp8_e32 v[214:215], v194
	v_cvt_pk_f32_fp8_sdwa v[216:217], v194 src0_sel:WORD_1
	v_pk_fma_f32 v[222:223], v[20:21], v[218:219], v[222:223]
	v_pk_fma_f32 v[224:225], v[22:23], v[220:221], v[224:225]
	v_cvt_pk_f32_fp8_e32 v[218:219], v195
	v_cvt_pk_f32_fp8_sdwa v[220:221], v195 src0_sel:WORD_1
	v_pk_fma_f32 v[222:223], v[24:25], v[214:215], v[222:223]
	v_pk_fma_f32 v[224:225], v[26:27], v[216:217], v[224:225]
	v_pk_fma_f32 v[222:223], v[28:29], v[218:219], v[222:223]
	v_pk_fma_f32 v[224:225], v[30:31], v[220:221], v[224:225]
	v_pk_add_f32 v[222:223], v[222:223], v[224:225]
	s_nop 0
	v_add_f32_e32 v230, v222, v223
	v_cvt_pk_f32_fp8_e32 v[214:215], v196
	v_cvt_pk_f32_fp8_sdwa v[216:217], v196 src0_sel:WORD_1
	v_cvt_pk_f32_fp8_e32 v[218:219], v197
	v_cvt_pk_f32_fp8_sdwa v[220:221], v197 src0_sel:WORD_1
	v_pk_mul_f32 v[222:223], v[16:17], v[214:215]
	v_pk_mul_f32 v[224:225], v[18:19], v[216:217]
	v_cvt_pk_f32_fp8_e32 v[214:215], v198
	v_cvt_pk_f32_fp8_sdwa v[216:217], v198 src0_sel:WORD_1
	v_pk_fma_f32 v[222:223], v[20:21], v[218:219], v[222:223]
	v_pk_fma_f32 v[224:225], v[22:23], v[220:221], v[224:225]
	v_cvt_pk_f32_fp8_e32 v[218:219], v199
	v_cvt_pk_f32_fp8_sdwa v[220:221], v199 src0_sel:WORD_1
	v_pk_fma_f32 v[222:223], v[24:25], v[214:215], v[222:223]
	v_pk_fma_f32 v[224:225], v[26:27], v[216:217], v[224:225]
	v_pk_fma_f32 v[222:223], v[28:29], v[218:219], v[222:223]
	v_pk_fma_f32 v[224:225], v[30:31], v[220:221], v[224:225]
	v_pk_add_f32 v[222:223], v[222:223], v[224:225]
	s_nop 0
	v_add_f32_e32 v231, v222, v223
	v_cvt_pk_f32_fp8_e32 v[214:215], v200
	v_cvt_pk_f32_fp8_sdwa v[216:217], v200 src0_sel:WORD_1
	v_cvt_pk_f32_fp8_e32 v[218:219], v201
; template <bool STORE>
; DI void peer_item(const Params& p, int item, char* smem) {
;     ...
;       float part[8];
; #pragma unroll
;       for (int u = 0; u < 8; ++u) {
;         float d = 0.f;
; #pragma unroll
;         for (int i = 0; i < 4; ++i) {
;           f32x2_t lo = __builtin_amdgcn_cvt_pk_f32_fp8((int)uq[u][i], false);
;           f32x2_t hi = __builtin_amdgcn_cvt_pk_f32_fp8((int)uq[u][i], true);
;           d += xf[4 * i] * lo.x + xf[4 * i + 1] * lo.y + xf[4 * i + 2] * hi.x + xf[4 * i + 3] * hi.y;
;         }
;         part[u] = d;
;       }
;       float q4[4], r2[2], h;
; #pragma unroll
;       for (int j = 0; j < 4; ++j) {
;         float mine = b5 ? part[j + 4] : part[j];
;         float other = b5 ? part[j] : part[j + 4];
;         q4[j] = mine + __shfl_xor(other, 32);
;       }
; #pragma unroll
;       for (int j = 0; j < 2; ++j) {
;         float mine = b4 ? q4[j + 2] : q4[j];
;         float other = b4 ? q4[j] : q4[j + 2];
;         r2[j] = mine + __shfl_xor(other, 16);
;       }
;       {
;         float mine = b3 ? r2[1] : r2[0];
;         float other = b3 ? r2[0] : r2[1];
;         h = mine + __shfl_xor(other, 8);
;       }
;       h += __shfl_xor(h, 4);
;       h += __shfl_xor(h, 2);
;       h += __shfl_xor(h, 1);
	v_cvt_pk_f32_fp8_sdwa v[220:221], v201 src0_sel:WORD_1
	v_pk_mul_f32 v[222:223], v[16:17], v[214:215]
	v_pk_mul_f32 v[224:225], v[18:19], v[216:217]
	v_cvt_pk_f32_fp8_e32 v[214:215], v202
	v_cvt_pk_f32_fp8_sdwa v[216:217], v202 src0_sel:WORD_1
	v_pk_fma_f32 v[222:223], v[20:21], v[218:219], v[222:223]
	v_pk_fma_f32 v[224:225], v[22:23], v[220:221], v[224:225]
	v_cvt_pk_f32_fp8_e32 v[218:219], v203
	v_cvt_pk_f32_fp8_sdwa v[220:221], v203 src0_sel:WORD_1
	v_pk_fma_f32 v[222:223], v[24:25], v[214:215], v[222:223]
	v_pk_fma_f32 v[224:225], v[26:27], v[216:217], v[224:225]
	v_pk_fma_f32 v[222:223], v[28:29], v[218:219], v[222:223]
	v_pk_fma_f32 v[224:225], v[30:31], v[220:221], v[224:225]
	v_pk_add_f32 v[222:223], v[222:223], v[224:225]
	s_nop 0
	v_add_f32_e32 v232, v222, v223
	v_cvt_pk_f32_fp8_e32 v[214:215], v204
	v_cvt_pk_f32_fp8_sdwa v[216:217], v204 src0_sel:WORD_1
	v_cvt_pk_f32_fp8_e32 v[218:219], v205
	v_cvt_pk_f32_fp8_sdwa v[220:221], v205 src0_sel:WORD_1
	v_pk_mul_f32 v[222:223], v[16:17], v[214:215]
	v_pk_mul_f32 v[224:225], v[18:19], v[216:217]
	v_cvt_pk_f32_fp8_e32 v[214:215], v206
	v_cvt_pk_f32_fp8_sdwa v[216:217], v206 src0_sel:WORD_1
	v_pk_fma_f32 v[222:223], v[20:21], v[218:219], v[222:223]
	v_pk_fma_f32 v[224:225], v[22:23], v[220:221], v[224:225]
	v_cvt_pk_f32_fp8_e32 v[218:219], v207
	v_cvt_pk_f32_fp8_sdwa v[220:221], v207 src0_sel:WORD_1
	v_pk_fma_f32 v[222:223], v[24:25], v[214:215], v[222:223]
	v_pk_fma_f32 v[224:225], v[26:27], v[216:217], v[224:225]
	v_pk_fma_f32 v[222:223], v[28:29], v[218:219], v[222:223]
	v_pk_fma_f32 v[224:225], v[30:31], v[220:221], v[224:225]
	v_pk_add_f32 v[222:223], v[222:223], v[224:225]
	s_nop 0
	v_add_f32_e32 v233, v222, v223
	v_permlane32_swap_b32_e32 v226, v230
	v_permlane32_swap_b32_e32 v227, v231
	v_permlane32_swap_b32_e32 v228, v232
	v_permlane32_swap_b32_e32 v229, v233
	v_add_f32_e32 v226, v226, v230
	v_add_f32_e32 v228, v228, v232
	v_add_f32_e32 v227, v227, v231
	v_add_f32_e32 v229, v229, v233
	s_nop 1
	v_permlane16_swap_b32_e32 v226, v228
	v_permlane16_swap_b32_e32 v227, v229
	v_add_f32_e32 v226, v226, v228
	v_add_f32_e32 v227, v227, v229
	s_nop 0
	v_cndmask_b32_e64 v230, v226, v227, s[24:25]
	v_cndmask_b32_e64 v231, v227, v226, s[24:25]
	s_nop 1
	v_add_f32_dpp v232, v231, v230 row_ror:8 row_mask:0xf bank_mask:0xf
	s_nop 1
	v_add_f32_dpp v233, v232, v232 quad_perm:[1,0,3,2] row_mask:0xf bank_mask:0xf
	s_nop 1
	v_add_f32_dpp v232, v233, v233 quad_perm:[2,3,0,1] row_mask:0xf bank_mask:0xf
	s_nop 1
	v_add_f32_dpp v233, v232, v232 row_half_mirror row_mask:0xf bank_mask:0xf
	ds_write_b32 v235, v233 offset:33280
	v_readlane_b32 s48, v134, s72
	v_readlane_b32 s49, v134, s73
	v_readlane_b32 s50, v134, s74
	v_readlane_b32 s51, v134, s75
	v_readlane_b32 s52, v134, s76
	v_readlane_b32 s53, v134, s77
	v_readlane_b32 s54, v134, s78
	v_readlane_b32 s55, v134, s79
	s_add_u32 s32, s0, s48
	s_addc_u32 s33, s1, 0
	s_add_u32 s34, s0, s49
	s_addc_u32 s35, s1, 0
	s_add_u32 s36, s0, s50
	s_addc_u32 s37, s1, 0
	s_add_u32 s38, s0, s51
	s_addc_u32 s39, s1, 0
	s_add_u32 s40, s0, s52
	s_addc_u32 s41, s1, 0
	s_add_u32 s42, s0, s53
	s_addc_u32 s43, s1, 0
	s_add_u32 s44, s0, s54
	s_addc_u32 s45, s1, 0
	s_add_u32 s46, s0, s55
	s_addc_u32 s47, s1, 0
	global_load_dwordx4 v[176:179], v234, s[32:33]
	global_load_dwordx4 v[180:183], v234, s[34:35]
	global_load_dwordx4 v[184:187], v234, s[36:37]
	global_load_dwordx4 v[188:191], v234, s[38:39]
	global_load_dwordx4 v[192:195], v234, s[40:41]
	global_load_dwordx4 v[196:199], v234, s[42:43]
	global_load_dwordx4 v[200:203], v234, s[44:45]
	global_load_dwordx4 v[204:207], v234, s[46:47]
	s_waitcnt vmcnt(8)
	v_cvt_pk_f32_fp8_e32 v[214:215], v144
	v_cvt_pk_f32_fp8_sdwa v[216:217], v144 src0_sel:WORD_1
	v_cvt_pk_f32_fp8_e32 v[218:219], v145
	v_cvt_pk_f32_fp8_sdwa v[220:221], v145 src0_sel:WORD_1
	v_pk_mul_f32 v[222:223], v[32:33], v[214:215]
	v_pk_mul_f32 v[224:225], v[34:35], v[216:217]
	v_cvt_pk_f32_fp8_e32 v[214:215], v146
	v_cvt_pk_f32_fp8_sdwa v[216:217], v146 src0_sel:WORD_1
	v_pk_fma_f32 v[222:223], v[36:37], v[218:219], v[222:223]
	v_pk_fma_f32 v[224:225], v[38:39], v[220:221], v[224:225]
	v_cvt_pk_f32_fp8_e32 v[218:219], v147
	v_cvt_pk_f32_fp8_sdwa v[220:221], v147 src0_sel:WORD_1
	v_pk_fma_f32 v[222:223], v[40:41], v[214:215], v[222:223]
	v_pk_fma_f32 v[224:225], v[42:43], v[216:217], v[224:225]
	v_pk_fma_f32 v[222:223], v[44:45], v[218:219], v[222:223]
	v_pk_fma_f32 v[224:225], v[46:47], v[220:221], v[224:225]
	v_pk_add_f32 v[222:223], v[222:223], v[224:225]
	s_nop 0
	v_add_f32_e32 v226, v222, v223
	v_cvt_pk_f32_fp8_e32 v[214:215], v148
	v_cvt_pk_f32_fp8_sdwa v[216:217], v148 src0_sel:WORD_1
	v_cvt_pk_f32_fp8_e32 v[218:219], v149
	v_cvt_pk_f32_fp8_sdwa v[220:221], v149 src0_sel:WORD_1
	v_pk_mul_f32 v[222:223], v[32:33], v[214:215]
	v_pk_mul_f32 v[224:225], v[34:35], v[216:217]
	v_cvt_pk_f32_fp8_e32 v[214:215], v150
	v_cvt_pk_f32_fp8_sdwa v[216:217], v150 src0_sel:WORD_1
	v_pk_fma_f32 v[222:223], v[36:37], v[218:219], v[222:223]
	v_pk_fma_f32 v[224:225], v[38:39], v[220:221], v[224:225]
	v_cvt_pk_f32_fp8_e32 v[218:219], v151
	v_cvt_pk_f32_fp8_sdwa v[220:221], v151 src0_sel:WORD_1
	v_pk_fma_f32 v[222:223], v[40:41], v[214:215], v[222:223]
	v_pk_fma_f32 v[224:225], v[42:43], v[216:217], v[224:225]
	v_pk_fma_f32 v[222:223], v[44:45], v[218:219], v[222:223]
	v_pk_fma_f32 v[224:225], v[46:47], v[220:221], v[224:225]
	v_pk_add_f32 v[222:223], v[222:223], v[224:225]
	s_nop 0
	v_add_f32_e32 v227, v222, v223
	v_cvt_pk_f32_fp8_e32 v[214:215], v152
	v_cvt_pk_f32_fp8_sdwa v[216:217], v152 src0_sel:WORD_1
	v_cvt_pk_f32_fp8_e32 v[218:219], v153
	v_cvt_pk_f32_fp8_sdwa v[220:221], v153 src0_sel:WORD_1
; template <bool STORE>
; DI void peer_item(const Params& p, int item, char* smem) {
;     ...
;       float part[8];
; #pragma unroll
;       for (int u = 0; u < 8; ++u) {
;         float d = 0.f;
; #pragma unroll
;         for (int i = 0; i < 4; ++i) {
;           f32x2_t lo = __builtin_amdgcn_cvt_pk_f32_fp8((int)uq[u][i], false);
;           f32x2_t hi = __builtin_amdgcn_cvt_pk_f32_fp8((int)uq[u][i], true);
;           d += xf[4 * i] * lo.x + xf[4 * i + 1] * lo.y + xf[4 * i + 2] * hi.x + xf[4 * i + 3] * hi.y;
;         }
;         part[u] = d;
;       }
;       float q4[4], r2[2], h;
; #pragma unroll
;       for (int j = 0; j < 4; ++j) {
;         float mine = b5 ? part[j + 4] : part[j];
;         float other = b5 ? part[j] : part[j + 4];
;         q4[j] = mine + __shfl_xor(other, 32);
;       }
; #pragma unroll
;       for (int j = 0; j < 2; ++j) {
;         float mine = b4 ? q4[j + 2] : q4[j];
;         float other = b4 ? q4[j] : q4[j + 2];
;         r2[j] = mine + __shfl_xor(other, 16);
;       }
;       {
;         float mine = b3 ? r2[1] : r2[0];
;         float other = b3 ? r2[0] : r2[1];
;         h = mine + __shfl_xor(other, 8);
;       }
;       h += __shfl_xor(h, 4);
;       h += __shfl_xor(h, 2);
;       h += __shfl_xor(h, 1);
	v_pk_mul_f32 v[222:223], v[32:33], v[214:215]
	v_pk_mul_f32 v[224:225], v[34:35], v[216:217]
	v_cvt_pk_f32_fp8_e32 v[214:215], v154
	v_cvt_pk_f32_fp8_sdwa v[216:217], v154 src0_sel:WORD_1
	v_pk_fma_f32 v[222:223], v[36:37], v[218:219], v[222:223]
	v_pk_fma_f32 v[224:225], v[38:39], v[220:221], v[224:225]
	v_cvt_pk_f32_fp8_e32 v[218:219], v155
	v_cvt_pk_f32_fp8_sdwa v[220:221], v155 src0_sel:WORD_1
	v_pk_fma_f32 v[222:223], v[40:41], v[214:215], v[222:223]
	v_pk_fma_f32 v[224:225], v[42:43], v[216:217], v[224:225]
	v_pk_fma_f32 v[222:223], v[44:45], v[218:219], v[222:223]
	v_pk_fma_f32 v[224:225], v[46:47], v[220:221], v[224:225]
	v_pk_add_f32 v[222:223], v[222:223], v[224:225]
	s_nop 0
	v_add_f32_e32 v228, v222, v223
	v_cvt_pk_f32_fp8_e32 v[214:215], v156
	v_cvt_pk_f32_fp8_sdwa v[216:217], v156 src0_sel:WORD_1
	v_cvt_pk_f32_fp8_e32 v[218:219], v157
	v_cvt_pk_f32_fp8_sdwa v[220:221], v157 src0_sel:WORD_1
	v_pk_mul_f32 v[222:223], v[32:33], v[214:215]
	v_pk_mul_f32 v[224:225], v[34:35], v[216:217]
	v_cvt_pk_f32_fp8_e32 v[214:215], v158
	v_cvt_pk_f32_fp8_sdwa v[216:217], v158 src0_sel:WORD_1
	v_pk_fma_f32 v[222:223], v[36:37], v[218:219], v[222:223]
	v_pk_fma_f32 v[224:225], v[38:39], v[220:221], v[224:225]
	v_cvt_pk_f32_fp8_e32 v[218:219], v159
	v_cvt_pk_f32_fp8_sdwa v[220:221], v159 src0_sel:WORD_1
	v_pk_fma_f32 v[222:223], v[40:41], v[214:215], v[222:223]
	v_pk_fma_f32 v[224:225], v[42:43], v[216:217], v[224:225]
	v_pk_fma_f32 v[222:223], v[44:45], v[218:219], v[222:223]
	v_pk_fma_f32 v[224:225], v[46:47], v[220:221], v[224:225]
	v_pk_add_f32 v[222:223], v[222:223], v[224:225]
	s_nop 0
	v_add_f32_e32 v229, v222, v223
	v_cvt_pk_f32_fp8_e32 v[214:215], v160
	v_cvt_pk_f32_fp8_sdwa v[216:217], v160 src0_sel:WORD_1
	v_cvt_pk_f32_fp8_e32 v[218:219], v161
	v_cvt_pk_f32_fp8_sdwa v[220:221], v161 src0_sel:WORD_1
	v_pk_mul_f32 v[222:223], v[32:33], v[214:215]
	v_pk_mul_f32 v[224:225], v[34:35], v[216:217]
	v_cvt_pk_f32_fp8_e32 v[214:215], v162
	v_cvt_pk_f32_fp8_sdwa v[216:217], v162 src0_sel:WORD_1
	v_pk_fma_f32 v[222:223], v[36:37], v[218:219], v[222:223]
	v_pk_fma_f32 v[224:225], v[38:39], v[220:221], v[224:225]
	v_cvt_pk_f32_fp8_e32 v[218:219], v163
	v_cvt_pk_f32_fp8_sdwa v[220:221], v163 src0_sel:WORD_1
	v_pk_fma_f32 v[222:223], v[40:41], v[214:215], v[222:223]
	v_pk_fma_f32 v[224:225], v[42:43], v[216:217], v[224:225]
	v_pk_fma_f32 v[222:223], v[44:45], v[218:219], v[222:223]
	v_pk_fma_f32 v[224:225], v[46:47], v[220:221], v[224:225]
	v_pk_add_f32 v[222:223], v[222:223], v[224:225]
	s_nop 0
	v_add_f32_e32 v230, v222, v223
	v_cvt_pk_f32_fp8_e32 v[214:215], v164
	v_cvt_pk_f32_fp8_sdwa v[216:217], v164 src0_sel:WORD_1
	v_cvt_pk_f32_fp8_e32 v[218:219], v165
	v_cvt_pk_f32_fp8_sdwa v[220:221], v165 src0_sel:WORD_1
	v_pk_mul_f32 v[222:223], v[32:33], v[214:215]
	v_pk_mul_f32 v[224:225], v[34:35], v[216:217]
	v_cvt_pk_f32_fp8_e32 v[214:215], v166
	v_cvt_pk_f32_fp8_sdwa v[216:217], v166 src0_sel:WORD_1
	v_pk_fma_f32 v[222:223], v[36:37], v[218:219], v[222:223]
	v_pk_fma_f32 v[224:225], v[38:39], v[220:221], v[224:225]
	v_cvt_pk_f32_fp8_e32 v[218:219], v167
	v_cvt_pk_f32_fp8_sdwa v[220:221], v167 src0_sel:WORD_1
	v_pk_fma_f32 v[222:223], v[40:41], v[214:215], v[222:223]
	v_pk_fma_f32 v[224:225], v[42:43], v[216:217], v[224:225]
	v_pk_fma_f32 v[222:223], v[44:45], v[218:219], v[222:223]
	v_pk_fma_f32 v[224:225], v[46:47], v[220:221], v[224:225]
	v_pk_add_f32 v[222:223], v[222:223], v[224:225]
	s_nop 0
	v_add_f32_e32 v231, v222, v223
	v_cvt_pk_f32_fp8_e32 v[214:215], v168
	v_cvt_pk_f32_fp8_sdwa v[216:217], v168 src0_sel:WORD_1
	v_cvt_pk_f32_fp8_e32 v[218:219], v169
	v_cvt_pk_f32_fp8_sdwa v[220:221], v169 src0_sel:WORD_1
	v_pk_mul_f32 v[222:223], v[32:33], v[214:215]
	v_pk_mul_f32 v[224:225], v[34:35], v[216:217]
	v_cvt_pk_f32_fp8_e32 v[214:215], v170
	v_cvt_pk_f32_fp8_sdwa v[216:217], v170 src0_sel:WORD_1
	v_pk_fma_f32 v[222:223], v[36:37], v[218:219], v[222:223]
	v_pk_fma_f32 v[224:225], v[38:39], v[220:221], v[224:225]
	v_cvt_pk_f32_fp8_e32 v[218:219], v171
	v_cvt_pk_f32_fp8_sdwa v[220:221], v171 src0_sel:WORD_1
	v_pk_fma_f32 v[222:223], v[40:41], v[214:215], v[222:223]
	v_pk_fma_f32 v[224:225], v[42:43], v[216:217], v[224:225]
	v_pk_fma_f32 v[222:223], v[44:45], v[218:219], v[222:223]
	v_pk_fma_f32 v[224:225], v[46:47], v[220:221], v[224:225]
	v_pk_add_f32 v[222:223], v[222:223], v[224:225]
	s_nop 0
	v_add_f32_e32 v232, v222, v223
	v_cvt_pk_f32_fp8_e32 v[214:215], v172
	v_cvt_pk_f32_fp8_sdwa v[216:217], v172 src0_sel:WORD_1
	v_cvt_pk_f32_fp8_e32 v[218:219], v173
	v_cvt_pk_f32_fp8_sdwa v[220:221], v173 src0_sel:WORD_1
	v_pk_mul_f32 v[222:223], v[32:33], v[214:215]
	v_pk_mul_f32 v[224:225], v[34:35], v[216:217]
	v_cvt_pk_f32_fp8_e32 v[214:215], v174
	v_cvt_pk_f32_fp8_sdwa v[216:217], v174 src0_sel:WORD_1
	v_pk_fma_f32 v[222:223], v[36:37], v[218:219], v[222:223]
	v_pk_fma_f32 v[224:225], v[38:39], v[220:221], v[224:225]
	v_cvt_pk_f32_fp8_e32 v[218:219], v175
	v_cvt_pk_f32_fp8_sdwa v[220:221], v175 src0_sel:WORD_1
	v_pk_fma_f32 v[222:223], v[40:41], v[214:215], v[222:223]
	v_pk_fma_f32 v[224:225], v[42:43], v[216:217], v[224:225]
	v_pk_fma_f32 v[222:223], v[44:45], v[218:219], v[222:223]
	v_pk_fma_f32 v[224:225], v[46:47], v[220:221], v[224:225]
	v_pk_add_f32 v[222:223], v[222:223], v[224:225]
	s_nop 0
	v_add_f32_e32 v233, v222, v223
	v_permlane32_swap_b32_e32 v226, v230
	v_permlane32_swap_b32_e32 v227, v231
	v_permlane32_swap_b32_e32 v228, v232
	v_permlane32_swap_b32_e32 v229, v233
	v_add_f32_e32 v226, v226, v230
	v_add_f32_e32 v228, v228, v232
	v_add_f32_e32 v227, v227, v231
	v_add_f32_e32 v229, v229, v233
	s_nop 1
	v_permlane16_swap_b32_e32 v226, v228
; template <bool STORE>
; DI void peer_item(const Params& p, int item, char* smem) {
;     ...
;       float part[8];
; #pragma unroll
;       for (int u = 0; u < 8; ++u) {
;         float d = 0.f;
; #pragma unroll
;         for (int i = 0; i < 4; ++i) {
;           f32x2_t lo = __builtin_amdgcn_cvt_pk_f32_fp8((int)uq[u][i], false);
;           f32x2_t hi = __builtin_amdgcn_cvt_pk_f32_fp8((int)uq[u][i], true);
;           d += xf[4 * i] * lo.x + xf[4 * i + 1] * lo.y + xf[4 * i + 2] * hi.x + xf[4 * i + 3] * hi.y;
;         }
;         part[u] = d;
;       }
;       float q4[4], r2[2], h;
; #pragma unroll
;       for (int j = 0; j < 4; ++j) {
;         float mine = b5 ? part[j + 4] : part[j];
;         float other = b5 ? part[j] : part[j + 4];
;         q4[j] = mine + __shfl_xor(other, 32);
;       }
; #pragma unroll
;       for (int j = 0; j < 2; ++j) {
;         float mine = b4 ? q4[j + 2] : q4[j];
;         float other = b4 ? q4[j] : q4[j + 2];
;         r2[j] = mine + __shfl_xor(other, 16);
;       }
;       {
;         float mine = b3 ? r2[1] : r2[0];
;         float other = b3 ? r2[0] : r2[1];
;         h = mine + __shfl_xor(other, 8);
;       }
;       h += __shfl_xor(h, 4);
;       h += __shfl_xor(h, 2);
;       h += __shfl_xor(h, 1);
	v_permlane16_swap_b32_e32 v227, v229
	v_add_f32_e32 v226, v226, v228
	v_add_f32_e32 v227, v227, v229
	s_nop 0
	v_cndmask_b32_e64 v230, v226, v227, s[24:25]
	v_cndmask_b32_e64 v231, v227, v226, s[24:25]
	s_nop 1
	v_add_f32_dpp v232, v231, v230 row_ror:8 row_mask:0xf bank_mask:0xf
	s_nop 1
	v_add_f32_dpp v233, v232, v232 quad_perm:[1,0,3,2] row_mask:0xf bank_mask:0xf
	s_nop 1
	v_add_f32_dpp v232, v233, v233 quad_perm:[2,3,0,1] row_mask:0xf bank_mask:0xf
	s_nop 1
	v_add_f32_dpp v233, v232, v232 row_half_mirror row_mask:0xf bank_mask:0xf
	ds_write_b32 v235, v233 offset:33792
	v_readlane_b32 s48, v136, s72
	v_readlane_b32 s49, v136, s73
	v_readlane_b32 s50, v136, s74
	v_readlane_b32 s51, v136, s75
	v_readlane_b32 s52, v136, s76
	v_readlane_b32 s53, v136, s77
	v_readlane_b32 s54, v136, s78
	v_readlane_b32 s55, v136, s79
	s_add_u32 s32, s0, s48
	s_addc_u32 s33, s1, 0
	s_add_u32 s34, s0, s49
	s_addc_u32 s35, s1, 0
	s_add_u32 s36, s0, s50
	s_addc_u32 s37, s1, 0
	s_add_u32 s38, s0, s51
	s_addc_u32 s39, s1, 0
	s_add_u32 s40, s0, s52
	s_addc_u32 s41, s1, 0
	s_add_u32 s42, s0, s53
	s_addc_u32 s43, s1, 0
	s_add_u32 s44, s0, s54
	s_addc_u32 s45, s1, 0
	s_add_u32 s46, s0, s55
	s_addc_u32 s47, s1, 0
	global_load_dwordx4 v[144:147], v234, s[32:33]
	global_load_dwordx4 v[148:151], v234, s[34:35]
	global_load_dwordx4 v[152:155], v234, s[36:37]
	global_load_dwordx4 v[156:159], v234, s[38:39]
	global_load_dwordx4 v[160:163], v234, s[40:41]
	global_load_dwordx4 v[164:167], v234, s[42:43]
	global_load_dwordx4 v[168:171], v234, s[44:45]
	global_load_dwordx4 v[172:175], v234, s[46:47]
	s_waitcnt vmcnt(8)
	v_cvt_pk_f32_fp8_e32 v[214:215], v176
	v_cvt_pk_f32_fp8_sdwa v[216:217], v176 src0_sel:WORD_1
	v_cvt_pk_f32_fp8_e32 v[218:219], v177
	v_cvt_pk_f32_fp8_sdwa v[220:221], v177 src0_sel:WORD_1
	v_pk_mul_f32 v[222:223], v[48:49], v[214:215]
	v_pk_mul_f32 v[224:225], v[50:51], v[216:217]
	v_cvt_pk_f32_fp8_e32 v[214:215], v178
	v_cvt_pk_f32_fp8_sdwa v[216:217], v178 src0_sel:WORD_1
	v_pk_fma_f32 v[222:223], v[52:53], v[218:219], v[222:223]
	v_pk_fma_f32 v[224:225], v[54:55], v[220:221], v[224:225]
	v_cvt_pk_f32_fp8_e32 v[218:219], v179
	v_cvt_pk_f32_fp8_sdwa v[220:221], v179 src0_sel:WORD_1
	v_pk_fma_f32 v[222:223], v[56:57], v[214:215], v[222:223]
	v_pk_fma_f32 v[224:225], v[58:59], v[216:217], v[224:225]
	v_pk_fma_f32 v[222:223], v[60:61], v[218:219], v[222:223]
	v_pk_fma_f32 v[224:225], v[62:63], v[220:221], v[224:225]
	v_pk_add_f32 v[222:223], v[222:223], v[224:225]
	s_nop 0
	v_add_f32_e32 v226, v222, v223
	v_cvt_pk_f32_fp8_e32 v[214:215], v180
	v_cvt_pk_f32_fp8_sdwa v[216:217], v180 src0_sel:WORD_1
	v_cvt_pk_f32_fp8_e32 v[218:219], v181
	v_cvt_pk_f32_fp8_sdwa v[220:221], v181 src0_sel:WORD_1
	v_pk_mul_f32 v[222:223], v[48:49], v[214:215]
	v_pk_mul_f32 v[224:225], v[50:51], v[216:217]
	v_cvt_pk_f32_fp8_e32 v[214:215], v182
	v_cvt_pk_f32_fp8_sdwa v[216:217], v182 src0_sel:WORD_1
	v_pk_fma_f32 v[222:223], v[52:53], v[218:219], v[222:223]
	v_pk_fma_f32 v[224:225], v[54:55], v[220:221], v[224:225]
	v_cvt_pk_f32_fp8_e32 v[218:219], v183
	v_cvt_pk_f32_fp8_sdwa v[220:221], v183 src0_sel:WORD_1
	v_pk_fma_f32 v[222:223], v[56:57], v[214:215], v[222:223]
	v_pk_fma_f32 v[224:225], v[58:59], v[216:217], v[224:225]
	v_pk_fma_f32 v[222:223], v[60:61], v[218:219], v[222:223]
	v_pk_fma_f32 v[224:225], v[62:63], v[220:221], v[224:225]
	v_pk_add_f32 v[222:223], v[222:223], v[224:225]
	s_nop 0
	v_add_f32_e32 v227, v222, v223
	v_cvt_pk_f32_fp8_e32 v[214:215], v184
	v_cvt_pk_f32_fp8_sdwa v[216:217], v184 src0_sel:WORD_1
	v_cvt_pk_f32_fp8_e32 v[218:219], v185
	v_cvt_pk_f32_fp8_sdwa v[220:221], v185 src0_sel:WORD_1
	v_pk_mul_f32 v[222:223], v[48:49], v[214:215]
	v_pk_mul_f32 v[224:225], v[50:51], v[216:217]
	v_cvt_pk_f32_fp8_e32 v[214:215], v186
	v_cvt_pk_f32_fp8_sdwa v[216:217], v186 src0_sel:WORD_1
	v_pk_fma_f32 v[222:223], v[52:53], v[218:219], v[222:223]
	v_pk_fma_f32 v[224:225], v[54:55], v[220:221], v[224:225]
	v_cvt_pk_f32_fp8_e32 v[218:219], v187
	v_cvt_pk_f32_fp8_sdwa v[220:221], v187 src0_sel:WORD_1
	v_pk_fma_f32 v[222:223], v[56:57], v[214:215], v[222:223]
	v_pk_fma_f32 v[224:225], v[58:59], v[216:217], v[224:225]
	v_pk_fma_f32 v[222:223], v[60:61], v[218:219], v[222:223]
	v_pk_fma_f32 v[224:225], v[62:63], v[220:221], v[224:225]
	v_pk_add_f32 v[222:223], v[222:223], v[224:225]
	s_nop 0
	v_add_f32_e32 v228, v222, v223
	v_cvt_pk_f32_fp8_e32 v[214:215], v188
	v_cvt_pk_f32_fp8_sdwa v[216:217], v188 src0_sel:WORD_1
	v_cvt_pk_f32_fp8_e32 v[218:219], v189
	v_cvt_pk_f32_fp8_sdwa v[220:221], v189 src0_sel:WORD_1
	v_pk_mul_f32 v[222:223], v[48:49], v[214:215]
	v_pk_mul_f32 v[224:225], v[50:51], v[216:217]
	v_cvt_pk_f32_fp8_e32 v[214:215], v190
	v_cvt_pk_f32_fp8_sdwa v[216:217], v190 src0_sel:WORD_1
	v_pk_fma_f32 v[222:223], v[52:53], v[218:219], v[222:223]
	v_pk_fma_f32 v[224:225], v[54:55], v[220:221], v[224:225]
	v_cvt_pk_f32_fp8_e32 v[218:219], v191
	v_cvt_pk_f32_fp8_sdwa v[220:221], v191 src0_sel:WORD_1
	v_pk_fma_f32 v[222:223], v[56:57], v[214:215], v[222:223]
	v_pk_fma_f32 v[224:225], v[58:59], v[216:217], v[224:225]
	v_pk_fma_f32 v[222:223], v[60:61], v[218:219], v[222:223]
	v_pk_fma_f32 v[224:225], v[62:63], v[220:221], v[224:225]
	v_pk_add_f32 v[222:223], v[222:223], v[224:225]
	s_nop 0
	v_add_f32_e32 v229, v222, v223
	v_cvt_pk_f32_fp8_e32 v[214:215], v192
	v_cvt_pk_f32_fp8_sdwa v[216:217], v192 src0_sel:WORD_1
	v_cvt_pk_f32_fp8_e32 v[218:219], v193
	v_cvt_pk_f32_fp8_sdwa v[220:221], v193 src0_sel:WORD_1
	v_pk_mul_f32 v[222:223], v[48:49], v[214:215]
	v_pk_mul_f32 v[224:225], v[50:51], v[216:217]
	v_cvt_pk_f32_fp8_e32 v[214:215], v194
	v_cvt_pk_f32_fp8_sdwa v[216:217], v194 src0_sel:WORD_1
; template <bool STORE>
; DI void peer_item(const Params& p, int item, char* smem) {
;     ...
;       float part[8];
; #pragma unroll
;       for (int u = 0; u < 8; ++u) {
;         float d = 0.f;
; #pragma unroll
;         for (int i = 0; i < 4; ++i) {
;           f32x2_t lo = __builtin_amdgcn_cvt_pk_f32_fp8((int)uq[u][i], false);
;           f32x2_t hi = __builtin_amdgcn_cvt_pk_f32_fp8((int)uq[u][i], true);
;           d += xf[4 * i] * lo.x + xf[4 * i + 1] * lo.y + xf[4 * i + 2] * hi.x + xf[4 * i + 3] * hi.y;
;         }
;         part[u] = d;
;       }
;       float q4[4], r2[2], h;
; #pragma unroll
;       for (int j = 0; j < 4; ++j) {
;         float mine = b5 ? part[j + 4] : part[j];
;         float other = b5 ? part[j] : part[j + 4];
;         q4[j] = mine + __shfl_xor(other, 32);
;       }
; #pragma unroll
;       for (int j = 0; j < 2; ++j) {
;         float mine = b4 ? q4[j + 2] : q4[j];
;         float other = b4 ? q4[j] : q4[j + 2];
;         r2[j] = mine + __shfl_xor(other, 16);
;       }
;       {
;         float mine = b3 ? r2[1] : r2[0];
;         float other = b3 ? r2[0] : r2[1];
;         h = mine + __shfl_xor(other, 8);
;       }
;       h += __shfl_xor(h, 4);
;       h += __shfl_xor(h, 2);
;       h += __shfl_xor(h, 1);
	v_pk_fma_f32 v[222:223], v[52:53], v[218:219], v[222:223]
	v_pk_fma_f32 v[224:225], v[54:55], v[220:221], v[224:225]
	v_cvt_pk_f32_fp8_e32 v[218:219], v195
	v_cvt_pk_f32_fp8_sdwa v[220:221], v195 src0_sel:WORD_1
	v_pk_fma_f32 v[222:223], v[56:57], v[214:215], v[222:223]
	v_pk_fma_f32 v[224:225], v[58:59], v[216:217], v[224:225]
	v_pk_fma_f32 v[222:223], v[60:61], v[218:219], v[222:223]
	v_pk_fma_f32 v[224:225], v[62:63], v[220:221], v[224:225]
	v_pk_add_f32 v[222:223], v[222:223], v[224:225]
	s_nop 0
	v_add_f32_e32 v230, v222, v223
	v_cvt_pk_f32_fp8_e32 v[214:215], v196
	v_cvt_pk_f32_fp8_sdwa v[216:217], v196 src0_sel:WORD_1
	v_cvt_pk_f32_fp8_e32 v[218:219], v197
	v_cvt_pk_f32_fp8_sdwa v[220:221], v197 src0_sel:WORD_1
	v_pk_mul_f32 v[222:223], v[48:49], v[214:215]
	v_pk_mul_f32 v[224:225], v[50:51], v[216:217]
	v_cvt_pk_f32_fp8_e32 v[214:215], v198
	v_cvt_pk_f32_fp8_sdwa v[216:217], v198 src0_sel:WORD_1
	v_pk_fma_f32 v[222:223], v[52:53], v[218:219], v[222:223]
	v_pk_fma_f32 v[224:225], v[54:55], v[220:221], v[224:225]
	v_cvt_pk_f32_fp8_e32 v[218:219], v199
	v_cvt_pk_f32_fp8_sdwa v[220:221], v199 src0_sel:WORD_1
	v_pk_fma_f32 v[222:223], v[56:57], v[214:215], v[222:223]
	v_pk_fma_f32 v[224:225], v[58:59], v[216:217], v[224:225]
	v_pk_fma_f32 v[222:223], v[60:61], v[218:219], v[222:223]
	v_pk_fma_f32 v[224:225], v[62:63], v[220:221], v[224:225]
	v_pk_add_f32 v[222:223], v[222:223], v[224:225]
	s_nop 0
	v_add_f32_e32 v231, v222, v223
	v_cvt_pk_f32_fp8_e32 v[214:215], v200
	v_cvt_pk_f32_fp8_sdwa v[216:217], v200 src0_sel:WORD_1
	v_cvt_pk_f32_fp8_e32 v[218:219], v201
	v_cvt_pk_f32_fp8_sdwa v[220:221], v201 src0_sel:WORD_1
	v_pk_mul_f32 v[222:223], v[48:49], v[214:215]
	v_pk_mul_f32 v[224:225], v[50:51], v[216:217]
	v_cvt_pk_f32_fp8_e32 v[214:215], v202
	v_cvt_pk_f32_fp8_sdwa v[216:217], v202 src0_sel:WORD_1
	v_pk_fma_f32 v[222:223], v[52:53], v[218:219], v[222:223]
	v_pk_fma_f32 v[224:225], v[54:55], v[220:221], v[224:225]
	v_cvt_pk_f32_fp8_e32 v[218:219], v203
	v_cvt_pk_f32_fp8_sdwa v[220:221], v203 src0_sel:WORD_1
	v_pk_fma_f32 v[222:223], v[56:57], v[214:215], v[222:223]
	v_pk_fma_f32 v[224:225], v[58:59], v[216:217], v[224:225]
	v_pk_fma_f32 v[222:223], v[60:61], v[218:219], v[222:223]
	v_pk_fma_f32 v[224:225], v[62:63], v[220:221], v[224:225]
	v_pk_add_f32 v[222:223], v[222:223], v[224:225]
	s_nop 0
	v_add_f32_e32 v232, v222, v223
	v_cvt_pk_f32_fp8_e32 v[214:215], v204
	v_cvt_pk_f32_fp8_sdwa v[216:217], v204 src0_sel:WORD_1
	v_cvt_pk_f32_fp8_e32 v[218:219], v205
	v_cvt_pk_f32_fp8_sdwa v[220:221], v205 src0_sel:WORD_1
	v_pk_mul_f32 v[222:223], v[48:49], v[214:215]
	v_pk_mul_f32 v[224:225], v[50:51], v[216:217]
	v_cvt_pk_f32_fp8_e32 v[214:215], v206
	v_cvt_pk_f32_fp8_sdwa v[216:217], v206 src0_sel:WORD_1
	v_pk_fma_f32 v[222:223], v[52:53], v[218:219], v[222:223]
	v_pk_fma_f32 v[224:225], v[54:55], v[220:221], v[224:225]
	v_cvt_pk_f32_fp8_e32 v[218:219], v207
	v_cvt_pk_f32_fp8_sdwa v[220:221], v207 src0_sel:WORD_1
	v_pk_fma_f32 v[222:223], v[56:57], v[214:215], v[222:223]
	v_pk_fma_f32 v[224:225], v[58:59], v[216:217], v[224:225]
	v_pk_fma_f32 v[222:223], v[60:61], v[218:219], v[222:223]
	v_pk_fma_f32 v[224:225], v[62:63], v[220:221], v[224:225]
	v_pk_add_f32 v[222:223], v[222:223], v[224:225]
	s_nop 0
	v_add_f32_e32 v233, v222, v223
	v_permlane32_swap_b32_e32 v226, v230
	v_permlane32_swap_b32_e32 v227, v231
	v_permlane32_swap_b32_e32 v228, v232
	v_permlane32_swap_b32_e32 v229, v233
	v_add_f32_e32 v226, v226, v230
	v_add_f32_e32 v228, v228, v232
	v_add_f32_e32 v227, v227, v231
	v_add_f32_e32 v229, v229, v233
	s_nop 1
	v_permlane16_swap_b32_e32 v226, v228
	v_permlane16_swap_b32_e32 v227, v229
	v_add_f32_e32 v226, v226, v228
	v_add_f32_e32 v227, v227, v229
	s_nop 0
	v_cndmask_b32_e64 v230, v226, v227, s[24:25]
	v_cndmask_b32_e64 v231, v227, v226, s[24:25]
	s_nop 1
	v_add_f32_dpp v232, v231, v230 row_ror:8 row_mask:0xf bank_mask:0xf
	s_nop 1
	v_add_f32_dpp v233, v232, v232 quad_perm:[1,0,3,2] row_mask:0xf bank_mask:0xf
	s_nop 1
	v_add_f32_dpp v232, v233, v233 quad_perm:[2,3,0,1] row_mask:0xf bank_mask:0xf
	s_nop 1
	v_add_f32_dpp v233, v232, v232 row_half_mirror row_mask:0xf bank_mask:0xf
	ds_write_b32 v235, v233 offset:34304
	v_readlane_b32 s48, v138, s72
	v_readlane_b32 s49, v138, s73
	v_readlane_b32 s50, v138, s74
	v_readlane_b32 s51, v138, s75
	v_readlane_b32 s52, v138, s76
	v_readlane_b32 s53, v138, s77
	v_readlane_b32 s54, v138, s78
	v_readlane_b32 s55, v138, s79
	s_add_u32 s32, s0, s48
	s_addc_u32 s33, s1, 0
	s_add_u32 s34, s0, s49
	s_addc_u32 s35, s1, 0
	s_add_u32 s36, s0, s50
	s_addc_u32 s37, s1, 0
	s_add_u32 s38, s0, s51
	s_addc_u32 s39, s1, 0
	s_add_u32 s40, s0, s52
	s_addc_u32 s41, s1, 0
	s_add_u32 s42, s0, s53
	s_addc_u32 s43, s1, 0
	s_add_u32 s44, s0, s54
	s_addc_u32 s45, s1, 0
	s_add_u32 s46, s0, s55
	s_addc_u32 s47, s1, 0
	global_load_dwordx4 v[176:179], v234, s[32:33]
	global_load_dwordx4 v[180:183], v234, s[34:35]
	global_load_dwordx4 v[184:187], v234, s[36:37]
	global_load_dwordx4 v[188:191], v234, s[38:39]
	global_load_dwordx4 v[192:195], v234, s[40:41]
	global_load_dwordx4 v[196:199], v234, s[42:43]
	global_load_dwordx4 v[200:203], v234, s[44:45]
	global_load_dwordx4 v[204:207], v234, s[46:47]
	s_waitcnt vmcnt(8)
; template <bool STORE>
; DI void peer_item(const Params& p, int item, char* smem) {
;     ...
;       float part[8];
; #pragma unroll
;       for (int u = 0; u < 8; ++u) {
;         float d = 0.f;
; #pragma unroll
;         for (int i = 0; i < 4; ++i) {
;           f32x2_t lo = __builtin_amdgcn_cvt_pk_f32_fp8((int)uq[u][i], false);
;           f32x2_t hi = __builtin_amdgcn_cvt_pk_f32_fp8((int)uq[u][i], true);
;           d += xf[4 * i] * lo.x + xf[4 * i + 1] * lo.y + xf[4 * i + 2] * hi.x + xf[4 * i + 3] * hi.y;
;         }
;         part[u] = d;
;       }
	v_cvt_pk_f32_fp8_e32 v[214:215], v144
	v_cvt_pk_f32_fp8_sdwa v[216:217], v144 src0_sel:WORD_1
	v_cvt_pk_f32_fp8_e32 v[218:219], v145
	v_cvt_pk_f32_fp8_sdwa v[220:221], v145 src0_sel:WORD_1
	v_pk_mul_f32 v[222:223], v[64:65], v[214:215]
	v_pk_mul_f32 v[224:225], v[66:67], v[216:217]
	v_cvt_pk_f32_fp8_e32 v[214:215], v146
	v_cvt_pk_f32_fp8_sdwa v[216:217], v146 src0_sel:WORD_1
	v_pk_fma_f32 v[222:223], v[68:69], v[218:219], v[222:223]
	v_pk_fma_f32 v[224:225], v[70:71], v[220:221], v[224:225]
	v_cvt_pk_f32_fp8_e32 v[218:219], v147
	v_cvt_pk_f32_fp8_sdwa v[220:221], v147 src0_sel:WORD_1
	v_pk_fma_f32 v[222:223], v[72:73], v[214:215], v[222:223]
	v_pk_fma_f32 v[224:225], v[74:75], v[216:217], v[224:225]
	v_pk_fma_f32 v[222:223], v[76:77], v[218:219], v[222:223]
	v_pk_fma_f32 v[224:225], v[78:79], v[220:221], v[224:225]
	v_pk_add_f32 v[222:223], v[222:223], v[224:225]
	s_nop 0
	v_add_f32_e32 v226, v222, v223
	v_cvt_pk_f32_fp8_e32 v[214:215], v148
	v_cvt_pk_f32_fp8_sdwa v[216:217], v148 src0_sel:WORD_1
	v_cvt_pk_f32_fp8_e32 v[218:219], v149
	v_cvt_pk_f32_fp8_sdwa v[220:221], v149 src0_sel:WORD_1
	v_pk_mul_f32 v[222:223], v[64:65], v[214:215]
	v_pk_mul_f32 v[224:225], v[66:67], v[216:217]
	v_cvt_pk_f32_fp8_e32 v[214:215], v150
	v_cvt_pk_f32_fp8_sdwa v[216:217], v150 src0_sel:WORD_1
	v_pk_fma_f32 v[222:223], v[68:69], v[218:219], v[222:223]
	v_pk_fma_f32 v[224:225], v[70:71], v[220:221], v[224:225]
	v_cvt_pk_f32_fp8_e32 v[218:219], v151
	v_cvt_pk_f32_fp8_sdwa v[220:221], v151 src0_sel:WORD_1
	v_pk_fma_f32 v[222:223], v[72:73], v[214:215], v[222:223]
	v_pk_fma_f32 v[224:225], v[74:75], v[216:217], v[224:225]
	v_pk_fma_f32 v[222:223], v[76:77], v[218:219], v[222:223]
	v_pk_fma_f32 v[224:225], v[78:79], v[220:221], v[224:225]
	v_pk_add_f32 v[222:223], v[222:223], v[224:225]
	s_nop 0
	v_add_f32_e32 v227, v222, v223
	v_cvt_pk_f32_fp8_e32 v[214:215], v152
	v_cvt_pk_f32_fp8_sdwa v[216:217], v152 src0_sel:WORD_1
	v_cvt_pk_f32_fp8_e32 v[218:219], v153
	v_cvt_pk_f32_fp8_sdwa v[220:221], v153 src0_sel:WORD_1
	v_pk_mul_f32 v[222:223], v[64:65], v[214:215]
	v_pk_mul_f32 v[224:225], v[66:67], v[216:217]
	v_cvt_pk_f32_fp8_e32 v[214:215], v154
	v_cvt_pk_f32_fp8_sdwa v[216:217], v154 src0_sel:WORD_1
	v_pk_fma_f32 v[222:223], v[68:69], v[218:219], v[222:223]
	v_pk_fma_f32 v[224:225], v[70:71], v[220:221], v[224:225]
	v_cvt_pk_f32_fp8_e32 v[218:219], v155
	v_cvt_pk_f32_fp8_sdwa v[220:221], v155 src0_sel:WORD_1
	v_pk_fma_f32 v[222:223], v[72:73], v[214:215], v[222:223]
	v_pk_fma_f32 v[224:225], v[74:75], v[216:217], v[224:225]
	v_pk_fma_f32 v[222:223], v[76:77], v[218:219], v[222:223]
	v_pk_fma_f32 v[224:225], v[78:79], v[220:221], v[224:225]
	v_pk_add_f32 v[222:223], v[222:223], v[224:225]
	s_nop 0
	v_add_f32_e32 v228, v222, v223
	v_cvt_pk_f32_fp8_e32 v[214:215], v156
	v_cvt_pk_f32_fp8_sdwa v[216:217], v156 src0_sel:WORD_1
	v_cvt_pk_f32_fp8_e32 v[218:219], v157
	v_cvt_pk_f32_fp8_sdwa v[220:221], v157 src0_sel:WORD_1
	v_pk_mul_f32 v[222:223], v[64:65], v[214:215]
	v_pk_mul_f32 v[224:225], v[66:67], v[216:217]
	v_cvt_pk_f32_fp8_e32 v[214:215], v158
	v_cvt_pk_f32_fp8_sdwa v[216:217], v158 src0_sel:WORD_1
	v_pk_fma_f32 v[222:223], v[68:69], v[218:219], v[222:223]
	v_pk_fma_f32 v[224:225], v[70:71], v[220:221], v[224:225]
	v_cvt_pk_f32_fp8_e32 v[218:219], v159
	v_cvt_pk_f32_fp8_sdwa v[220:221], v159 src0_sel:WORD_1
	v_pk_fma_f32 v[222:223], v[72:73], v[214:215], v[222:223]
	v_pk_fma_f32 v[224:225], v[74:75], v[216:217], v[224:225]
	v_pk_fma_f32 v[222:223], v[76:77], v[218:219], v[222:223]
	v_pk_fma_f32 v[224:225], v[78:79], v[220:221], v[224:225]
	v_pk_add_f32 v[222:223], v[222:223], v[224:225]
	s_nop 0
	v_add_f32_e32 v229, v222, v223
	v_cvt_pk_f32_fp8_e32 v[214:215], v160
	v_cvt_pk_f32_fp8_sdwa v[216:217], v160 src0_sel:WORD_1
	v_cvt_pk_f32_fp8_e32 v[218:219], v161
	v_cvt_pk_f32_fp8_sdwa v[220:221], v161 src0_sel:WORD_1
	v_pk_mul_f32 v[222:223], v[64:65], v[214:215]
	v_pk_mul_f32 v[224:225], v[66:67], v[216:217]
	v_cvt_pk_f32_fp8_e32 v[214:215], v162
	v_cvt_pk_f32_fp8_sdwa v[216:217], v162 src0_sel:WORD_1
	v_pk_fma_f32 v[222:223], v[68:69], v[218:219], v[222:223]
	v_pk_fma_f32 v[224:225], v[70:71], v[220:221], v[224:225]
	v_cvt_pk_f32_fp8_e32 v[218:219], v163
	v_cvt_pk_f32_fp8_sdwa v[220:221], v163 src0_sel:WORD_1
	v_pk_fma_f32 v[222:223], v[72:73], v[214:215], v[222:223]
	v_pk_fma_f32 v[224:225], v[74:75], v[216:217], v[224:225]
	v_pk_fma_f32 v[222:223], v[76:77], v[218:219], v[222:223]
	v_pk_fma_f32 v[224:225], v[78:79], v[220:221], v[224:225]
	v_pk_add_f32 v[222:223], v[222:223], v[224:225]
	s_nop 0
	v_add_f32_e32 v230, v222, v223
	v_cvt_pk_f32_fp8_e32 v[214:215], v164
	v_cvt_pk_f32_fp8_sdwa v[216:217], v164 src0_sel:WORD_1
	v_cvt_pk_f32_fp8_e32 v[218:219], v165
	v_cvt_pk_f32_fp8_sdwa v[220:221], v165 src0_sel:WORD_1
	v_pk_mul_f32 v[222:223], v[64:65], v[214:215]
	v_pk_mul_f32 v[224:225], v[66:67], v[216:217]
	v_cvt_pk_f32_fp8_e32 v[214:215], v166
	v_cvt_pk_f32_fp8_sdwa v[216:217], v166 src0_sel:WORD_1
	v_pk_fma_f32 v[222:223], v[68:69], v[218:219], v[222:223]
	v_pk_fma_f32 v[224:225], v[70:71], v[220:221], v[224:225]
	v_cvt_pk_f32_fp8_e32 v[218:219], v167
	v_cvt_pk_f32_fp8_sdwa v[220:221], v167 src0_sel:WORD_1
	v_pk_fma_f32 v[222:223], v[72:73], v[214:215], v[222:223]
	v_pk_fma_f32 v[224:225], v[74:75], v[216:217], v[224:225]
	v_pk_fma_f32 v[222:223], v[76:77], v[218:219], v[222:223]
	v_pk_fma_f32 v[224:225], v[78:79], v[220:221], v[224:225]
	v_pk_add_f32 v[222:223], v[222:223], v[224:225]
	s_nop 0
	v_add_f32_e32 v231, v222, v223
	v_cvt_pk_f32_fp8_e32 v[214:215], v168
	v_cvt_pk_f32_fp8_sdwa v[216:217], v168 src0_sel:WORD_1
	v_cvt_pk_f32_fp8_e32 v[218:219], v169
; template <bool STORE>
; DI void peer_item(const Params& p, int item, char* smem) {
;     ...
;       float part[8];
; #pragma unroll
;       for (int u = 0; u < 8; ++u) {
;         float d = 0.f;
; #pragma unroll
;         for (int i = 0; i < 4; ++i) {
;           f32x2_t lo = __builtin_amdgcn_cvt_pk_f32_fp8((int)uq[u][i], false);
;           f32x2_t hi = __builtin_amdgcn_cvt_pk_f32_fp8((int)uq[u][i], true);
;           d += xf[4 * i] * lo.x + xf[4 * i + 1] * lo.y + xf[4 * i + 2] * hi.x + xf[4 * i + 3] * hi.y;
;         }
;         part[u] = d;
;       }
;       float q4[4], r2[2], h;
; #pragma unroll
;       for (int j = 0; j < 4; ++j) {
;         float mine = b5 ? part[j + 4] : part[j];
;         float other = b5 ? part[j] : part[j + 4];
;         q4[j] = mine + __shfl_xor(other, 32);
;       }
; #pragma unroll
;       for (int j = 0; j < 2; ++j) {
;         float mine = b4 ? q4[j + 2] : q4[j];
;         float other = b4 ? q4[j] : q4[j + 2];
;         r2[j] = mine + __shfl_xor(other, 16);
;       }
;       {
;         float mine = b3 ? r2[1] : r2[0];
;         float other = b3 ? r2[0] : r2[1];
;         h = mine + __shfl_xor(other, 8);
;       }
;       h += __shfl_xor(h, 4);
;       h += __shfl_xor(h, 2);
;       h += __shfl_xor(h, 1);
	v_cvt_pk_f32_fp8_sdwa v[220:221], v169 src0_sel:WORD_1
	v_pk_mul_f32 v[222:223], v[64:65], v[214:215]
	v_pk_mul_f32 v[224:225], v[66:67], v[216:217]
	v_cvt_pk_f32_fp8_e32 v[214:215], v170
	v_cvt_pk_f32_fp8_sdwa v[216:217], v170 src0_sel:WORD_1
	v_pk_fma_f32 v[222:223], v[68:69], v[218:219], v[222:223]
	v_pk_fma_f32 v[224:225], v[70:71], v[220:221], v[224:225]
	v_cvt_pk_f32_fp8_e32 v[218:219], v171
	v_cvt_pk_f32_fp8_sdwa v[220:221], v171 src0_sel:WORD_1
	v_pk_fma_f32 v[222:223], v[72:73], v[214:215], v[222:223]
	v_pk_fma_f32 v[224:225], v[74:75], v[216:217], v[224:225]
	v_pk_fma_f32 v[222:223], v[76:77], v[218:219], v[222:223]
	v_pk_fma_f32 v[224:225], v[78:79], v[220:221], v[224:225]
	v_pk_add_f32 v[222:223], v[222:223], v[224:225]
	s_nop 0
	v_add_f32_e32 v232, v222, v223
	v_cvt_pk_f32_fp8_e32 v[214:215], v172
	v_cvt_pk_f32_fp8_sdwa v[216:217], v172 src0_sel:WORD_1
	v_cvt_pk_f32_fp8_e32 v[218:219], v173
	v_cvt_pk_f32_fp8_sdwa v[220:221], v173 src0_sel:WORD_1
	v_pk_mul_f32 v[222:223], v[64:65], v[214:215]
	v_pk_mul_f32 v[224:225], v[66:67], v[216:217]
	v_cvt_pk_f32_fp8_e32 v[214:215], v174
	v_cvt_pk_f32_fp8_sdwa v[216:217], v174 src0_sel:WORD_1
	v_pk_fma_f32 v[222:223], v[68:69], v[218:219], v[222:223]
	v_pk_fma_f32 v[224:225], v[70:71], v[220:221], v[224:225]
	v_cvt_pk_f32_fp8_e32 v[218:219], v175
	v_cvt_pk_f32_fp8_sdwa v[220:221], v175 src0_sel:WORD_1
	v_pk_fma_f32 v[222:223], v[72:73], v[214:215], v[222:223]
	v_pk_fma_f32 v[224:225], v[74:75], v[216:217], v[224:225]
	v_pk_fma_f32 v[222:223], v[76:77], v[218:219], v[222:223]
	v_pk_fma_f32 v[224:225], v[78:79], v[220:221], v[224:225]
	v_pk_add_f32 v[222:223], v[222:223], v[224:225]
	s_nop 0
	v_add_f32_e32 v233, v222, v223
	v_permlane32_swap_b32_e32 v226, v230
	v_permlane32_swap_b32_e32 v227, v231
	v_permlane32_swap_b32_e32 v228, v232
	v_permlane32_swap_b32_e32 v229, v233
	v_add_f32_e32 v226, v226, v230
	v_add_f32_e32 v228, v228, v232
	v_add_f32_e32 v227, v227, v231
	v_add_f32_e32 v229, v229, v233
	s_nop 1
	v_permlane16_swap_b32_e32 v226, v228
	v_permlane16_swap_b32_e32 v227, v229
	v_add_f32_e32 v226, v226, v228
	v_add_f32_e32 v227, v227, v229
	s_nop 0
	v_cndmask_b32_e64 v230, v226, v227, s[24:25]
	v_cndmask_b32_e64 v231, v227, v226, s[24:25]
	s_nop 1
	v_add_f32_dpp v232, v231, v230 row_ror:8 row_mask:0xf bank_mask:0xf
	s_nop 1
	v_add_f32_dpp v233, v232, v232 quad_perm:[1,0,3,2] row_mask:0xf bank_mask:0xf
	s_nop 1
	v_add_f32_dpp v232, v233, v233 quad_perm:[2,3,0,1] row_mask:0xf bank_mask:0xf
	s_nop 1
	v_add_f32_dpp v233, v232, v232 row_half_mirror row_mask:0xf bank_mask:0xf
	ds_write_b32 v235, v233 offset:34816
	v_readlane_b32 s48, v140, s72
	v_readlane_b32 s49, v140, s73
	v_readlane_b32 s50, v140, s74
	v_readlane_b32 s51, v140, s75
	v_readlane_b32 s52, v140, s76
	v_readlane_b32 s53, v140, s77
	v_readlane_b32 s54, v140, s78
	v_readlane_b32 s55, v140, s79
	s_add_u32 s32, s0, s48
	s_addc_u32 s33, s1, 0
	s_add_u32 s34, s0, s49
	s_addc_u32 s35, s1, 0
	s_add_u32 s36, s0, s50
	s_addc_u32 s37, s1, 0
	s_add_u32 s38, s0, s51
	s_addc_u32 s39, s1, 0
	s_add_u32 s40, s0, s52
	s_addc_u32 s41, s1, 0
	s_add_u32 s42, s0, s53
	s_addc_u32 s43, s1, 0
	s_add_u32 s44, s0, s54
	s_addc_u32 s45, s1, 0
	s_add_u32 s46, s0, s55
	s_addc_u32 s47, s1, 0
	global_load_dwordx4 v[144:147], v234, s[32:33]
	global_load_dwordx4 v[148:151], v234, s[34:35]
	global_load_dwordx4 v[152:155], v234, s[36:37]
	global_load_dwordx4 v[156:159], v234, s[38:39]
	global_load_dwordx4 v[160:163], v234, s[40:41]
	global_load_dwordx4 v[164:167], v234, s[42:43]
	global_load_dwordx4 v[168:171], v234, s[44:45]
	global_load_dwordx4 v[172:175], v234, s[46:47]
	s_waitcnt vmcnt(8)
	v_cvt_pk_f32_fp8_e32 v[214:215], v176
	v_cvt_pk_f32_fp8_sdwa v[216:217], v176 src0_sel:WORD_1
	v_cvt_pk_f32_fp8_e32 v[218:219], v177
	v_cvt_pk_f32_fp8_sdwa v[220:221], v177 src0_sel:WORD_1
	v_pk_mul_f32 v[222:223], v[80:81], v[214:215]
	v_pk_mul_f32 v[224:225], v[82:83], v[216:217]
	v_cvt_pk_f32_fp8_e32 v[214:215], v178
	v_cvt_pk_f32_fp8_sdwa v[216:217], v178 src0_sel:WORD_1
	v_pk_fma_f32 v[222:223], v[84:85], v[218:219], v[222:223]
	v_pk_fma_f32 v[224:225], v[86:87], v[220:221], v[224:225]
	v_cvt_pk_f32_fp8_e32 v[218:219], v179
	v_cvt_pk_f32_fp8_sdwa v[220:221], v179 src0_sel:WORD_1
	v_pk_fma_f32 v[222:223], v[88:89], v[214:215], v[222:223]
	v_pk_fma_f32 v[224:225], v[90:91], v[216:217], v[224:225]
	v_pk_fma_f32 v[222:223], v[92:93], v[218:219], v[222:223]
	v_pk_fma_f32 v[224:225], v[94:95], v[220:221], v[224:225]
	v_pk_add_f32 v[222:223], v[222:223], v[224:225]
	s_nop 0
	v_add_f32_e32 v226, v222, v223
	v_cvt_pk_f32_fp8_e32 v[214:215], v180
	v_cvt_pk_f32_fp8_sdwa v[216:217], v180 src0_sel:WORD_1
	v_cvt_pk_f32_fp8_e32 v[218:219], v181
	v_cvt_pk_f32_fp8_sdwa v[220:221], v181 src0_sel:WORD_1
	v_pk_mul_f32 v[222:223], v[80:81], v[214:215]
	v_pk_mul_f32 v[224:225], v[82:83], v[216:217]
	v_cvt_pk_f32_fp8_e32 v[214:215], v182
	v_cvt_pk_f32_fp8_sdwa v[216:217], v182 src0_sel:WORD_1
	v_pk_fma_f32 v[222:223], v[84:85], v[218:219], v[222:223]
	v_pk_fma_f32 v[224:225], v[86:87], v[220:221], v[224:225]
	v_cvt_pk_f32_fp8_e32 v[218:219], v183
	v_cvt_pk_f32_fp8_sdwa v[220:221], v183 src0_sel:WORD_1
	v_pk_fma_f32 v[222:223], v[88:89], v[214:215], v[222:223]
	v_pk_fma_f32 v[224:225], v[90:91], v[216:217], v[224:225]
	v_pk_fma_f32 v[222:223], v[92:93], v[218:219], v[222:223]
	v_pk_fma_f32 v[224:225], v[94:95], v[220:221], v[224:225]
	v_pk_add_f32 v[222:223], v[222:223], v[224:225]
	s_nop 0
	v_add_f32_e32 v227, v222, v223
	v_cvt_pk_f32_fp8_e32 v[214:215], v184
	v_cvt_pk_f32_fp8_sdwa v[216:217], v184 src0_sel:WORD_1
	v_cvt_pk_f32_fp8_e32 v[218:219], v185
	v_cvt_pk_f32_fp8_sdwa v[220:221], v185 src0_sel:WORD_1
; template <bool STORE>
; DI void peer_item(const Params& p, int item, char* smem) {
;     ...
;       float part[8];
; #pragma unroll
;       for (int u = 0; u < 8; ++u) {
;         float d = 0.f;
; #pragma unroll
;         for (int i = 0; i < 4; ++i) {
;           f32x2_t lo = __builtin_amdgcn_cvt_pk_f32_fp8((int)uq[u][i], false);
;           f32x2_t hi = __builtin_amdgcn_cvt_pk_f32_fp8((int)uq[u][i], true);
;           d += xf[4 * i] * lo.x + xf[4 * i + 1] * lo.y + xf[4 * i + 2] * hi.x + xf[4 * i + 3] * hi.y;
;         }
;         part[u] = d;
;       }
;       float q4[4], r2[2], h;
; #pragma unroll
;       for (int j = 0; j < 4; ++j) {
;         float mine = b5 ? part[j + 4] : part[j];
;         float other = b5 ? part[j] : part[j + 4];
;         q4[j] = mine + __shfl_xor(other, 32);
;       }
; #pragma unroll
;       for (int j = 0; j < 2; ++j) {
;         float mine = b4 ? q4[j + 2] : q4[j];
;         float other = b4 ? q4[j] : q4[j + 2];
;         r2[j] = mine + __shfl_xor(other, 16);
;       }
;       {
;         float mine = b3 ? r2[1] : r2[0];
;         float other = b3 ? r2[0] : r2[1];
;         h = mine + __shfl_xor(other, 8);
;       }
;       h += __shfl_xor(h, 4);
;       h += __shfl_xor(h, 2);
;       h += __shfl_xor(h, 1);
	v_pk_mul_f32 v[222:223], v[80:81], v[214:215]
	v_pk_mul_f32 v[224:225], v[82:83], v[216:217]
	v_cvt_pk_f32_fp8_e32 v[214:215], v186
	v_cvt_pk_f32_fp8_sdwa v[216:217], v186 src0_sel:WORD_1
	v_pk_fma_f32 v[222:223], v[84:85], v[218:219], v[222:223]
	v_pk_fma_f32 v[224:225], v[86:87], v[220:221], v[224:225]
	v_cvt_pk_f32_fp8_e32 v[218:219], v187
	v_cvt_pk_f32_fp8_sdwa v[220:221], v187 src0_sel:WORD_1
	v_pk_fma_f32 v[222:223], v[88:89], v[214:215], v[222:223]
	v_pk_fma_f32 v[224:225], v[90:91], v[216:217], v[224:225]
	v_pk_fma_f32 v[222:223], v[92:93], v[218:219], v[222:223]
	v_pk_fma_f32 v[224:225], v[94:95], v[220:221], v[224:225]
	v_pk_add_f32 v[222:223], v[222:223], v[224:225]
	s_nop 0
	v_add_f32_e32 v228, v222, v223
	v_cvt_pk_f32_fp8_e32 v[214:215], v188
	v_cvt_pk_f32_fp8_sdwa v[216:217], v188 src0_sel:WORD_1
	v_cvt_pk_f32_fp8_e32 v[218:219], v189
	v_cvt_pk_f32_fp8_sdwa v[220:221], v189 src0_sel:WORD_1
	v_pk_mul_f32 v[222:223], v[80:81], v[214:215]
	v_pk_mul_f32 v[224:225], v[82:83], v[216:217]
	v_cvt_pk_f32_fp8_e32 v[214:215], v190
	v_cvt_pk_f32_fp8_sdwa v[216:217], v190 src0_sel:WORD_1
	v_pk_fma_f32 v[222:223], v[84:85], v[218:219], v[222:223]
	v_pk_fma_f32 v[224:225], v[86:87], v[220:221], v[224:225]
	v_cvt_pk_f32_fp8_e32 v[218:219], v191
	v_cvt_pk_f32_fp8_sdwa v[220:221], v191 src0_sel:WORD_1
	v_pk_fma_f32 v[222:223], v[88:89], v[214:215], v[222:223]
	v_pk_fma_f32 v[224:225], v[90:91], v[216:217], v[224:225]
	v_pk_fma_f32 v[222:223], v[92:93], v[218:219], v[222:223]
	v_pk_fma_f32 v[224:225], v[94:95], v[220:221], v[224:225]
	v_pk_add_f32 v[222:223], v[222:223], v[224:225]
	s_nop 0
	v_add_f32_e32 v229, v222, v223
	v_cvt_pk_f32_fp8_e32 v[214:215], v192
	v_cvt_pk_f32_fp8_sdwa v[216:217], v192 src0_sel:WORD_1
	v_cvt_pk_f32_fp8_e32 v[218:219], v193
	v_cvt_pk_f32_fp8_sdwa v[220:221], v193 src0_sel:WORD_1
	v_pk_mul_f32 v[222:223], v[80:81], v[214:215]
	v_pk_mul_f32 v[224:225], v[82:83], v[216:217]
	v_cvt_pk_f32_fp8_e32 v[214:215], v194
	v_cvt_pk_f32_fp8_sdwa v[216:217], v194 src0_sel:WORD_1
	v_pk_fma_f32 v[222:223], v[84:85], v[218:219], v[222:223]
	v_pk_fma_f32 v[224:225], v[86:87], v[220:221], v[224:225]
	v_cvt_pk_f32_fp8_e32 v[218:219], v195
	v_cvt_pk_f32_fp8_sdwa v[220:221], v195 src0_sel:WORD_1
	v_pk_fma_f32 v[222:223], v[88:89], v[214:215], v[222:223]
	v_pk_fma_f32 v[224:225], v[90:91], v[216:217], v[224:225]
	v_pk_fma_f32 v[222:223], v[92:93], v[218:219], v[222:223]
	v_pk_fma_f32 v[224:225], v[94:95], v[220:221], v[224:225]
	v_pk_add_f32 v[222:223], v[222:223], v[224:225]
	s_nop 0
	v_add_f32_e32 v230, v222, v223
	v_cvt_pk_f32_fp8_e32 v[214:215], v196
	v_cvt_pk_f32_fp8_sdwa v[216:217], v196 src0_sel:WORD_1
	v_cvt_pk_f32_fp8_e32 v[218:219], v197
	v_cvt_pk_f32_fp8_sdwa v[220:221], v197 src0_sel:WORD_1
	v_pk_mul_f32 v[222:223], v[80:81], v[214:215]
	v_pk_mul_f32 v[224:225], v[82:83], v[216:217]
	v_cvt_pk_f32_fp8_e32 v[214:215], v198
	v_cvt_pk_f32_fp8_sdwa v[216:217], v198 src0_sel:WORD_1
	v_pk_fma_f32 v[222:223], v[84:85], v[218:219], v[222:223]
	v_pk_fma_f32 v[224:225], v[86:87], v[220:221], v[224:225]
	v_cvt_pk_f32_fp8_e32 v[218:219], v199
	v_cvt_pk_f32_fp8_sdwa v[220:221], v199 src0_sel:WORD_1
	v_pk_fma_f32 v[222:223], v[88:89], v[214:215], v[222:223]
	v_pk_fma_f32 v[224:225], v[90:91], v[216:217], v[224:225]
	v_pk_fma_f32 v[222:223], v[92:93], v[218:219], v[222:223]
	v_pk_fma_f32 v[224:225], v[94:95], v[220:221], v[224:225]
	v_pk_add_f32 v[222:223], v[222:223], v[224:225]
	s_nop 0
	v_add_f32_e32 v231, v222, v223
	v_cvt_pk_f32_fp8_e32 v[214:215], v200
	v_cvt_pk_f32_fp8_sdwa v[216:217], v200 src0_sel:WORD_1
	v_cvt_pk_f32_fp8_e32 v[218:219], v201
	v_cvt_pk_f32_fp8_sdwa v[220:221], v201 src0_sel:WORD_1
	v_pk_mul_f32 v[222:223], v[80:81], v[214:215]
	v_pk_mul_f32 v[224:225], v[82:83], v[216:217]
	v_cvt_pk_f32_fp8_e32 v[214:215], v202
	v_cvt_pk_f32_fp8_sdwa v[216:217], v202 src0_sel:WORD_1
	v_pk_fma_f32 v[222:223], v[84:85], v[218:219], v[222:223]
	v_pk_fma_f32 v[224:225], v[86:87], v[220:221], v[224:225]
	v_cvt_pk_f32_fp8_e32 v[218:219], v203
	v_cvt_pk_f32_fp8_sdwa v[220:221], v203 src0_sel:WORD_1
	v_pk_fma_f32 v[222:223], v[88:89], v[214:215], v[222:223]
	v_pk_fma_f32 v[224:225], v[90:91], v[216:217], v[224:225]
	v_pk_fma_f32 v[222:223], v[92:93], v[218:219], v[222:223]
	v_pk_fma_f32 v[224:225], v[94:95], v[220:221], v[224:225]
	v_pk_add_f32 v[222:223], v[222:223], v[224:225]
	s_nop 0
	v_add_f32_e32 v232, v222, v223
	v_cvt_pk_f32_fp8_e32 v[214:215], v204
	v_cvt_pk_f32_fp8_sdwa v[216:217], v204 src0_sel:WORD_1
	v_cvt_pk_f32_fp8_e32 v[218:219], v205
	v_cvt_pk_f32_fp8_sdwa v[220:221], v205 src0_sel:WORD_1
	v_pk_mul_f32 v[222:223], v[80:81], v[214:215]
	v_pk_mul_f32 v[224:225], v[82:83], v[216:217]
	v_cvt_pk_f32_fp8_e32 v[214:215], v206
	v_cvt_pk_f32_fp8_sdwa v[216:217], v206 src0_sel:WORD_1
	v_pk_fma_f32 v[222:223], v[84:85], v[218:219], v[222:223]
	v_pk_fma_f32 v[224:225], v[86:87], v[220:221], v[224:225]
	v_cvt_pk_f32_fp8_e32 v[218:219], v207
	v_cvt_pk_f32_fp8_sdwa v[220:221], v207 src0_sel:WORD_1
	v_pk_fma_f32 v[222:223], v[88:89], v[214:215], v[222:223]
	v_pk_fma_f32 v[224:225], v[90:91], v[216:217], v[224:225]
	v_pk_fma_f32 v[222:223], v[92:93], v[218:219], v[222:223]
	v_pk_fma_f32 v[224:225], v[94:95], v[220:221], v[224:225]
	v_pk_add_f32 v[222:223], v[222:223], v[224:225]
	s_nop 0
	v_add_f32_e32 v233, v222, v223
	v_permlane32_swap_b32_e32 v226, v230
	v_permlane32_swap_b32_e32 v227, v231
	v_permlane32_swap_b32_e32 v228, v232
	v_permlane32_swap_b32_e32 v229, v233
	v_add_f32_e32 v226, v226, v230
	v_add_f32_e32 v228, v228, v232
	v_add_f32_e32 v227, v227, v231
	v_add_f32_e32 v229, v229, v233
	s_nop 1
	v_permlane16_swap_b32_e32 v226, v228
; template <bool STORE>
; DI void peer_item(const Params& p, int item, char* smem) {
;     ...
;       float part[8];
; #pragma unroll
;       for (int u = 0; u < 8; ++u) {
;         float d = 0.f;
; #pragma unroll
;         for (int i = 0; i < 4; ++i) {
;           f32x2_t lo = __builtin_amdgcn_cvt_pk_f32_fp8((int)uq[u][i], false);
;           f32x2_t hi = __builtin_amdgcn_cvt_pk_f32_fp8((int)uq[u][i], true);
;           d += xf[4 * i] * lo.x + xf[4 * i + 1] * lo.y + xf[4 * i + 2] * hi.x + xf[4 * i + 3] * hi.y;
;         }
;         part[u] = d;
;       }
;       float q4[4], r2[2], h;
; #pragma unroll
;       for (int j = 0; j < 4; ++j) {
;         float mine = b5 ? part[j + 4] : part[j];
;         float other = b5 ? part[j] : part[j + 4];
;         q4[j] = mine + __shfl_xor(other, 32);
;       }
; #pragma unroll
;       for (int j = 0; j < 2; ++j) {
;         float mine = b4 ? q4[j + 2] : q4[j];
;         float other = b4 ? q4[j] : q4[j + 2];
;         r2[j] = mine + __shfl_xor(other, 16);
;       }
;       {
;         float mine = b3 ? r2[1] : r2[0];
;         float other = b3 ? r2[0] : r2[1];
;         h = mine + __shfl_xor(other, 8);
;       }
;       h += __shfl_xor(h, 4);
;       h += __shfl_xor(h, 2);
;       h += __shfl_xor(h, 1);
	v_permlane16_swap_b32_e32 v227, v229
	v_add_f32_e32 v226, v226, v228
	v_add_f32_e32 v227, v227, v229
	s_nop 0
	v_cndmask_b32_e64 v230, v226, v227, s[24:25]
	v_cndmask_b32_e64 v231, v227, v226, s[24:25]
	s_nop 1
	v_add_f32_dpp v232, v231, v230 row_ror:8 row_mask:0xf bank_mask:0xf
	s_nop 1
	v_add_f32_dpp v233, v232, v232 quad_perm:[1,0,3,2] row_mask:0xf bank_mask:0xf
	s_nop 1
	v_add_f32_dpp v232, v233, v233 quad_perm:[2,3,0,1] row_mask:0xf bank_mask:0xf
	s_nop 1
	v_add_f32_dpp v233, v232, v232 row_half_mirror row_mask:0xf bank_mask:0xf
	ds_write_b32 v235, v233 offset:35328
	v_readlane_b32 s48, v142, s72
	v_readlane_b32 s49, v142, s73
	v_readlane_b32 s50, v142, s74
	v_readlane_b32 s51, v142, s75
	v_readlane_b32 s52, v142, s76
	v_readlane_b32 s53, v142, s77
	v_readlane_b32 s54, v142, s78
	v_readlane_b32 s55, v142, s79
	s_add_u32 s32, s0, s48
	s_addc_u32 s33, s1, 0
	s_add_u32 s34, s0, s49
	s_addc_u32 s35, s1, 0
	s_add_u32 s36, s0, s50
	s_addc_u32 s37, s1, 0
	s_add_u32 s38, s0, s51
	s_addc_u32 s39, s1, 0
	s_add_u32 s40, s0, s52
	s_addc_u32 s41, s1, 0
	s_add_u32 s42, s0, s53
	s_addc_u32 s43, s1, 0
	s_add_u32 s44, s0, s54
	s_addc_u32 s45, s1, 0
	s_add_u32 s46, s0, s55
	s_addc_u32 s47, s1, 0
	global_load_dwordx4 v[176:179], v234, s[32:33]
	global_load_dwordx4 v[180:183], v234, s[34:35]
	global_load_dwordx4 v[184:187], v234, s[36:37]
	global_load_dwordx4 v[188:191], v234, s[38:39]
	global_load_dwordx4 v[192:195], v234, s[40:41]
	global_load_dwordx4 v[196:199], v234, s[42:43]
	global_load_dwordx4 v[200:203], v234, s[44:45]
	global_load_dwordx4 v[204:207], v234, s[46:47]
	s_waitcnt vmcnt(8)
	v_cvt_pk_f32_fp8_e32 v[214:215], v144
	v_cvt_pk_f32_fp8_sdwa v[216:217], v144 src0_sel:WORD_1
	v_cvt_pk_f32_fp8_e32 v[218:219], v145
	v_cvt_pk_f32_fp8_sdwa v[220:221], v145 src0_sel:WORD_1
	v_pk_mul_f32 v[222:223], v[96:97], v[214:215]
	v_pk_mul_f32 v[224:225], v[98:99], v[216:217]
	v_cvt_pk_f32_fp8_e32 v[214:215], v146
	v_cvt_pk_f32_fp8_sdwa v[216:217], v146 src0_sel:WORD_1
	v_pk_fma_f32 v[222:223], v[100:101], v[218:219], v[222:223]
	v_pk_fma_f32 v[224:225], v[102:103], v[220:221], v[224:225]
	v_cvt_pk_f32_fp8_e32 v[218:219], v147
	v_cvt_pk_f32_fp8_sdwa v[220:221], v147 src0_sel:WORD_1
	v_pk_fma_f32 v[222:223], v[104:105], v[214:215], v[222:223]
	v_pk_fma_f32 v[224:225], v[106:107], v[216:217], v[224:225]
	v_pk_fma_f32 v[222:223], v[108:109], v[218:219], v[222:223]
	v_pk_fma_f32 v[224:225], v[110:111], v[220:221], v[224:225]
	v_pk_add_f32 v[222:223], v[222:223], v[224:225]
	s_nop 0
	v_add_f32_e32 v226, v222, v223
	v_cvt_pk_f32_fp8_e32 v[214:215], v148
	v_cvt_pk_f32_fp8_sdwa v[216:217], v148 src0_sel:WORD_1
	v_cvt_pk_f32_fp8_e32 v[218:219], v149
	v_cvt_pk_f32_fp8_sdwa v[220:221], v149 src0_sel:WORD_1
	v_pk_mul_f32 v[222:223], v[96:97], v[214:215]
	v_pk_mul_f32 v[224:225], v[98:99], v[216:217]
	v_cvt_pk_f32_fp8_e32 v[214:215], v150
	v_cvt_pk_f32_fp8_sdwa v[216:217], v150 src0_sel:WORD_1
	v_pk_fma_f32 v[222:223], v[100:101], v[218:219], v[222:223]
	v_pk_fma_f32 v[224:225], v[102:103], v[220:221], v[224:225]
	v_cvt_pk_f32_fp8_e32 v[218:219], v151
	v_cvt_pk_f32_fp8_sdwa v[220:221], v151 src0_sel:WORD_1
	v_pk_fma_f32 v[222:223], v[104:105], v[214:215], v[222:223]
	v_pk_fma_f32 v[224:225], v[106:107], v[216:217], v[224:225]
	v_pk_fma_f32 v[222:223], v[108:109], v[218:219], v[222:223]
	v_pk_fma_f32 v[224:225], v[110:111], v[220:221], v[224:225]
	v_pk_add_f32 v[222:223], v[222:223], v[224:225]
	s_nop 0
	v_add_f32_e32 v227, v222, v223
	v_cvt_pk_f32_fp8_e32 v[214:215], v152
	v_cvt_pk_f32_fp8_sdwa v[216:217], v152 src0_sel:WORD_1
	v_cvt_pk_f32_fp8_e32 v[218:219], v153
	v_cvt_pk_f32_fp8_sdwa v[220:221], v153 src0_sel:WORD_1
	v_pk_mul_f32 v[222:223], v[96:97], v[214:215]
	v_pk_mul_f32 v[224:225], v[98:99], v[216:217]
	v_cvt_pk_f32_fp8_e32 v[214:215], v154
	v_cvt_pk_f32_fp8_sdwa v[216:217], v154 src0_sel:WORD_1
	v_pk_fma_f32 v[222:223], v[100:101], v[218:219], v[222:223]
	v_pk_fma_f32 v[224:225], v[102:103], v[220:221], v[224:225]
	v_cvt_pk_f32_fp8_e32 v[218:219], v155
	v_cvt_pk_f32_fp8_sdwa v[220:221], v155 src0_sel:WORD_1
	v_pk_fma_f32 v[222:223], v[104:105], v[214:215], v[222:223]
	v_pk_fma_f32 v[224:225], v[106:107], v[216:217], v[224:225]
	v_pk_fma_f32 v[222:223], v[108:109], v[218:219], v[222:223]
	v_pk_fma_f32 v[224:225], v[110:111], v[220:221], v[224:225]
	v_pk_add_f32 v[222:223], v[222:223], v[224:225]
	s_nop 0
	v_add_f32_e32 v228, v222, v223
	v_cvt_pk_f32_fp8_e32 v[214:215], v156
	v_cvt_pk_f32_fp8_sdwa v[216:217], v156 src0_sel:WORD_1
	v_cvt_pk_f32_fp8_e32 v[218:219], v157
	v_cvt_pk_f32_fp8_sdwa v[220:221], v157 src0_sel:WORD_1
	v_pk_mul_f32 v[222:223], v[96:97], v[214:215]
	v_pk_mul_f32 v[224:225], v[98:99], v[216:217]
	v_cvt_pk_f32_fp8_e32 v[214:215], v158
	v_cvt_pk_f32_fp8_sdwa v[216:217], v158 src0_sel:WORD_1
	v_pk_fma_f32 v[222:223], v[100:101], v[218:219], v[222:223]
	v_pk_fma_f32 v[224:225], v[102:103], v[220:221], v[224:225]
	v_cvt_pk_f32_fp8_e32 v[218:219], v159
	v_cvt_pk_f32_fp8_sdwa v[220:221], v159 src0_sel:WORD_1
	v_pk_fma_f32 v[222:223], v[104:105], v[214:215], v[222:223]
	v_pk_fma_f32 v[224:225], v[106:107], v[216:217], v[224:225]
	v_pk_fma_f32 v[222:223], v[108:109], v[218:219], v[222:223]
	v_pk_fma_f32 v[224:225], v[110:111], v[220:221], v[224:225]
	v_pk_add_f32 v[222:223], v[222:223], v[224:225]
	s_nop 0
	v_add_f32_e32 v229, v222, v223
	v_cvt_pk_f32_fp8_e32 v[214:215], v160
	v_cvt_pk_f32_fp8_sdwa v[216:217], v160 src0_sel:WORD_1
	v_cvt_pk_f32_fp8_e32 v[218:219], v161
	v_cvt_pk_f32_fp8_sdwa v[220:221], v161 src0_sel:WORD_1
	v_pk_mul_f32 v[222:223], v[96:97], v[214:215]
	v_pk_mul_f32 v[224:225], v[98:99], v[216:217]
	v_cvt_pk_f32_fp8_e32 v[214:215], v162
; template <bool STORE>
; DI void peer_item(const Params& p, int item, char* smem) {
;     ...
;       float part[8];
; #pragma unroll
;       for (int u = 0; u < 8; ++u) {
;         float d = 0.f;
; #pragma unroll
;         for (int i = 0; i < 4; ++i) {
;           f32x2_t lo = __builtin_amdgcn_cvt_pk_f32_fp8((int)uq[u][i], false);
;           f32x2_t hi = __builtin_amdgcn_cvt_pk_f32_fp8((int)uq[u][i], true);
;           d += xf[4 * i] * lo.x + xf[4 * i + 1] * lo.y + xf[4 * i + 2] * hi.x + xf[4 * i + 3] * hi.y;
;         }
;         part[u] = d;
;       }
;       float q4[4], r2[2], h;
; #pragma unroll
;       for (int j = 0; j < 4; ++j) {
;         float mine = b5 ? part[j + 4] : part[j];
;         float other = b5 ? part[j] : part[j + 4];
;         q4[j] = mine + __shfl_xor(other, 32);
;       }
; #pragma unroll
;       for (int j = 0; j < 2; ++j) {
;         float mine = b4 ? q4[j + 2] : q4[j];
;         float other = b4 ? q4[j] : q4[j + 2];
;         r2[j] = mine + __shfl_xor(other, 16);
;       }
;       {
;         float mine = b3 ? r2[1] : r2[0];
;         float other = b3 ? r2[0] : r2[1];
;         h = mine + __shfl_xor(other, 8);
;       }
;       h += __shfl_xor(h, 4);
;       h += __shfl_xor(h, 2);
;       h += __shfl_xor(h, 1);
	v_cvt_pk_f32_fp8_sdwa v[216:217], v162 src0_sel:WORD_1
	v_pk_fma_f32 v[222:223], v[100:101], v[218:219], v[222:223]
	v_pk_fma_f32 v[224:225], v[102:103], v[220:221], v[224:225]
	v_cvt_pk_f32_fp8_e32 v[218:219], v163
	v_cvt_pk_f32_fp8_sdwa v[220:221], v163 src0_sel:WORD_1
	v_pk_fma_f32 v[222:223], v[104:105], v[214:215], v[222:223]
	v_pk_fma_f32 v[224:225], v[106:107], v[216:217], v[224:225]
	v_pk_fma_f32 v[222:223], v[108:109], v[218:219], v[222:223]
	v_pk_fma_f32 v[224:225], v[110:111], v[220:221], v[224:225]
	v_pk_add_f32 v[222:223], v[222:223], v[224:225]
	s_nop 0
	v_add_f32_e32 v230, v222, v223
	v_cvt_pk_f32_fp8_e32 v[214:215], v164
	v_cvt_pk_f32_fp8_sdwa v[216:217], v164 src0_sel:WORD_1
	v_cvt_pk_f32_fp8_e32 v[218:219], v165
	v_cvt_pk_f32_fp8_sdwa v[220:221], v165 src0_sel:WORD_1
	v_pk_mul_f32 v[222:223], v[96:97], v[214:215]
	v_pk_mul_f32 v[224:225], v[98:99], v[216:217]
	v_cvt_pk_f32_fp8_e32 v[214:215], v166
	v_cvt_pk_f32_fp8_sdwa v[216:217], v166 src0_sel:WORD_1
	v_pk_fma_f32 v[222:223], v[100:101], v[218:219], v[222:223]
	v_pk_fma_f32 v[224:225], v[102:103], v[220:221], v[224:225]
	v_cvt_pk_f32_fp8_e32 v[218:219], v167
	v_cvt_pk_f32_fp8_sdwa v[220:221], v167 src0_sel:WORD_1
	v_pk_fma_f32 v[222:223], v[104:105], v[214:215], v[222:223]
	v_pk_fma_f32 v[224:225], v[106:107], v[216:217], v[224:225]
	v_pk_fma_f32 v[222:223], v[108:109], v[218:219], v[222:223]
	v_pk_fma_f32 v[224:225], v[110:111], v[220:221], v[224:225]
	v_pk_add_f32 v[222:223], v[222:223], v[224:225]
	s_nop 0
	v_add_f32_e32 v231, v222, v223
	v_cvt_pk_f32_fp8_e32 v[214:215], v168
	v_cvt_pk_f32_fp8_sdwa v[216:217], v168 src0_sel:WORD_1
	v_cvt_pk_f32_fp8_e32 v[218:219], v169
	v_cvt_pk_f32_fp8_sdwa v[220:221], v169 src0_sel:WORD_1
	v_pk_mul_f32 v[222:223], v[96:97], v[214:215]
	v_pk_mul_f32 v[224:225], v[98:99], v[216:217]
	v_cvt_pk_f32_fp8_e32 v[214:215], v170
	v_cvt_pk_f32_fp8_sdwa v[216:217], v170 src0_sel:WORD_1
	v_pk_fma_f32 v[222:223], v[100:101], v[218:219], v[222:223]
	v_pk_fma_f32 v[224:225], v[102:103], v[220:221], v[224:225]
	v_cvt_pk_f32_fp8_e32 v[218:219], v171
	v_cvt_pk_f32_fp8_sdwa v[220:221], v171 src0_sel:WORD_1
	v_pk_fma_f32 v[222:223], v[104:105], v[214:215], v[222:223]
	v_pk_fma_f32 v[224:225], v[106:107], v[216:217], v[224:225]
	v_pk_fma_f32 v[222:223], v[108:109], v[218:219], v[222:223]
	v_pk_fma_f32 v[224:225], v[110:111], v[220:221], v[224:225]
	v_pk_add_f32 v[222:223], v[222:223], v[224:225]
	s_nop 0
	v_add_f32_e32 v232, v222, v223
	v_cvt_pk_f32_fp8_e32 v[214:215], v172
	v_cvt_pk_f32_fp8_sdwa v[216:217], v172 src0_sel:WORD_1
	v_cvt_pk_f32_fp8_e32 v[218:219], v173
	v_cvt_pk_f32_fp8_sdwa v[220:221], v173 src0_sel:WORD_1
	v_pk_mul_f32 v[222:223], v[96:97], v[214:215]
	v_pk_mul_f32 v[224:225], v[98:99], v[216:217]
	v_cvt_pk_f32_fp8_e32 v[214:215], v174
	v_cvt_pk_f32_fp8_sdwa v[216:217], v174 src0_sel:WORD_1
	v_pk_fma_f32 v[222:223], v[100:101], v[218:219], v[222:223]
	v_pk_fma_f32 v[224:225], v[102:103], v[220:221], v[224:225]
	v_cvt_pk_f32_fp8_e32 v[218:219], v175
	v_cvt_pk_f32_fp8_sdwa v[220:221], v175 src0_sel:WORD_1
	v_pk_fma_f32 v[222:223], v[104:105], v[214:215], v[222:223]
	v_pk_fma_f32 v[224:225], v[106:107], v[216:217], v[224:225]
	v_pk_fma_f32 v[222:223], v[108:109], v[218:219], v[222:223]
	v_pk_fma_f32 v[224:225], v[110:111], v[220:221], v[224:225]
	v_pk_add_f32 v[222:223], v[222:223], v[224:225]
	s_nop 0
	v_add_f32_e32 v233, v222, v223
	v_permlane32_swap_b32_e32 v226, v230
	v_permlane32_swap_b32_e32 v227, v231
	v_permlane32_swap_b32_e32 v228, v232
	v_permlane32_swap_b32_e32 v229, v233
	v_add_f32_e32 v226, v226, v230
	v_add_f32_e32 v228, v228, v232
	v_add_f32_e32 v227, v227, v231
	v_add_f32_e32 v229, v229, v233
	s_nop 1
	v_permlane16_swap_b32_e32 v226, v228
	v_permlane16_swap_b32_e32 v227, v229
	v_add_f32_e32 v226, v226, v228
	v_add_f32_e32 v227, v227, v229
	s_nop 0
	v_cndmask_b32_e64 v230, v226, v227, s[24:25]
	v_cndmask_b32_e64 v231, v227, v226, s[24:25]
	s_nop 1
	v_add_f32_dpp v232, v231, v230 row_ror:8 row_mask:0xf bank_mask:0xf
	s_nop 1
	v_add_f32_dpp v233, v232, v232 quad_perm:[1,0,3,2] row_mask:0xf bank_mask:0xf
	s_nop 1
	v_add_f32_dpp v232, v233, v233 quad_perm:[2,3,0,1] row_mask:0xf bank_mask:0xf
	s_nop 1
	v_add_f32_dpp v233, v232, v232 row_half_mirror row_mask:0xf bank_mask:0xf
	ds_write_b32 v235, v233 offset:35840
	v_readlane_b32 s48, v129, s72
	v_readlane_b32 s49, v129, s73
	v_readlane_b32 s50, v129, s74
	v_readlane_b32 s51, v129, s75
	v_readlane_b32 s52, v129, s76
	v_readlane_b32 s53, v129, s77
	v_readlane_b32 s54, v129, s78
	v_readlane_b32 s55, v129, s79
	s_add_u32 s32, s0, s48
	s_addc_u32 s33, s1, 0
	s_add_u32 s34, s0, s49
	s_addc_u32 s35, s1, 0
	s_add_u32 s36, s0, s50
	s_addc_u32 s37, s1, 0
	s_add_u32 s38, s0, s51
	s_addc_u32 s39, s1, 0
	s_add_u32 s40, s0, s52
	s_addc_u32 s41, s1, 0
	s_add_u32 s42, s0, s53
	s_addc_u32 s43, s1, 0
	s_add_u32 s44, s0, s54
	s_addc_u32 s45, s1, 0
	s_add_u32 s46, s0, s55
	s_addc_u32 s47, s1, 0
	global_load_dwordx4 v[144:147], v234, s[32:33]
	global_load_dwordx4 v[148:151], v234, s[34:35]
	global_load_dwordx4 v[152:155], v234, s[36:37]
	global_load_dwordx4 v[156:159], v234, s[38:39]
	global_load_dwordx4 v[160:163], v234, s[40:41]
	global_load_dwordx4 v[164:167], v234, s[42:43]
	global_load_dwordx4 v[168:171], v234, s[44:45]
	global_load_dwordx4 v[172:175], v234, s[46:47]
	s_waitcnt vmcnt(8)
; template <bool STORE>
; DI void peer_item(const Params& p, int item, char* smem) {
;     ...
;       float part[8];
; #pragma unroll
;       for (int u = 0; u < 8; ++u) {
;         float d = 0.f;
; #pragma unroll
;         for (int i = 0; i < 4; ++i) {
;           f32x2_t lo = __builtin_amdgcn_cvt_pk_f32_fp8((int)uq[u][i], false);
;           f32x2_t hi = __builtin_amdgcn_cvt_pk_f32_fp8((int)uq[u][i], true);
;           d += xf[4 * i] * lo.x + xf[4 * i + 1] * lo.y + xf[4 * i + 2] * hi.x + xf[4 * i + 3] * hi.y;
;         }
;         part[u] = d;
;       }
	v_cvt_pk_f32_fp8_e32 v[214:215], v176
	v_cvt_pk_f32_fp8_sdwa v[216:217], v176 src0_sel:WORD_1
	v_cvt_pk_f32_fp8_e32 v[218:219], v177
	v_cvt_pk_f32_fp8_sdwa v[220:221], v177 src0_sel:WORD_1
	v_pk_mul_f32 v[222:223], v[112:113], v[214:215]
	v_pk_mul_f32 v[224:225], v[114:115], v[216:217]
	v_cvt_pk_f32_fp8_e32 v[214:215], v178
	v_cvt_pk_f32_fp8_sdwa v[216:217], v178 src0_sel:WORD_1
	v_pk_fma_f32 v[222:223], v[116:117], v[218:219], v[222:223]
	v_pk_fma_f32 v[224:225], v[118:119], v[220:221], v[224:225]
	v_cvt_pk_f32_fp8_e32 v[218:219], v179
	v_cvt_pk_f32_fp8_sdwa v[220:221], v179 src0_sel:WORD_1
	v_pk_fma_f32 v[222:223], v[120:121], v[214:215], v[222:223]
	v_pk_fma_f32 v[224:225], v[122:123], v[216:217], v[224:225]
	v_pk_fma_f32 v[222:223], v[124:125], v[218:219], v[222:223]
	v_pk_fma_f32 v[224:225], v[126:127], v[220:221], v[224:225]
	v_pk_add_f32 v[222:223], v[222:223], v[224:225]
	s_nop 0
	v_add_f32_e32 v226, v222, v223
	v_cvt_pk_f32_fp8_e32 v[214:215], v180
	v_cvt_pk_f32_fp8_sdwa v[216:217], v180 src0_sel:WORD_1
	v_cvt_pk_f32_fp8_e32 v[218:219], v181
	v_cvt_pk_f32_fp8_sdwa v[220:221], v181 src0_sel:WORD_1
	v_pk_mul_f32 v[222:223], v[112:113], v[214:215]
	v_pk_mul_f32 v[224:225], v[114:115], v[216:217]
	v_cvt_pk_f32_fp8_e32 v[214:215], v182
	v_cvt_pk_f32_fp8_sdwa v[216:217], v182 src0_sel:WORD_1
	v_pk_fma_f32 v[222:223], v[116:117], v[218:219], v[222:223]
	v_pk_fma_f32 v[224:225], v[118:119], v[220:221], v[224:225]
	v_cvt_pk_f32_fp8_e32 v[218:219], v183
	v_cvt_pk_f32_fp8_sdwa v[220:221], v183 src0_sel:WORD_1
	v_pk_fma_f32 v[222:223], v[120:121], v[214:215], v[222:223]
	v_pk_fma_f32 v[224:225], v[122:123], v[216:217], v[224:225]
	v_pk_fma_f32 v[222:223], v[124:125], v[218:219], v[222:223]
	v_pk_fma_f32 v[224:225], v[126:127], v[220:221], v[224:225]
	v_pk_add_f32 v[222:223], v[222:223], v[224:225]
	s_nop 0
	v_add_f32_e32 v227, v222, v223
	v_cvt_pk_f32_fp8_e32 v[214:215], v184
	v_cvt_pk_f32_fp8_sdwa v[216:217], v184 src0_sel:WORD_1
	v_cvt_pk_f32_fp8_e32 v[218:219], v185
	v_cvt_pk_f32_fp8_sdwa v[220:221], v185 src0_sel:WORD_1
	v_pk_mul_f32 v[222:223], v[112:113], v[214:215]
	v_pk_mul_f32 v[224:225], v[114:115], v[216:217]
	v_cvt_pk_f32_fp8_e32 v[214:215], v186
	v_cvt_pk_f32_fp8_sdwa v[216:217], v186 src0_sel:WORD_1
	v_pk_fma_f32 v[222:223], v[116:117], v[218:219], v[222:223]
	v_pk_fma_f32 v[224:225], v[118:119], v[220:221], v[224:225]
	v_cvt_pk_f32_fp8_e32 v[218:219], v187
	v_cvt_pk_f32_fp8_sdwa v[220:221], v187 src0_sel:WORD_1
	v_pk_fma_f32 v[222:223], v[120:121], v[214:215], v[222:223]
	v_pk_fma_f32 v[224:225], v[122:123], v[216:217], v[224:225]
	v_pk_fma_f32 v[222:223], v[124:125], v[218:219], v[222:223]
	v_pk_fma_f32 v[224:225], v[126:127], v[220:221], v[224:225]
	v_pk_add_f32 v[222:223], v[222:223], v[224:225]
	s_nop 0
	v_add_f32_e32 v228, v222, v223
	v_cvt_pk_f32_fp8_e32 v[214:215], v188
	v_cvt_pk_f32_fp8_sdwa v[216:217], v188 src0_sel:WORD_1
	v_cvt_pk_f32_fp8_e32 v[218:219], v189
	v_cvt_pk_f32_fp8_sdwa v[220:221], v189 src0_sel:WORD_1
	v_pk_mul_f32 v[222:223], v[112:113], v[214:215]
	v_pk_mul_f32 v[224:225], v[114:115], v[216:217]
	v_cvt_pk_f32_fp8_e32 v[214:215], v190
	v_cvt_pk_f32_fp8_sdwa v[216:217], v190 src0_sel:WORD_1
	v_pk_fma_f32 v[222:223], v[116:117], v[218:219], v[222:223]
	v_pk_fma_f32 v[224:225], v[118:119], v[220:221], v[224:225]
	v_cvt_pk_f32_fp8_e32 v[218:219], v191
	v_cvt_pk_f32_fp8_sdwa v[220:221], v191 src0_sel:WORD_1
	v_pk_fma_f32 v[222:223], v[120:121], v[214:215], v[222:223]
	v_pk_fma_f32 v[224:225], v[122:123], v[216:217], v[224:225]
	v_pk_fma_f32 v[222:223], v[124:125], v[218:219], v[222:223]
	v_pk_fma_f32 v[224:225], v[126:127], v[220:221], v[224:225]
	v_pk_add_f32 v[222:223], v[222:223], v[224:225]
	s_nop 0
	v_add_f32_e32 v229, v222, v223
	v_cvt_pk_f32_fp8_e32 v[214:215], v192
	v_cvt_pk_f32_fp8_sdwa v[216:217], v192 src0_sel:WORD_1
	v_cvt_pk_f32_fp8_e32 v[218:219], v193
	v_cvt_pk_f32_fp8_sdwa v[220:221], v193 src0_sel:WORD_1
	v_pk_mul_f32 v[222:223], v[112:113], v[214:215]
	v_pk_mul_f32 v[224:225], v[114:115], v[216:217]
	v_cvt_pk_f32_fp8_e32 v[214:215], v194
	v_cvt_pk_f32_fp8_sdwa v[216:217], v194 src0_sel:WORD_1
	v_pk_fma_f32 v[222:223], v[116:117], v[218:219], v[222:223]
	v_pk_fma_f32 v[224:225], v[118:119], v[220:221], v[224:225]
	v_cvt_pk_f32_fp8_e32 v[218:219], v195
	v_cvt_pk_f32_fp8_sdwa v[220:221], v195 src0_sel:WORD_1
	v_pk_fma_f32 v[222:223], v[120:121], v[214:215], v[222:223]
	v_pk_fma_f32 v[224:225], v[122:123], v[216:217], v[224:225]
	v_pk_fma_f32 v[222:223], v[124:125], v[218:219], v[222:223]
	v_pk_fma_f32 v[224:225], v[126:127], v[220:221], v[224:225]
	v_pk_add_f32 v[222:223], v[222:223], v[224:225]
	s_nop 0
	v_add_f32_e32 v230, v222, v223
	v_cvt_pk_f32_fp8_e32 v[214:215], v196
	v_cvt_pk_f32_fp8_sdwa v[216:217], v196 src0_sel:WORD_1
	v_cvt_pk_f32_fp8_e32 v[218:219], v197
	v_cvt_pk_f32_fp8_sdwa v[220:221], v197 src0_sel:WORD_1
	v_pk_mul_f32 v[222:223], v[112:113], v[214:215]
	v_pk_mul_f32 v[224:225], v[114:115], v[216:217]
	v_cvt_pk_f32_fp8_e32 v[214:215], v198
	v_cvt_pk_f32_fp8_sdwa v[216:217], v198 src0_sel:WORD_1
	v_pk_fma_f32 v[222:223], v[116:117], v[218:219], v[222:223]
	v_pk_fma_f32 v[224:225], v[118:119], v[220:221], v[224:225]
	v_cvt_pk_f32_fp8_e32 v[218:219], v199
	v_cvt_pk_f32_fp8_sdwa v[220:221], v199 src0_sel:WORD_1
	v_pk_fma_f32 v[222:223], v[120:121], v[214:215], v[222:223]
	v_pk_fma_f32 v[224:225], v[122:123], v[216:217], v[224:225]
	v_pk_fma_f32 v[222:223], v[124:125], v[218:219], v[222:223]
	v_pk_fma_f32 v[224:225], v[126:127], v[220:221], v[224:225]
	v_pk_add_f32 v[222:223], v[222:223], v[224:225]
	s_nop 0
	v_add_f32_e32 v231, v222, v223
	v_cvt_pk_f32_fp8_e32 v[214:215], v200
; template <bool STORE>
; DI void peer_item(const Params& p, int item, char* smem) {
;     ...
;       float part[8];
; #pragma unroll
;       for (int u = 0; u < 8; ++u) {
;         float d = 0.f;
; #pragma unroll
;         for (int i = 0; i < 4; ++i) {
;           f32x2_t lo = __builtin_amdgcn_cvt_pk_f32_fp8((int)uq[u][i], false);
;           f32x2_t hi = __builtin_amdgcn_cvt_pk_f32_fp8((int)uq[u][i], true);
;           d += xf[4 * i] * lo.x + xf[4 * i + 1] * lo.y + xf[4 * i + 2] * hi.x + xf[4 * i + 3] * hi.y;
;         }
;         part[u] = d;
;       }
;       float q4[4], r2[2], h;
; #pragma unroll
;       for (int j = 0; j < 4; ++j) {
;         float mine = b5 ? part[j + 4] : part[j];
;         float other = b5 ? part[j] : part[j + 4];
;         q4[j] = mine + __shfl_xor(other, 32);
;       }
; #pragma unroll
;       for (int j = 0; j < 2; ++j) {
;         float mine = b4 ? q4[j + 2] : q4[j];
;         float other = b4 ? q4[j] : q4[j + 2];
;         r2[j] = mine + __shfl_xor(other, 16);
;       }
;       {
;         float mine = b3 ? r2[1] : r2[0];
;         float other = b3 ? r2[0] : r2[1];
;         h = mine + __shfl_xor(other, 8);
;       }
;       h += __shfl_xor(h, 4);
;       h += __shfl_xor(h, 2);
;       h += __shfl_xor(h, 1);
	v_cvt_pk_f32_fp8_sdwa v[216:217], v200 src0_sel:WORD_1
	v_cvt_pk_f32_fp8_e32 v[218:219], v201
	v_cvt_pk_f32_fp8_sdwa v[220:221], v201 src0_sel:WORD_1
	v_pk_mul_f32 v[222:223], v[112:113], v[214:215]
	v_pk_mul_f32 v[224:225], v[114:115], v[216:217]
	v_cvt_pk_f32_fp8_e32 v[214:215], v202
	v_cvt_pk_f32_fp8_sdwa v[216:217], v202 src0_sel:WORD_1
	v_pk_fma_f32 v[222:223], v[116:117], v[218:219], v[222:223]
	v_pk_fma_f32 v[224:225], v[118:119], v[220:221], v[224:225]
	v_cvt_pk_f32_fp8_e32 v[218:219], v203
	v_cvt_pk_f32_fp8_sdwa v[220:221], v203 src0_sel:WORD_1
	v_pk_fma_f32 v[222:223], v[120:121], v[214:215], v[222:223]
	v_pk_fma_f32 v[224:225], v[122:123], v[216:217], v[224:225]
	v_pk_fma_f32 v[222:223], v[124:125], v[218:219], v[222:223]
	v_pk_fma_f32 v[224:225], v[126:127], v[220:221], v[224:225]
	v_pk_add_f32 v[222:223], v[222:223], v[224:225]
	s_nop 0
	v_add_f32_e32 v232, v222, v223
	v_cvt_pk_f32_fp8_e32 v[214:215], v204
	v_cvt_pk_f32_fp8_sdwa v[216:217], v204 src0_sel:WORD_1
	v_cvt_pk_f32_fp8_e32 v[218:219], v205
	v_cvt_pk_f32_fp8_sdwa v[220:221], v205 src0_sel:WORD_1
	v_pk_mul_f32 v[222:223], v[112:113], v[214:215]
	v_pk_mul_f32 v[224:225], v[114:115], v[216:217]
	v_cvt_pk_f32_fp8_e32 v[214:215], v206
	v_cvt_pk_f32_fp8_sdwa v[216:217], v206 src0_sel:WORD_1
	v_pk_fma_f32 v[222:223], v[116:117], v[218:219], v[222:223]
	v_pk_fma_f32 v[224:225], v[118:119], v[220:221], v[224:225]
	v_cvt_pk_f32_fp8_e32 v[218:219], v207
	v_cvt_pk_f32_fp8_sdwa v[220:221], v207 src0_sel:WORD_1
	v_pk_fma_f32 v[222:223], v[120:121], v[214:215], v[222:223]
	v_pk_fma_f32 v[224:225], v[122:123], v[216:217], v[224:225]
	v_pk_fma_f32 v[222:223], v[124:125], v[218:219], v[222:223]
	v_pk_fma_f32 v[224:225], v[126:127], v[220:221], v[224:225]
	v_pk_add_f32 v[222:223], v[222:223], v[224:225]
	s_nop 0
	v_add_f32_e32 v233, v222, v223
	v_permlane32_swap_b32_e32 v226, v230
	v_permlane32_swap_b32_e32 v227, v231
	v_permlane32_swap_b32_e32 v228, v232
	v_permlane32_swap_b32_e32 v229, v233
	v_add_f32_e32 v226, v226, v230
	v_add_f32_e32 v228, v228, v232
	v_add_f32_e32 v227, v227, v231
	v_add_f32_e32 v229, v229, v233
	s_nop 1
	v_permlane16_swap_b32_e32 v226, v228
	v_permlane16_swap_b32_e32 v227, v229
	v_add_f32_e32 v226, v226, v228
	v_add_f32_e32 v227, v227, v229
	s_nop 0
	v_cndmask_b32_e64 v230, v226, v227, s[24:25]
	v_cndmask_b32_e64 v231, v227, v226, s[24:25]
	s_nop 1
	v_add_f32_dpp v232, v231, v230 row_ror:8 row_mask:0xf bank_mask:0xf
	s_nop 1
	v_add_f32_dpp v233, v232, v232 quad_perm:[1,0,3,2] row_mask:0xf bank_mask:0xf
	s_nop 1
	v_add_f32_dpp v232, v233, v233 quad_perm:[2,3,0,1] row_mask:0xf bank_mask:0xf
	s_nop 1
	v_add_f32_dpp v233, v232, v232 row_half_mirror row_mask:0xf bank_mask:0xf
	ds_write_b32 v235, v233 offset:36352
	v_readlane_b32 s48, v131, s72
	v_readlane_b32 s49, v131, s73
	v_readlane_b32 s50, v131, s74
	v_readlane_b32 s51, v131, s75
	v_readlane_b32 s52, v131, s76
	v_readlane_b32 s53, v131, s77
	v_readlane_b32 s54, v131, s78
	v_readlane_b32 s55, v131, s79
	s_add_u32 s32, s0, s48
	s_addc_u32 s33, s1, 0
	s_add_u32 s34, s0, s49
	s_addc_u32 s35, s1, 0
	s_add_u32 s36, s0, s50
	s_addc_u32 s37, s1, 0
	s_add_u32 s38, s0, s51
	s_addc_u32 s39, s1, 0
	s_add_u32 s40, s0, s52
	s_addc_u32 s41, s1, 0
	s_add_u32 s42, s0, s53
	s_addc_u32 s43, s1, 0
	s_add_u32 s44, s0, s54
	s_addc_u32 s45, s1, 0
	s_add_u32 s46, s0, s55
	s_addc_u32 s47, s1, 0
	global_load_dwordx4 v[176:179], v234, s[32:33]
	global_load_dwordx4 v[180:183], v234, s[34:35]
	global_load_dwordx4 v[184:187], v234, s[36:37]
	global_load_dwordx4 v[188:191], v234, s[38:39]
	global_load_dwordx4 v[192:195], v234, s[40:41]
	global_load_dwordx4 v[196:199], v234, s[42:43]
	global_load_dwordx4 v[200:203], v234, s[44:45]
	global_load_dwordx4 v[204:207], v234, s[46:47]
	s_waitcnt vmcnt(8)
	v_cvt_pk_f32_fp8_e32 v[214:215], v144
	v_cvt_pk_f32_fp8_sdwa v[216:217], v144 src0_sel:WORD_1
	v_cvt_pk_f32_fp8_e32 v[218:219], v145
	v_cvt_pk_f32_fp8_sdwa v[220:221], v145 src0_sel:WORD_1
	v_pk_mul_f32 v[222:223], v[0:1], v[214:215]
	v_pk_mul_f32 v[224:225], v[2:3], v[216:217]
	v_cvt_pk_f32_fp8_e32 v[214:215], v146
	v_cvt_pk_f32_fp8_sdwa v[216:217], v146 src0_sel:WORD_1
	v_pk_fma_f32 v[222:223], v[4:5], v[218:219], v[222:223]
	v_pk_fma_f32 v[224:225], v[6:7], v[220:221], v[224:225]
	v_cvt_pk_f32_fp8_e32 v[218:219], v147
	v_cvt_pk_f32_fp8_sdwa v[220:221], v147 src0_sel:WORD_1
	v_pk_fma_f32 v[222:223], v[8:9], v[214:215], v[222:223]
	v_pk_fma_f32 v[224:225], v[10:11], v[216:217], v[224:225]
	v_pk_fma_f32 v[222:223], v[12:13], v[218:219], v[222:223]
	v_pk_fma_f32 v[224:225], v[14:15], v[220:221], v[224:225]
	v_pk_add_f32 v[222:223], v[222:223], v[224:225]
	s_nop 0
	v_add_f32_e32 v226, v222, v223
	v_cvt_pk_f32_fp8_e32 v[214:215], v148
	v_cvt_pk_f32_fp8_sdwa v[216:217], v148 src0_sel:WORD_1
	v_cvt_pk_f32_fp8_e32 v[218:219], v149
	v_cvt_pk_f32_fp8_sdwa v[220:221], v149 src0_sel:WORD_1
	v_pk_mul_f32 v[222:223], v[0:1], v[214:215]
	v_pk_mul_f32 v[224:225], v[2:3], v[216:217]
	v_cvt_pk_f32_fp8_e32 v[214:215], v150
	v_cvt_pk_f32_fp8_sdwa v[216:217], v150 src0_sel:WORD_1
	v_pk_fma_f32 v[222:223], v[4:5], v[218:219], v[222:223]
	v_pk_fma_f32 v[224:225], v[6:7], v[220:221], v[224:225]
	v_cvt_pk_f32_fp8_e32 v[218:219], v151
	v_cvt_pk_f32_fp8_sdwa v[220:221], v151 src0_sel:WORD_1
	v_pk_fma_f32 v[222:223], v[8:9], v[214:215], v[222:223]
	v_pk_fma_f32 v[224:225], v[10:11], v[216:217], v[224:225]
	v_pk_fma_f32 v[222:223], v[12:13], v[218:219], v[222:223]
	v_pk_fma_f32 v[224:225], v[14:15], v[220:221], v[224:225]
	v_pk_add_f32 v[222:223], v[222:223], v[224:225]
	s_nop 0
	v_add_f32_e32 v227, v222, v223
	v_cvt_pk_f32_fp8_e32 v[214:215], v152
; template <bool STORE>
; DI void peer_item(const Params& p, int item, char* smem) {
;     ...
;       float part[8];
; #pragma unroll
;       for (int u = 0; u < 8; ++u) {
;         float d = 0.f;
; #pragma unroll
;         for (int i = 0; i < 4; ++i) {
;           f32x2_t lo = __builtin_amdgcn_cvt_pk_f32_fp8((int)uq[u][i], false);
;           f32x2_t hi = __builtin_amdgcn_cvt_pk_f32_fp8((int)uq[u][i], true);
;           d += xf[4 * i] * lo.x + xf[4 * i + 1] * lo.y + xf[4 * i + 2] * hi.x + xf[4 * i + 3] * hi.y;
;         }
;         part[u] = d;
;       }
	v_cvt_pk_f32_fp8_sdwa v[216:217], v152 src0_sel:WORD_1
	v_cvt_pk_f32_fp8_e32 v[218:219], v153
	v_cvt_pk_f32_fp8_sdwa v[220:221], v153 src0_sel:WORD_1
	v_pk_mul_f32 v[222:223], v[0:1], v[214:215]
	v_pk_mul_f32 v[224:225], v[2:3], v[216:217]
	v_cvt_pk_f32_fp8_e32 v[214:215], v154
	v_cvt_pk_f32_fp8_sdwa v[216:217], v154 src0_sel:WORD_1
	v_pk_fma_f32 v[222:223], v[4:5], v[218:219], v[222:223]
	v_pk_fma_f32 v[224:225], v[6:7], v[220:221], v[224:225]
	v_cvt_pk_f32_fp8_e32 v[218:219], v155
	v_cvt_pk_f32_fp8_sdwa v[220:221], v155 src0_sel:WORD_1
	v_pk_fma_f32 v[222:223], v[8:9], v[214:215], v[222:223]
	v_pk_fma_f32 v[224:225], v[10:11], v[216:217], v[224:225]
	v_pk_fma_f32 v[222:223], v[12:13], v[218:219], v[222:223]
	v_pk_fma_f32 v[224:225], v[14:15], v[220:221], v[224:225]
	v_pk_add_f32 v[222:223], v[222:223], v[224:225]
	s_nop 0
	v_add_f32_e32 v228, v222, v223
	v_cvt_pk_f32_fp8_e32 v[214:215], v156
	v_cvt_pk_f32_fp8_sdwa v[216:217], v156 src0_sel:WORD_1
	v_cvt_pk_f32_fp8_e32 v[218:219], v157
	v_cvt_pk_f32_fp8_sdwa v[220:221], v157 src0_sel:WORD_1
	v_pk_mul_f32 v[222:223], v[0:1], v[214:215]
	v_pk_mul_f32 v[224:225], v[2:3], v[216:217]
	v_cvt_pk_f32_fp8_e32 v[214:215], v158
	v_cvt_pk_f32_fp8_sdwa v[216:217], v158 src0_sel:WORD_1
	v_pk_fma_f32 v[222:223], v[4:5], v[218:219], v[222:223]
	v_pk_fma_f32 v[224:225], v[6:7], v[220:221], v[224:225]
	v_cvt_pk_f32_fp8_e32 v[218:219], v159
	v_cvt_pk_f32_fp8_sdwa v[220:221], v159 src0_sel:WORD_1
	v_pk_fma_f32 v[222:223], v[8:9], v[214:215], v[222:223]
	v_pk_fma_f32 v[224:225], v[10:11], v[216:217], v[224:225]
	v_pk_fma_f32 v[222:223], v[12:13], v[218:219], v[222:223]
	v_pk_fma_f32 v[224:225], v[14:15], v[220:221], v[224:225]
	v_pk_add_f32 v[222:223], v[222:223], v[224:225]
	s_nop 0
	v_add_f32_e32 v229, v222, v223
	v_cvt_pk_f32_fp8_e32 v[214:215], v160
	v_cvt_pk_f32_fp8_sdwa v[216:217], v160 src0_sel:WORD_1
	v_cvt_pk_f32_fp8_e32 v[218:219], v161
	v_cvt_pk_f32_fp8_sdwa v[220:221], v161 src0_sel:WORD_1
	v_pk_mul_f32 v[222:223], v[0:1], v[214:215]
	v_pk_mul_f32 v[224:225], v[2:3], v[216:217]
	v_cvt_pk_f32_fp8_e32 v[214:215], v162
	v_cvt_pk_f32_fp8_sdwa v[216:217], v162 src0_sel:WORD_1
	v_pk_fma_f32 v[222:223], v[4:5], v[218:219], v[222:223]
	v_pk_fma_f32 v[224:225], v[6:7], v[220:221], v[224:225]
	v_cvt_pk_f32_fp8_e32 v[218:219], v163
	v_cvt_pk_f32_fp8_sdwa v[220:221], v163 src0_sel:WORD_1
	v_pk_fma_f32 v[222:223], v[8:9], v[214:215], v[222:223]
	v_pk_fma_f32 v[224:225], v[10:11], v[216:217], v[224:225]
	v_pk_fma_f32 v[222:223], v[12:13], v[218:219], v[222:223]
	v_pk_fma_f32 v[224:225], v[14:15], v[220:221], v[224:225]
	v_pk_add_f32 v[222:223], v[222:223], v[224:225]
	s_nop 0
	v_add_f32_e32 v230, v222, v223
	v_cvt_pk_f32_fp8_e32 v[214:215], v164
	v_cvt_pk_f32_fp8_sdwa v[216:217], v164 src0_sel:WORD_1
	v_cvt_pk_f32_fp8_e32 v[218:219], v165
	v_cvt_pk_f32_fp8_sdwa v[220:221], v165 src0_sel:WORD_1
	v_pk_mul_f32 v[222:223], v[0:1], v[214:215]
	v_pk_mul_f32 v[224:225], v[2:3], v[216:217]
	v_cvt_pk_f32_fp8_e32 v[214:215], v166
	v_cvt_pk_f32_fp8_sdwa v[216:217], v166 src0_sel:WORD_1
	v_pk_fma_f32 v[222:223], v[4:5], v[218:219], v[222:223]
	v_pk_fma_f32 v[224:225], v[6:7], v[220:221], v[224:225]
	v_cvt_pk_f32_fp8_e32 v[218:219], v167
	v_cvt_pk_f32_fp8_sdwa v[220:221], v167 src0_sel:WORD_1
	v_pk_fma_f32 v[222:223], v[8:9], v[214:215], v[222:223]
	v_pk_fma_f32 v[224:225], v[10:11], v[216:217], v[224:225]
	v_pk_fma_f32 v[222:223], v[12:13], v[218:219], v[222:223]
	v_pk_fma_f32 v[224:225], v[14:15], v[220:221], v[224:225]
	v_pk_add_f32 v[222:223], v[222:223], v[224:225]
	s_nop 0
	v_add_f32_e32 v231, v222, v223
	v_cvt_pk_f32_fp8_e32 v[214:215], v168
	v_cvt_pk_f32_fp8_sdwa v[216:217], v168 src0_sel:WORD_1
	v_cvt_pk_f32_fp8_e32 v[218:219], v169
	v_cvt_pk_f32_fp8_sdwa v[220:221], v169 src0_sel:WORD_1
	v_pk_mul_f32 v[222:223], v[0:1], v[214:215]
	v_pk_mul_f32 v[224:225], v[2:3], v[216:217]
	v_cvt_pk_f32_fp8_e32 v[214:215], v170
	v_cvt_pk_f32_fp8_sdwa v[216:217], v170 src0_sel:WORD_1
	v_pk_fma_f32 v[222:223], v[4:5], v[218:219], v[222:223]
	v_pk_fma_f32 v[224:225], v[6:7], v[220:221], v[224:225]
	v_cvt_pk_f32_fp8_e32 v[218:219], v171
	v_cvt_pk_f32_fp8_sdwa v[220:221], v171 src0_sel:WORD_1
	v_pk_fma_f32 v[222:223], v[8:9], v[214:215], v[222:223]
	v_pk_fma_f32 v[224:225], v[10:11], v[216:217], v[224:225]
	v_pk_fma_f32 v[222:223], v[12:13], v[218:219], v[222:223]
	v_pk_fma_f32 v[224:225], v[14:15], v[220:221], v[224:225]
	v_pk_add_f32 v[222:223], v[222:223], v[224:225]
	s_nop 0
	v_add_f32_e32 v232, v222, v223
	v_cvt_pk_f32_fp8_e32 v[214:215], v172
	v_cvt_pk_f32_fp8_sdwa v[216:217], v172 src0_sel:WORD_1
	v_cvt_pk_f32_fp8_e32 v[218:219], v173
	v_cvt_pk_f32_fp8_sdwa v[220:221], v173 src0_sel:WORD_1
	v_pk_mul_f32 v[222:223], v[0:1], v[214:215]
	v_pk_mul_f32 v[224:225], v[2:3], v[216:217]
	v_cvt_pk_f32_fp8_e32 v[214:215], v174
	v_cvt_pk_f32_fp8_sdwa v[216:217], v174 src0_sel:WORD_1
	v_pk_fma_f32 v[222:223], v[4:5], v[218:219], v[222:223]
	v_pk_fma_f32 v[224:225], v[6:7], v[220:221], v[224:225]
	v_cvt_pk_f32_fp8_e32 v[218:219], v175
	v_cvt_pk_f32_fp8_sdwa v[220:221], v175 src0_sel:WORD_1
	v_pk_fma_f32 v[222:223], v[8:9], v[214:215], v[222:223]
	v_pk_fma_f32 v[224:225], v[10:11], v[216:217], v[224:225]
	v_pk_fma_f32 v[222:223], v[12:13], v[218:219], v[222:223]
	v_pk_fma_f32 v[224:225], v[14:15], v[220:221], v[224:225]
	v_pk_add_f32 v[222:223], v[222:223], v[224:225]
	s_nop 0
	v_add_f32_e32 v233, v222, v223
	v_permlane32_swap_b32_e32 v226, v230
	v_permlane32_swap_b32_e32 v227, v231
	v_permlane32_swap_b32_e32 v228, v232
	v_permlane32_swap_b32_e32 v229, v233
	v_add_f32_e32 v226, v226, v230
	v_add_f32_e32 v228, v228, v232
; template <bool STORE>
; DI void peer_item(const Params& p, int item, char* smem) {
;     ...
;       float part[8];
; #pragma unroll
;       for (int u = 0; u < 8; ++u) {
;         float d = 0.f;
; #pragma unroll
;         for (int i = 0; i < 4; ++i) {
;           f32x2_t lo = __builtin_amdgcn_cvt_pk_f32_fp8((int)uq[u][i], false);
;           f32x2_t hi = __builtin_amdgcn_cvt_pk_f32_fp8((int)uq[u][i], true);
;           d += xf[4 * i] * lo.x + xf[4 * i + 1] * lo.y + xf[4 * i + 2] * hi.x + xf[4 * i + 3] * hi.y;
;         }
;         part[u] = d;
;       }
;       float q4[4], r2[2], h;
; #pragma unroll
;       for (int j = 0; j < 4; ++j) {
;         float mine = b5 ? part[j + 4] : part[j];
;         float other = b5 ? part[j] : part[j + 4];
;         q4[j] = mine + __shfl_xor(other, 32);
;       }
; #pragma unroll
;       for (int j = 0; j < 2; ++j) {
;         float mine = b4 ? q4[j + 2] : q4[j];
;         float other = b4 ? q4[j] : q4[j + 2];
;         r2[j] = mine + __shfl_xor(other, 16);
;       }
;       {
;         float mine = b3 ? r2[1] : r2[0];
;         float other = b3 ? r2[0] : r2[1];
;         h = mine + __shfl_xor(other, 8);
;       }
;       h += __shfl_xor(h, 4);
;       h += __shfl_xor(h, 2);
;       h += __shfl_xor(h, 1);
	v_add_f32_e32 v227, v227, v231
	v_add_f32_e32 v229, v229, v233
	s_nop 1
	v_permlane16_swap_b32_e32 v226, v228
	v_permlane16_swap_b32_e32 v227, v229
	v_add_f32_e32 v226, v226, v228
	v_add_f32_e32 v227, v227, v229
	s_nop 0
	v_cndmask_b32_e64 v230, v226, v227, s[24:25]
	v_cndmask_b32_e64 v231, v227, v226, s[24:25]
	s_nop 1
	v_add_f32_dpp v232, v231, v230 row_ror:8 row_mask:0xf bank_mask:0xf
	s_nop 1
	v_add_f32_dpp v233, v232, v232 quad_perm:[1,0,3,2] row_mask:0xf bank_mask:0xf
	s_nop 1
	v_add_f32_dpp v232, v233, v233 quad_perm:[2,3,0,1] row_mask:0xf bank_mask:0xf
	s_nop 1
	v_add_f32_dpp v233, v232, v232 row_half_mirror row_mask:0xf bank_mask:0xf
	ds_write_b32 v235, v233 offset:32800
	v_readlane_b32 s48, v133, s72
	v_readlane_b32 s49, v133, s73
	v_readlane_b32 s50, v133, s74
	v_readlane_b32 s51, v133, s75
	v_readlane_b32 s52, v133, s76
	v_readlane_b32 s53, v133, s77
	v_readlane_b32 s54, v133, s78
	v_readlane_b32 s55, v133, s79
	s_add_u32 s32, s0, s48
	s_addc_u32 s33, s1, 0
	s_add_u32 s34, s0, s49
	s_addc_u32 s35, s1, 0
	s_add_u32 s36, s0, s50
	s_addc_u32 s37, s1, 0
	s_add_u32 s38, s0, s51
	s_addc_u32 s39, s1, 0
	s_add_u32 s40, s0, s52
	s_addc_u32 s41, s1, 0
	s_add_u32 s42, s0, s53
	s_addc_u32 s43, s1, 0
	s_add_u32 s44, s0, s54
	s_addc_u32 s45, s1, 0
	s_add_u32 s46, s0, s55
	s_addc_u32 s47, s1, 0
	global_load_dwordx4 v[144:147], v234, s[32:33]
	global_load_dwordx4 v[148:151], v234, s[34:35]
	global_load_dwordx4 v[152:155], v234, s[36:37]
	global_load_dwordx4 v[156:159], v234, s[38:39]
	global_load_dwordx4 v[160:163], v234, s[40:41]
	global_load_dwordx4 v[164:167], v234, s[42:43]
	global_load_dwordx4 v[168:171], v234, s[44:45]
	global_load_dwordx4 v[172:175], v234, s[46:47]
	s_waitcnt vmcnt(8)
	v_cvt_pk_f32_fp8_e32 v[214:215], v176
	v_cvt_pk_f32_fp8_sdwa v[216:217], v176 src0_sel:WORD_1
	v_cvt_pk_f32_fp8_e32 v[218:219], v177
	v_cvt_pk_f32_fp8_sdwa v[220:221], v177 src0_sel:WORD_1
	v_pk_mul_f32 v[222:223], v[16:17], v[214:215]
	v_pk_mul_f32 v[224:225], v[18:19], v[216:217]
	v_cvt_pk_f32_fp8_e32 v[214:215], v178
	v_cvt_pk_f32_fp8_sdwa v[216:217], v178 src0_sel:WORD_1
	v_pk_fma_f32 v[222:223], v[20:21], v[218:219], v[222:223]
	v_pk_fma_f32 v[224:225], v[22:23], v[220:221], v[224:225]
	v_cvt_pk_f32_fp8_e32 v[218:219], v179
	v_cvt_pk_f32_fp8_sdwa v[220:221], v179 src0_sel:WORD_1
	v_pk_fma_f32 v[222:223], v[24:25], v[214:215], v[222:223]
	v_pk_fma_f32 v[224:225], v[26:27], v[216:217], v[224:225]
	v_pk_fma_f32 v[222:223], v[28:29], v[218:219], v[222:223]
	v_pk_fma_f32 v[224:225], v[30:31], v[220:221], v[224:225]
	v_pk_add_f32 v[222:223], v[222:223], v[224:225]
	s_nop 0
	v_add_f32_e32 v226, v222, v223
	v_cvt_pk_f32_fp8_e32 v[214:215], v180
	v_cvt_pk_f32_fp8_sdwa v[216:217], v180 src0_sel:WORD_1
	v_cvt_pk_f32_fp8_e32 v[218:219], v181
	v_cvt_pk_f32_fp8_sdwa v[220:221], v181 src0_sel:WORD_1
	v_pk_mul_f32 v[222:223], v[16:17], v[214:215]
	v_pk_mul_f32 v[224:225], v[18:19], v[216:217]
	v_cvt_pk_f32_fp8_e32 v[214:215], v182
	v_cvt_pk_f32_fp8_sdwa v[216:217], v182 src0_sel:WORD_1
	v_pk_fma_f32 v[222:223], v[20:21], v[218:219], v[222:223]
	v_pk_fma_f32 v[224:225], v[22:23], v[220:221], v[224:225]
	v_cvt_pk_f32_fp8_e32 v[218:219], v183
	v_cvt_pk_f32_fp8_sdwa v[220:221], v183 src0_sel:WORD_1
	v_pk_fma_f32 v[222:223], v[24:25], v[214:215], v[222:223]
	v_pk_fma_f32 v[224:225], v[26:27], v[216:217], v[224:225]
	v_pk_fma_f32 v[222:223], v[28:29], v[218:219], v[222:223]
	v_pk_fma_f32 v[224:225], v[30:31], v[220:221], v[224:225]
	v_pk_add_f32 v[222:223], v[222:223], v[224:225]
	s_nop 0
	v_add_f32_e32 v227, v222, v223
	v_cvt_pk_f32_fp8_e32 v[214:215], v184
	v_cvt_pk_f32_fp8_sdwa v[216:217], v184 src0_sel:WORD_1
	v_cvt_pk_f32_fp8_e32 v[218:219], v185
	v_cvt_pk_f32_fp8_sdwa v[220:221], v185 src0_sel:WORD_1
	v_pk_mul_f32 v[222:223], v[16:17], v[214:215]
	v_pk_mul_f32 v[224:225], v[18:19], v[216:217]
	v_cvt_pk_f32_fp8_e32 v[214:215], v186
	v_cvt_pk_f32_fp8_sdwa v[216:217], v186 src0_sel:WORD_1
	v_pk_fma_f32 v[222:223], v[20:21], v[218:219], v[222:223]
	v_pk_fma_f32 v[224:225], v[22:23], v[220:221], v[224:225]
	v_cvt_pk_f32_fp8_e32 v[218:219], v187
	v_cvt_pk_f32_fp8_sdwa v[220:221], v187 src0_sel:WORD_1
	v_pk_fma_f32 v[222:223], v[24:25], v[214:215], v[222:223]
	v_pk_fma_f32 v[224:225], v[26:27], v[216:217], v[224:225]
	v_pk_fma_f32 v[222:223], v[28:29], v[218:219], v[222:223]
	v_pk_fma_f32 v[224:225], v[30:31], v[220:221], v[224:225]
	v_pk_add_f32 v[222:223], v[222:223], v[224:225]
	s_nop 0
	v_add_f32_e32 v228, v222, v223
	v_cvt_pk_f32_fp8_e32 v[214:215], v188
	v_cvt_pk_f32_fp8_sdwa v[216:217], v188 src0_sel:WORD_1
	v_cvt_pk_f32_fp8_e32 v[218:219], v189
	v_cvt_pk_f32_fp8_sdwa v[220:221], v189 src0_sel:WORD_1
	v_pk_mul_f32 v[222:223], v[16:17], v[214:215]
	v_pk_mul_f32 v[224:225], v[18:19], v[216:217]
	v_cvt_pk_f32_fp8_e32 v[214:215], v190
	v_cvt_pk_f32_fp8_sdwa v[216:217], v190 src0_sel:WORD_1
	v_pk_fma_f32 v[222:223], v[20:21], v[218:219], v[222:223]
	v_pk_fma_f32 v[224:225], v[22:23], v[220:221], v[224:225]
	v_cvt_pk_f32_fp8_e32 v[218:219], v191
	v_cvt_pk_f32_fp8_sdwa v[220:221], v191 src0_sel:WORD_1
	v_pk_fma_f32 v[222:223], v[24:25], v[214:215], v[222:223]
	v_pk_fma_f32 v[224:225], v[26:27], v[216:217], v[224:225]
	v_pk_fma_f32 v[222:223], v[28:29], v[218:219], v[222:223]
	v_pk_fma_f32 v[224:225], v[30:31], v[220:221], v[224:225]
	v_pk_add_f32 v[222:223], v[222:223], v[224:225]
	s_nop 0
	v_add_f32_e32 v229, v222, v223
	v_cvt_pk_f32_fp8_e32 v[214:215], v192
	v_cvt_pk_f32_fp8_sdwa v[216:217], v192 src0_sel:WORD_1
	v_cvt_pk_f32_fp8_e32 v[218:219], v193
	v_cvt_pk_f32_fp8_sdwa v[220:221], v193 src0_sel:WORD_1
	v_pk_mul_f32 v[222:223], v[16:17], v[214:215]
; template <bool STORE>
; DI void peer_item(const Params& p, int item, char* smem) {
;     ...
;       float part[8];
; #pragma unroll
;       for (int u = 0; u < 8; ++u) {
;         float d = 0.f;
; #pragma unroll
;         for (int i = 0; i < 4; ++i) {
;           f32x2_t lo = __builtin_amdgcn_cvt_pk_f32_fp8((int)uq[u][i], false);
;           f32x2_t hi = __builtin_amdgcn_cvt_pk_f32_fp8((int)uq[u][i], true);
;           d += xf[4 * i] * lo.x + xf[4 * i + 1] * lo.y + xf[4 * i + 2] * hi.x + xf[4 * i + 3] * hi.y;
;         }
;         part[u] = d;
;       }
;       float q4[4], r2[2], h;
; #pragma unroll
;       for (int j = 0; j < 4; ++j) {
;         float mine = b5 ? part[j + 4] : part[j];
;         float other = b5 ? part[j] : part[j + 4];
;         q4[j] = mine + __shfl_xor(other, 32);
;       }
; #pragma unroll
;       for (int j = 0; j < 2; ++j) {
;         float mine = b4 ? q4[j + 2] : q4[j];
;         float other = b4 ? q4[j] : q4[j + 2];
;         r2[j] = mine + __shfl_xor(other, 16);
;       }
;       {
;         float mine = b3 ? r2[1] : r2[0];
;         float other = b3 ? r2[0] : r2[1];
;         h = mine + __shfl_xor(other, 8);
;       }
;       h += __shfl_xor(h, 4);
;       h += __shfl_xor(h, 2);
;       h += __shfl_xor(h, 1);
	v_pk_mul_f32 v[224:225], v[18:19], v[216:217]
	v_cvt_pk_f32_fp8_e32 v[214:215], v194
	v_cvt_pk_f32_fp8_sdwa v[216:217], v194 src0_sel:WORD_1
	v_pk_fma_f32 v[222:223], v[20:21], v[218:219], v[222:223]
	v_pk_fma_f32 v[224:225], v[22:23], v[220:221], v[224:225]
	v_cvt_pk_f32_fp8_e32 v[218:219], v195
	v_cvt_pk_f32_fp8_sdwa v[220:221], v195 src0_sel:WORD_1
	v_pk_fma_f32 v[222:223], v[24:25], v[214:215], v[222:223]
	v_pk_fma_f32 v[224:225], v[26:27], v[216:217], v[224:225]
	v_pk_fma_f32 v[222:223], v[28:29], v[218:219], v[222:223]
	v_pk_fma_f32 v[224:225], v[30:31], v[220:221], v[224:225]
	v_pk_add_f32 v[222:223], v[222:223], v[224:225]
	s_nop 0
	v_add_f32_e32 v230, v222, v223
	v_cvt_pk_f32_fp8_e32 v[214:215], v196
	v_cvt_pk_f32_fp8_sdwa v[216:217], v196 src0_sel:WORD_1
	v_cvt_pk_f32_fp8_e32 v[218:219], v197
	v_cvt_pk_f32_fp8_sdwa v[220:221], v197 src0_sel:WORD_1
	v_pk_mul_f32 v[222:223], v[16:17], v[214:215]
	v_pk_mul_f32 v[224:225], v[18:19], v[216:217]
	v_cvt_pk_f32_fp8_e32 v[214:215], v198
	v_cvt_pk_f32_fp8_sdwa v[216:217], v198 src0_sel:WORD_1
	v_pk_fma_f32 v[222:223], v[20:21], v[218:219], v[222:223]
	v_pk_fma_f32 v[224:225], v[22:23], v[220:221], v[224:225]
	v_cvt_pk_f32_fp8_e32 v[218:219], v199
	v_cvt_pk_f32_fp8_sdwa v[220:221], v199 src0_sel:WORD_1
	v_pk_fma_f32 v[222:223], v[24:25], v[214:215], v[222:223]
	v_pk_fma_f32 v[224:225], v[26:27], v[216:217], v[224:225]
	v_pk_fma_f32 v[222:223], v[28:29], v[218:219], v[222:223]
	v_pk_fma_f32 v[224:225], v[30:31], v[220:221], v[224:225]
	v_pk_add_f32 v[222:223], v[222:223], v[224:225]
	s_nop 0
	v_add_f32_e32 v231, v222, v223
	v_cvt_pk_f32_fp8_e32 v[214:215], v200
	v_cvt_pk_f32_fp8_sdwa v[216:217], v200 src0_sel:WORD_1
	v_cvt_pk_f32_fp8_e32 v[218:219], v201
	v_cvt_pk_f32_fp8_sdwa v[220:221], v201 src0_sel:WORD_1
	v_pk_mul_f32 v[222:223], v[16:17], v[214:215]
	v_pk_mul_f32 v[224:225], v[18:19], v[216:217]
	v_cvt_pk_f32_fp8_e32 v[214:215], v202
	v_cvt_pk_f32_fp8_sdwa v[216:217], v202 src0_sel:WORD_1
	v_pk_fma_f32 v[222:223], v[20:21], v[218:219], v[222:223]
	v_pk_fma_f32 v[224:225], v[22:23], v[220:221], v[224:225]
	v_cvt_pk_f32_fp8_e32 v[218:219], v203
	v_cvt_pk_f32_fp8_sdwa v[220:221], v203 src0_sel:WORD_1
	v_pk_fma_f32 v[222:223], v[24:25], v[214:215], v[222:223]
	v_pk_fma_f32 v[224:225], v[26:27], v[216:217], v[224:225]
	v_pk_fma_f32 v[222:223], v[28:29], v[218:219], v[222:223]
	v_pk_fma_f32 v[224:225], v[30:31], v[220:221], v[224:225]
	v_pk_add_f32 v[222:223], v[222:223], v[224:225]
	s_nop 0
	v_add_f32_e32 v232, v222, v223
	v_cvt_pk_f32_fp8_e32 v[214:215], v204
	v_cvt_pk_f32_fp8_sdwa v[216:217], v204 src0_sel:WORD_1
	v_cvt_pk_f32_fp8_e32 v[218:219], v205
	v_cvt_pk_f32_fp8_sdwa v[220:221], v205 src0_sel:WORD_1
	v_pk_mul_f32 v[222:223], v[16:17], v[214:215]
	v_pk_mul_f32 v[224:225], v[18:19], v[216:217]
	v_cvt_pk_f32_fp8_e32 v[214:215], v206
	v_cvt_pk_f32_fp8_sdwa v[216:217], v206 src0_sel:WORD_1
	v_pk_fma_f32 v[222:223], v[20:21], v[218:219], v[222:223]
	v_pk_fma_f32 v[224:225], v[22:23], v[220:221], v[224:225]
	v_cvt_pk_f32_fp8_e32 v[218:219], v207
	v_cvt_pk_f32_fp8_sdwa v[220:221], v207 src0_sel:WORD_1
	v_pk_fma_f32 v[222:223], v[24:25], v[214:215], v[222:223]
	v_pk_fma_f32 v[224:225], v[26:27], v[216:217], v[224:225]
	v_pk_fma_f32 v[222:223], v[28:29], v[218:219], v[222:223]
	v_pk_fma_f32 v[224:225], v[30:31], v[220:221], v[224:225]
	v_pk_add_f32 v[222:223], v[222:223], v[224:225]
	s_nop 0
	v_add_f32_e32 v233, v222, v223
	v_permlane32_swap_b32_e32 v226, v230
	v_permlane32_swap_b32_e32 v227, v231
	v_permlane32_swap_b32_e32 v228, v232
	v_permlane32_swap_b32_e32 v229, v233
	v_add_f32_e32 v226, v226, v230
	v_add_f32_e32 v228, v228, v232
	v_add_f32_e32 v227, v227, v231
	v_add_f32_e32 v229, v229, v233
	s_nop 1
	v_permlane16_swap_b32_e32 v226, v228
	v_permlane16_swap_b32_e32 v227, v229
	v_add_f32_e32 v226, v226, v228
	v_add_f32_e32 v227, v227, v229
	s_nop 0
	v_cndmask_b32_e64 v230, v226, v227, s[24:25]
	v_cndmask_b32_e64 v231, v227, v226, s[24:25]
	s_nop 1
	v_add_f32_dpp v232, v231, v230 row_ror:8 row_mask:0xf bank_mask:0xf
	s_nop 1
	v_add_f32_dpp v233, v232, v232 quad_perm:[1,0,3,2] row_mask:0xf bank_mask:0xf
	s_nop 1
	v_add_f32_dpp v232, v233, v233 quad_perm:[2,3,0,1] row_mask:0xf bank_mask:0xf
	s_nop 1
	v_add_f32_dpp v233, v232, v232 row_half_mirror row_mask:0xf bank_mask:0xf
	ds_write_b32 v235, v233 offset:33312
	v_readlane_b32 s48, v135, s72
	v_readlane_b32 s49, v135, s73
	v_readlane_b32 s50, v135, s74
	v_readlane_b32 s51, v135, s75
	v_readlane_b32 s52, v135, s76
	v_readlane_b32 s53, v135, s77
	v_readlane_b32 s54, v135, s78
	v_readlane_b32 s55, v135, s79
	s_add_u32 s32, s0, s48
	s_addc_u32 s33, s1, 0
	s_add_u32 s34, s0, s49
	s_addc_u32 s35, s1, 0
	s_add_u32 s36, s0, s50
	s_addc_u32 s37, s1, 0
	s_add_u32 s38, s0, s51
	s_addc_u32 s39, s1, 0
	s_add_u32 s40, s0, s52
	s_addc_u32 s41, s1, 0
	s_add_u32 s42, s0, s53
	s_addc_u32 s43, s1, 0
	s_add_u32 s44, s0, s54
	s_addc_u32 s45, s1, 0
	s_add_u32 s46, s0, s55
	s_addc_u32 s47, s1, 0
	global_load_dwordx4 v[176:179], v234, s[32:33]
	global_load_dwordx4 v[180:183], v234, s[34:35]
	global_load_dwordx4 v[184:187], v234, s[36:37]
	global_load_dwordx4 v[188:191], v234, s[38:39]
	global_load_dwordx4 v[192:195], v234, s[40:41]
	global_load_dwordx4 v[196:199], v234, s[42:43]
	global_load_dwordx4 v[200:203], v234, s[44:45]
	global_load_dwordx4 v[204:207], v234, s[46:47]
	s_waitcnt vmcnt(8)
; template <bool STORE>
; DI void peer_item(const Params& p, int item, char* smem) {
;     ...
;       float part[8];
; #pragma unroll
;       for (int u = 0; u < 8; ++u) {
;         float d = 0.f;
; #pragma unroll
;         for (int i = 0; i < 4; ++i) {
;           f32x2_t lo = __builtin_amdgcn_cvt_pk_f32_fp8((int)uq[u][i], false);
;           f32x2_t hi = __builtin_amdgcn_cvt_pk_f32_fp8((int)uq[u][i], true);
;           d += xf[4 * i] * lo.x + xf[4 * i + 1] * lo.y + xf[4 * i + 2] * hi.x + xf[4 * i + 3] * hi.y;
;         }
;         part[u] = d;
;       }
	v_cvt_pk_f32_fp8_e32 v[214:215], v144
	v_cvt_pk_f32_fp8_sdwa v[216:217], v144 src0_sel:WORD_1
	v_cvt_pk_f32_fp8_e32 v[218:219], v145
	v_cvt_pk_f32_fp8_sdwa v[220:221], v145 src0_sel:WORD_1
	v_pk_mul_f32 v[222:223], v[32:33], v[214:215]
	v_pk_mul_f32 v[224:225], v[34:35], v[216:217]
	v_cvt_pk_f32_fp8_e32 v[214:215], v146
	v_cvt_pk_f32_fp8_sdwa v[216:217], v146 src0_sel:WORD_1
	v_pk_fma_f32 v[222:223], v[36:37], v[218:219], v[222:223]
	v_pk_fma_f32 v[224:225], v[38:39], v[220:221], v[224:225]
	v_cvt_pk_f32_fp8_e32 v[218:219], v147
	v_cvt_pk_f32_fp8_sdwa v[220:221], v147 src0_sel:WORD_1
	v_pk_fma_f32 v[222:223], v[40:41], v[214:215], v[222:223]
	v_pk_fma_f32 v[224:225], v[42:43], v[216:217], v[224:225]
	v_pk_fma_f32 v[222:223], v[44:45], v[218:219], v[222:223]
	v_pk_fma_f32 v[224:225], v[46:47], v[220:221], v[224:225]
	v_pk_add_f32 v[222:223], v[222:223], v[224:225]
	s_nop 0
	v_add_f32_e32 v226, v222, v223
	v_cvt_pk_f32_fp8_e32 v[214:215], v148
	v_cvt_pk_f32_fp8_sdwa v[216:217], v148 src0_sel:WORD_1
	v_cvt_pk_f32_fp8_e32 v[218:219], v149
	v_cvt_pk_f32_fp8_sdwa v[220:221], v149 src0_sel:WORD_1
	v_pk_mul_f32 v[222:223], v[32:33], v[214:215]
	v_pk_mul_f32 v[224:225], v[34:35], v[216:217]
	v_cvt_pk_f32_fp8_e32 v[214:215], v150
	v_cvt_pk_f32_fp8_sdwa v[216:217], v150 src0_sel:WORD_1
	v_pk_fma_f32 v[222:223], v[36:37], v[218:219], v[222:223]
	v_pk_fma_f32 v[224:225], v[38:39], v[220:221], v[224:225]
	v_cvt_pk_f32_fp8_e32 v[218:219], v151
	v_cvt_pk_f32_fp8_sdwa v[220:221], v151 src0_sel:WORD_1
	v_pk_fma_f32 v[222:223], v[40:41], v[214:215], v[222:223]
	v_pk_fma_f32 v[224:225], v[42:43], v[216:217], v[224:225]
	v_pk_fma_f32 v[222:223], v[44:45], v[218:219], v[222:223]
	v_pk_fma_f32 v[224:225], v[46:47], v[220:221], v[224:225]
	v_pk_add_f32 v[222:223], v[222:223], v[224:225]
	s_nop 0
	v_add_f32_e32 v227, v222, v223
	v_cvt_pk_f32_fp8_e32 v[214:215], v152
	v_cvt_pk_f32_fp8_sdwa v[216:217], v152 src0_sel:WORD_1
	v_cvt_pk_f32_fp8_e32 v[218:219], v153
	v_cvt_pk_f32_fp8_sdwa v[220:221], v153 src0_sel:WORD_1
	v_pk_mul_f32 v[222:223], v[32:33], v[214:215]
	v_pk_mul_f32 v[224:225], v[34:35], v[216:217]
	v_cvt_pk_f32_fp8_e32 v[214:215], v154
	v_cvt_pk_f32_fp8_sdwa v[216:217], v154 src0_sel:WORD_1
	v_pk_fma_f32 v[222:223], v[36:37], v[218:219], v[222:223]
	v_pk_fma_f32 v[224:225], v[38:39], v[220:221], v[224:225]
	v_cvt_pk_f32_fp8_e32 v[218:219], v155
	v_cvt_pk_f32_fp8_sdwa v[220:221], v155 src0_sel:WORD_1
	v_pk_fma_f32 v[222:223], v[40:41], v[214:215], v[222:223]
	v_pk_fma_f32 v[224:225], v[42:43], v[216:217], v[224:225]
	v_pk_fma_f32 v[222:223], v[44:45], v[218:219], v[222:223]
	v_pk_fma_f32 v[224:225], v[46:47], v[220:221], v[224:225]
	v_pk_add_f32 v[222:223], v[222:223], v[224:225]
	s_nop 0
	v_add_f32_e32 v228, v222, v223
	v_cvt_pk_f32_fp8_e32 v[214:215], v156
	v_cvt_pk_f32_fp8_sdwa v[216:217], v156 src0_sel:WORD_1
	v_cvt_pk_f32_fp8_e32 v[218:219], v157
	v_cvt_pk_f32_fp8_sdwa v[220:221], v157 src0_sel:WORD_1
	v_pk_mul_f32 v[222:223], v[32:33], v[214:215]
	v_pk_mul_f32 v[224:225], v[34:35], v[216:217]
	v_cvt_pk_f32_fp8_e32 v[214:215], v158
	v_cvt_pk_f32_fp8_sdwa v[216:217], v158 src0_sel:WORD_1
	v_pk_fma_f32 v[222:223], v[36:37], v[218:219], v[222:223]
	v_pk_fma_f32 v[224:225], v[38:39], v[220:221], v[224:225]
	v_cvt_pk_f32_fp8_e32 v[218:219], v159
	v_cvt_pk_f32_fp8_sdwa v[220:221], v159 src0_sel:WORD_1
	v_pk_fma_f32 v[222:223], v[40:41], v[214:215], v[222:223]
	v_pk_fma_f32 v[224:225], v[42:43], v[216:217], v[224:225]
	v_pk_fma_f32 v[222:223], v[44:45], v[218:219], v[222:223]
	v_pk_fma_f32 v[224:225], v[46:47], v[220:221], v[224:225]
	v_pk_add_f32 v[222:223], v[222:223], v[224:225]
	s_nop 0
	v_add_f32_e32 v229, v222, v223
	v_cvt_pk_f32_fp8_e32 v[214:215], v160
	v_cvt_pk_f32_fp8_sdwa v[216:217], v160 src0_sel:WORD_1
	v_cvt_pk_f32_fp8_e32 v[218:219], v161
	v_cvt_pk_f32_fp8_sdwa v[220:221], v161 src0_sel:WORD_1
	v_pk_mul_f32 v[222:223], v[32:33], v[214:215]
	v_pk_mul_f32 v[224:225], v[34:35], v[216:217]
	v_cvt_pk_f32_fp8_e32 v[214:215], v162
	v_cvt_pk_f32_fp8_sdwa v[216:217], v162 src0_sel:WORD_1
	v_pk_fma_f32 v[222:223], v[36:37], v[218:219], v[222:223]
	v_pk_fma_f32 v[224:225], v[38:39], v[220:221], v[224:225]
	v_cvt_pk_f32_fp8_e32 v[218:219], v163
	v_cvt_pk_f32_fp8_sdwa v[220:221], v163 src0_sel:WORD_1
	v_pk_fma_f32 v[222:223], v[40:41], v[214:215], v[222:223]
	v_pk_fma_f32 v[224:225], v[42:43], v[216:217], v[224:225]
	v_pk_fma_f32 v[222:223], v[44:45], v[218:219], v[222:223]
	v_pk_fma_f32 v[224:225], v[46:47], v[220:221], v[224:225]
	v_pk_add_f32 v[222:223], v[222:223], v[224:225]
	s_nop 0
	v_add_f32_e32 v230, v222, v223
	v_cvt_pk_f32_fp8_e32 v[214:215], v164
	v_cvt_pk_f32_fp8_sdwa v[216:217], v164 src0_sel:WORD_1
	v_cvt_pk_f32_fp8_e32 v[218:219], v165
	v_cvt_pk_f32_fp8_sdwa v[220:221], v165 src0_sel:WORD_1
	v_pk_mul_f32 v[222:223], v[32:33], v[214:215]
	v_pk_mul_f32 v[224:225], v[34:35], v[216:217]
	v_cvt_pk_f32_fp8_e32 v[214:215], v166
	v_cvt_pk_f32_fp8_sdwa v[216:217], v166 src0_sel:WORD_1
	v_pk_fma_f32 v[222:223], v[36:37], v[218:219], v[222:223]
	v_pk_fma_f32 v[224:225], v[38:39], v[220:221], v[224:225]
	v_cvt_pk_f32_fp8_e32 v[218:219], v167
	v_cvt_pk_f32_fp8_sdwa v[220:221], v167 src0_sel:WORD_1
	v_pk_fma_f32 v[222:223], v[40:41], v[214:215], v[222:223]
	v_pk_fma_f32 v[224:225], v[42:43], v[216:217], v[224:225]
	v_pk_fma_f32 v[222:223], v[44:45], v[218:219], v[222:223]
	v_pk_fma_f32 v[224:225], v[46:47], v[220:221], v[224:225]
	v_pk_add_f32 v[222:223], v[222:223], v[224:225]
	s_nop 0
	v_add_f32_e32 v231, v222, v223
	v_cvt_pk_f32_fp8_e32 v[214:215], v168
	v_cvt_pk_f32_fp8_sdwa v[216:217], v168 src0_sel:WORD_1
	v_cvt_pk_f32_fp8_e32 v[218:219], v169
; template <bool STORE>
; DI void peer_item(const Params& p, int item, char* smem) {
;     ...
; #pragma unroll
;       for (int u = 0; u < 8; ++u) {
;         float d = 0.f;
; #pragma unroll
;         for (int i = 0; i < 4; ++i) {
;           f32x2_t lo = __builtin_amdgcn_cvt_pk_f32_fp8((int)uq[u][i], false);
;           f32x2_t hi = __builtin_amdgcn_cvt_pk_f32_fp8((int)uq[u][i], true);
;           d += xf[4 * i] * lo.x + xf[4 * i + 1] * lo.y + xf[4 * i + 2] * hi.x + xf[4 * i + 3] * hi.y;
;         }
;         part[u] = d;
;       }
;       float q4[4], r2[2], h;
; #pragma unroll
;       for (int j = 0; j < 4; ++j) {
;         float mine = b5 ? part[j + 4] : part[j];
;         float other = b5 ? part[j] : part[j + 4];
;         q4[j] = mine + __shfl_xor(other, 32);
;       }
; #pragma unroll
;       for (int j = 0; j < 2; ++j) {
;         float mine = b4 ? q4[j + 2] : q4[j];
;         float other = b4 ? q4[j] : q4[j + 2];
;         r2[j] = mine + __shfl_xor(other, 16);
;       }
;       {
;         float mine = b3 ? r2[1] : r2[0];
;         float other = b3 ? r2[0] : r2[1];
;         h = mine + __shfl_xor(other, 8);
;       }
;       h += __shfl_xor(h, 4);
;       h += __shfl_xor(h, 2);
;       h += __shfl_xor(h, 1);
	v_cvt_pk_f32_fp8_sdwa v[220:221], v169 src0_sel:WORD_1
	v_pk_mul_f32 v[222:223], v[32:33], v[214:215]
	v_pk_mul_f32 v[224:225], v[34:35], v[216:217]
	v_cvt_pk_f32_fp8_e32 v[214:215], v170
	v_cvt_pk_f32_fp8_sdwa v[216:217], v170 src0_sel:WORD_1
	v_pk_fma_f32 v[222:223], v[36:37], v[218:219], v[222:223]
	v_pk_fma_f32 v[224:225], v[38:39], v[220:221], v[224:225]
	v_cvt_pk_f32_fp8_e32 v[218:219], v171
	v_cvt_pk_f32_fp8_sdwa v[220:221], v171 src0_sel:WORD_1
	v_pk_fma_f32 v[222:223], v[40:41], v[214:215], v[222:223]
	v_pk_fma_f32 v[224:225], v[42:43], v[216:217], v[224:225]
	v_pk_fma_f32 v[222:223], v[44:45], v[218:219], v[222:223]
	v_pk_fma_f32 v[224:225], v[46:47], v[220:221], v[224:225]
	v_pk_add_f32 v[222:223], v[222:223], v[224:225]
	s_nop 0
	v_add_f32_e32 v232, v222, v223
	v_cvt_pk_f32_fp8_e32 v[214:215], v172
	v_cvt_pk_f32_fp8_sdwa v[216:217], v172 src0_sel:WORD_1
	v_cvt_pk_f32_fp8_e32 v[218:219], v173
	v_cvt_pk_f32_fp8_sdwa v[220:221], v173 src0_sel:WORD_1
	v_pk_mul_f32 v[222:223], v[32:33], v[214:215]
	v_pk_mul_f32 v[224:225], v[34:35], v[216:217]
	v_cvt_pk_f32_fp8_e32 v[214:215], v174
	v_cvt_pk_f32_fp8_sdwa v[216:217], v174 src0_sel:WORD_1
	v_pk_fma_f32 v[222:223], v[36:37], v[218:219], v[222:223]
	v_pk_fma_f32 v[224:225], v[38:39], v[220:221], v[224:225]
	v_cvt_pk_f32_fp8_e32 v[218:219], v175
	v_cvt_pk_f32_fp8_sdwa v[220:221], v175 src0_sel:WORD_1
	v_pk_fma_f32 v[222:223], v[40:41], v[214:215], v[222:223]
	v_pk_fma_f32 v[224:225], v[42:43], v[216:217], v[224:225]
	v_pk_fma_f32 v[222:223], v[44:45], v[218:219], v[222:223]
	v_pk_fma_f32 v[224:225], v[46:47], v[220:221], v[224:225]
	v_pk_add_f32 v[222:223], v[222:223], v[224:225]
	s_nop 0
	v_add_f32_e32 v233, v222, v223
	v_permlane32_swap_b32_e32 v226, v230
	v_permlane32_swap_b32_e32 v227, v231
	v_permlane32_swap_b32_e32 v228, v232
	v_permlane32_swap_b32_e32 v229, v233
	v_add_f32_e32 v226, v226, v230
	v_add_f32_e32 v228, v228, v232
	v_add_f32_e32 v227, v227, v231
	v_add_f32_e32 v229, v229, v233
	s_nop 1
	v_permlane16_swap_b32_e32 v226, v228
	v_permlane16_swap_b32_e32 v227, v229
	v_add_f32_e32 v226, v226, v228
	v_add_f32_e32 v227, v227, v229
	s_nop 0
	v_cndmask_b32_e64 v230, v226, v227, s[24:25]
	v_cndmask_b32_e64 v231, v227, v226, s[24:25]
	s_nop 1
	v_add_f32_dpp v232, v231, v230 row_ror:8 row_mask:0xf bank_mask:0xf
	s_nop 1
	v_add_f32_dpp v233, v232, v232 quad_perm:[1,0,3,2] row_mask:0xf bank_mask:0xf
	s_nop 1
	v_add_f32_dpp v232, v233, v233 quad_perm:[2,3,0,1] row_mask:0xf bank_mask:0xf
	s_nop 1
	v_add_f32_dpp v233, v232, v232 row_half_mirror row_mask:0xf bank_mask:0xf
	ds_write_b32 v235, v233 offset:33824
	v_readlane_b32 s48, v137, s72
	v_readlane_b32 s49, v137, s73
	v_readlane_b32 s50, v137, s74
	v_readlane_b32 s51, v137, s75
	v_readlane_b32 s52, v137, s76
	v_readlane_b32 s53, v137, s77
	v_readlane_b32 s54, v137, s78
	v_readlane_b32 s55, v137, s79
	s_add_u32 s32, s0, s48
	s_addc_u32 s33, s1, 0
	s_add_u32 s34, s0, s49
	s_addc_u32 s35, s1, 0
	s_add_u32 s36, s0, s50
	s_addc_u32 s37, s1, 0
	s_add_u32 s38, s0, s51
	s_addc_u32 s39, s1, 0
	s_add_u32 s40, s0, s52
	s_addc_u32 s41, s1, 0
	s_add_u32 s42, s0, s53
	s_addc_u32 s43, s1, 0
	s_add_u32 s44, s0, s54
	s_addc_u32 s45, s1, 0
	s_add_u32 s46, s0, s55
	s_addc_u32 s47, s1, 0
	global_load_dwordx4 v[144:147], v234, s[32:33]
	global_load_dwordx4 v[148:151], v234, s[34:35]
	global_load_dwordx4 v[152:155], v234, s[36:37]
	global_load_dwordx4 v[156:159], v234, s[38:39]
	global_load_dwordx4 v[160:163], v234, s[40:41]
	global_load_dwordx4 v[164:167], v234, s[42:43]
	global_load_dwordx4 v[168:171], v234, s[44:45]
	global_load_dwordx4 v[172:175], v234, s[46:47]
	s_waitcnt vmcnt(8)
	v_cvt_pk_f32_fp8_e32 v[214:215], v176
	v_cvt_pk_f32_fp8_sdwa v[216:217], v176 src0_sel:WORD_1
	v_cvt_pk_f32_fp8_e32 v[218:219], v177
	v_cvt_pk_f32_fp8_sdwa v[220:221], v177 src0_sel:WORD_1
	v_pk_mul_f32 v[222:223], v[48:49], v[214:215]
	v_pk_mul_f32 v[224:225], v[50:51], v[216:217]
	v_cvt_pk_f32_fp8_e32 v[214:215], v178
	v_cvt_pk_f32_fp8_sdwa v[216:217], v178 src0_sel:WORD_1
	v_pk_fma_f32 v[222:223], v[52:53], v[218:219], v[222:223]
	v_pk_fma_f32 v[224:225], v[54:55], v[220:221], v[224:225]
	v_cvt_pk_f32_fp8_e32 v[218:219], v179
	v_cvt_pk_f32_fp8_sdwa v[220:221], v179 src0_sel:WORD_1
	v_pk_fma_f32 v[222:223], v[56:57], v[214:215], v[222:223]
	v_pk_fma_f32 v[224:225], v[58:59], v[216:217], v[224:225]
	v_pk_fma_f32 v[222:223], v[60:61], v[218:219], v[222:223]
	v_pk_fma_f32 v[224:225], v[62:63], v[220:221], v[224:225]
	v_pk_add_f32 v[222:223], v[222:223], v[224:225]
	s_nop 0
	v_add_f32_e32 v226, v222, v223
	v_cvt_pk_f32_fp8_e32 v[214:215], v180
	v_cvt_pk_f32_fp8_sdwa v[216:217], v180 src0_sel:WORD_1
	v_cvt_pk_f32_fp8_e32 v[218:219], v181
	v_cvt_pk_f32_fp8_sdwa v[220:221], v181 src0_sel:WORD_1
	v_pk_mul_f32 v[222:223], v[48:49], v[214:215]
	v_pk_mul_f32 v[224:225], v[50:51], v[216:217]
	v_cvt_pk_f32_fp8_e32 v[214:215], v182
	v_cvt_pk_f32_fp8_sdwa v[216:217], v182 src0_sel:WORD_1
	v_pk_fma_f32 v[222:223], v[52:53], v[218:219], v[222:223]
	v_pk_fma_f32 v[224:225], v[54:55], v[220:221], v[224:225]
	v_cvt_pk_f32_fp8_e32 v[218:219], v183
	v_cvt_pk_f32_fp8_sdwa v[220:221], v183 src0_sel:WORD_1
	v_pk_fma_f32 v[222:223], v[56:57], v[214:215], v[222:223]
	v_pk_fma_f32 v[224:225], v[58:59], v[216:217], v[224:225]
	v_pk_fma_f32 v[222:223], v[60:61], v[218:219], v[222:223]
	v_pk_fma_f32 v[224:225], v[62:63], v[220:221], v[224:225]
	v_pk_add_f32 v[222:223], v[222:223], v[224:225]
	s_nop 0
	v_add_f32_e32 v227, v222, v223
	v_cvt_pk_f32_fp8_e32 v[214:215], v184
	v_cvt_pk_f32_fp8_sdwa v[216:217], v184 src0_sel:WORD_1
	v_cvt_pk_f32_fp8_e32 v[218:219], v185
	v_cvt_pk_f32_fp8_sdwa v[220:221], v185 src0_sel:WORD_1
; template <bool STORE>
; DI void peer_item(const Params& p, int item, char* smem) {
;     ...
; #pragma unroll
;       for (int u = 0; u < 8; ++u) {
;         float d = 0.f;
; #pragma unroll
;         for (int i = 0; i < 4; ++i) {
;           f32x2_t lo = __builtin_amdgcn_cvt_pk_f32_fp8((int)uq[u][i], false);
;           f32x2_t hi = __builtin_amdgcn_cvt_pk_f32_fp8((int)uq[u][i], true);
;           d += xf[4 * i] * lo.x + xf[4 * i + 1] * lo.y + xf[4 * i + 2] * hi.x + xf[4 * i + 3] * hi.y;
;         }
;         part[u] = d;
;       }
;       float q4[4], r2[2], h;
; #pragma unroll
;       for (int j = 0; j < 4; ++j) {
;         float mine = b5 ? part[j + 4] : part[j];
;         float other = b5 ? part[j] : part[j + 4];
;         q4[j] = mine + __shfl_xor(other, 32);
;       }
; #pragma unroll
;       for (int j = 0; j < 2; ++j) {
;         float mine = b4 ? q4[j + 2] : q4[j];
;         float other = b4 ? q4[j] : q4[j + 2];
;         r2[j] = mine + __shfl_xor(other, 16);
;       }
;       {
;         float mine = b3 ? r2[1] : r2[0];
;         float other = b3 ? r2[0] : r2[1];
;         h = mine + __shfl_xor(other, 8);
;       }
;       h += __shfl_xor(h, 4);
;       h += __shfl_xor(h, 2);
;       h += __shfl_xor(h, 1);
	v_pk_mul_f32 v[222:223], v[48:49], v[214:215]
	v_pk_mul_f32 v[224:225], v[50:51], v[216:217]
	v_cvt_pk_f32_fp8_e32 v[214:215], v186
	v_cvt_pk_f32_fp8_sdwa v[216:217], v186 src0_sel:WORD_1
	v_pk_fma_f32 v[222:223], v[52:53], v[218:219], v[222:223]
	v_pk_fma_f32 v[224:225], v[54:55], v[220:221], v[224:225]
	v_cvt_pk_f32_fp8_e32 v[218:219], v187
	v_cvt_pk_f32_fp8_sdwa v[220:221], v187 src0_sel:WORD_1
	v_pk_fma_f32 v[222:223], v[56:57], v[214:215], v[222:223]
	v_pk_fma_f32 v[224:225], v[58:59], v[216:217], v[224:225]
	v_pk_fma_f32 v[222:223], v[60:61], v[218:219], v[222:223]
	v_pk_fma_f32 v[224:225], v[62:63], v[220:221], v[224:225]
	v_pk_add_f32 v[222:223], v[222:223], v[224:225]
	s_nop 0
	v_add_f32_e32 v228, v222, v223
	v_cvt_pk_f32_fp8_e32 v[214:215], v188
	v_cvt_pk_f32_fp8_sdwa v[216:217], v188 src0_sel:WORD_1
	v_cvt_pk_f32_fp8_e32 v[218:219], v189
	v_cvt_pk_f32_fp8_sdwa v[220:221], v189 src0_sel:WORD_1
	v_pk_mul_f32 v[222:223], v[48:49], v[214:215]
	v_pk_mul_f32 v[224:225], v[50:51], v[216:217]
	v_cvt_pk_f32_fp8_e32 v[214:215], v190
	v_cvt_pk_f32_fp8_sdwa v[216:217], v190 src0_sel:WORD_1
	v_pk_fma_f32 v[222:223], v[52:53], v[218:219], v[222:223]
	v_pk_fma_f32 v[224:225], v[54:55], v[220:221], v[224:225]
	v_cvt_pk_f32_fp8_e32 v[218:219], v191
	v_cvt_pk_f32_fp8_sdwa v[220:221], v191 src0_sel:WORD_1
	v_pk_fma_f32 v[222:223], v[56:57], v[214:215], v[222:223]
	v_pk_fma_f32 v[224:225], v[58:59], v[216:217], v[224:225]
	v_pk_fma_f32 v[222:223], v[60:61], v[218:219], v[222:223]
	v_pk_fma_f32 v[224:225], v[62:63], v[220:221], v[224:225]
	v_pk_add_f32 v[222:223], v[222:223], v[224:225]
	s_nop 0
	v_add_f32_e32 v229, v222, v223
	v_cvt_pk_f32_fp8_e32 v[214:215], v192
	v_cvt_pk_f32_fp8_sdwa v[216:217], v192 src0_sel:WORD_1
	v_cvt_pk_f32_fp8_e32 v[218:219], v193
	v_cvt_pk_f32_fp8_sdwa v[220:221], v193 src0_sel:WORD_1
	v_pk_mul_f32 v[222:223], v[48:49], v[214:215]
	v_pk_mul_f32 v[224:225], v[50:51], v[216:217]
	v_cvt_pk_f32_fp8_e32 v[214:215], v194
	v_cvt_pk_f32_fp8_sdwa v[216:217], v194 src0_sel:WORD_1
	v_pk_fma_f32 v[222:223], v[52:53], v[218:219], v[222:223]
	v_pk_fma_f32 v[224:225], v[54:55], v[220:221], v[224:225]
	v_cvt_pk_f32_fp8_e32 v[218:219], v195
	v_cvt_pk_f32_fp8_sdwa v[220:221], v195 src0_sel:WORD_1
	v_pk_fma_f32 v[222:223], v[56:57], v[214:215], v[222:223]
	v_pk_fma_f32 v[224:225], v[58:59], v[216:217], v[224:225]
	v_pk_fma_f32 v[222:223], v[60:61], v[218:219], v[222:223]
	v_pk_fma_f32 v[224:225], v[62:63], v[220:221], v[224:225]
	v_pk_add_f32 v[222:223], v[222:223], v[224:225]
	s_nop 0
	v_add_f32_e32 v230, v222, v223
	v_cvt_pk_f32_fp8_e32 v[214:215], v196
	v_cvt_pk_f32_fp8_sdwa v[216:217], v196 src0_sel:WORD_1
	v_cvt_pk_f32_fp8_e32 v[218:219], v197
	v_cvt_pk_f32_fp8_sdwa v[220:221], v197 src0_sel:WORD_1
	v_pk_mul_f32 v[222:223], v[48:49], v[214:215]
	v_pk_mul_f32 v[224:225], v[50:51], v[216:217]
	v_cvt_pk_f32_fp8_e32 v[214:215], v198
	v_cvt_pk_f32_fp8_sdwa v[216:217], v198 src0_sel:WORD_1
	v_pk_fma_f32 v[222:223], v[52:53], v[218:219], v[222:223]
	v_pk_fma_f32 v[224:225], v[54:55], v[220:221], v[224:225]
	v_cvt_pk_f32_fp8_e32 v[218:219], v199
	v_cvt_pk_f32_fp8_sdwa v[220:221], v199 src0_sel:WORD_1
	v_pk_fma_f32 v[222:223], v[56:57], v[214:215], v[222:223]
	v_pk_fma_f32 v[224:225], v[58:59], v[216:217], v[224:225]
	v_pk_fma_f32 v[222:223], v[60:61], v[218:219], v[222:223]
	v_pk_fma_f32 v[224:225], v[62:63], v[220:221], v[224:225]
	v_pk_add_f32 v[222:223], v[222:223], v[224:225]
	s_nop 0
	v_add_f32_e32 v231, v222, v223
	v_cvt_pk_f32_fp8_e32 v[214:215], v200
	v_cvt_pk_f32_fp8_sdwa v[216:217], v200 src0_sel:WORD_1
	v_cvt_pk_f32_fp8_e32 v[218:219], v201
	v_cvt_pk_f32_fp8_sdwa v[220:221], v201 src0_sel:WORD_1
	v_pk_mul_f32 v[222:223], v[48:49], v[214:215]
	v_pk_mul_f32 v[224:225], v[50:51], v[216:217]
	v_cvt_pk_f32_fp8_e32 v[214:215], v202
	v_cvt_pk_f32_fp8_sdwa v[216:217], v202 src0_sel:WORD_1
	v_pk_fma_f32 v[222:223], v[52:53], v[218:219], v[222:223]
	v_pk_fma_f32 v[224:225], v[54:55], v[220:221], v[224:225]
	v_cvt_pk_f32_fp8_e32 v[218:219], v203
	v_cvt_pk_f32_fp8_sdwa v[220:221], v203 src0_sel:WORD_1
	v_pk_fma_f32 v[222:223], v[56:57], v[214:215], v[222:223]
	v_pk_fma_f32 v[224:225], v[58:59], v[216:217], v[224:225]
	v_pk_fma_f32 v[222:223], v[60:61], v[218:219], v[222:223]
	v_pk_fma_f32 v[224:225], v[62:63], v[220:221], v[224:225]
	v_pk_add_f32 v[222:223], v[222:223], v[224:225]
	s_nop 0
	v_add_f32_e32 v232, v222, v223
	v_cvt_pk_f32_fp8_e32 v[214:215], v204
	v_cvt_pk_f32_fp8_sdwa v[216:217], v204 src0_sel:WORD_1
	v_cvt_pk_f32_fp8_e32 v[218:219], v205
	v_cvt_pk_f32_fp8_sdwa v[220:221], v205 src0_sel:WORD_1
	v_pk_mul_f32 v[222:223], v[48:49], v[214:215]
	v_pk_mul_f32 v[224:225], v[50:51], v[216:217]
	v_cvt_pk_f32_fp8_e32 v[214:215], v206
	v_cvt_pk_f32_fp8_sdwa v[216:217], v206 src0_sel:WORD_1
	v_pk_fma_f32 v[222:223], v[52:53], v[218:219], v[222:223]
	v_pk_fma_f32 v[224:225], v[54:55], v[220:221], v[224:225]
	v_cvt_pk_f32_fp8_e32 v[218:219], v207
	v_cvt_pk_f32_fp8_sdwa v[220:221], v207 src0_sel:WORD_1
	v_pk_fma_f32 v[222:223], v[56:57], v[214:215], v[222:223]
	v_pk_fma_f32 v[224:225], v[58:59], v[216:217], v[224:225]
	v_pk_fma_f32 v[222:223], v[60:61], v[218:219], v[222:223]
	v_pk_fma_f32 v[224:225], v[62:63], v[220:221], v[224:225]
	v_pk_add_f32 v[222:223], v[222:223], v[224:225]
	s_nop 0
	v_add_f32_e32 v233, v222, v223
	v_permlane32_swap_b32_e32 v226, v230
	v_permlane32_swap_b32_e32 v227, v231
	v_permlane32_swap_b32_e32 v228, v232
	v_permlane32_swap_b32_e32 v229, v233
	v_add_f32_e32 v226, v226, v230
	v_add_f32_e32 v228, v228, v232
	v_add_f32_e32 v227, v227, v231
	v_add_f32_e32 v229, v229, v233
	s_nop 1
	v_permlane16_swap_b32_e32 v226, v228
; template <bool STORE>
; DI void peer_item(const Params& p, int item, char* smem) {
;     ...
; #pragma unroll
;       for (int u = 0; u < 8; ++u) {
;         int e = e_s[tl * 128 + k + u];
;         uq[u] = *(const u32x4*)(U8 + (size_t)e * 1024 + lane * 16);
;     ...
;       for (int j = 0; j < 4; ++j) {
;         float mine = b5 ? part[j + 4] : part[j];
;         float other = b5 ? part[j] : part[j + 4];
;         q4[j] = mine + __shfl_xor(other, 32);
;       }
; #pragma unroll
;       for (int j = 0; j < 2; ++j) {
;         float mine = b4 ? q4[j + 2] : q4[j];
;         float other = b4 ? q4[j] : q4[j + 2];
;         r2[j] = mine + __shfl_xor(other, 16);
;       }
;       {
;         float mine = b3 ? r2[1] : r2[0];
;         float other = b3 ? r2[0] : r2[1];
;         h = mine + __shfl_xor(other, 8);
;       }
;       h += __shfl_xor(h, 4);
;       h += __shfl_xor(h, 2);
;       h += __shfl_xor(h, 1);
	v_permlane16_swap_b32_e32 v227, v229
	v_add_f32_e32 v226, v226, v228
	v_add_f32_e32 v227, v227, v229
	s_nop 0
	v_cndmask_b32_e64 v230, v226, v227, s[24:25]
	v_cndmask_b32_e64 v231, v227, v226, s[24:25]
	s_nop 1
	v_add_f32_dpp v232, v231, v230 row_ror:8 row_mask:0xf bank_mask:0xf
	s_nop 1
	v_add_f32_dpp v233, v232, v232 quad_perm:[1,0,3,2] row_mask:0xf bank_mask:0xf
	s_nop 1
	v_add_f32_dpp v232, v233, v233 quad_perm:[2,3,0,1] row_mask:0xf bank_mask:0xf
	s_nop 1
	v_add_f32_dpp v233, v232, v232 row_half_mirror row_mask:0xf bank_mask:0xf
	ds_write_b32 v235, v233 offset:34336
	v_readlane_b32 s48, v139, s72
	v_readlane_b32 s49, v139, s73
	v_readlane_b32 s50, v139, s74
	v_readlane_b32 s51, v139, s75
	v_readlane_b32 s52, v139, s76
	v_readlane_b32 s53, v139, s77
	v_readlane_b32 s54, v139, s78
	v_readlane_b32 s55, v139, s79
	s_add_u32 s32, s0, s48
	s_addc_u32 s33, s1, 0
	s_add_u32 s34, s0, s49
	s_addc_u32 s35, s1, 0
	s_add_u32 s36, s0, s50
	s_addc_u32 s37, s1, 0
	s_add_u32 s38, s0, s51
	s_addc_u32 s39, s1, 0
	s_add_u32 s40, s0, s52
	s_addc_u32 s41, s1, 0
	s_add_u32 s42, s0, s53
	s_addc_u32 s43, s1, 0
	s_add_u32 s44, s0, s54
	s_addc_u32 s45, s1, 0
	s_add_u32 s46, s0, s55
	s_addc_u32 s47, s1, 0
	global_load_dwordx4 v[176:179], v234, s[32:33]
	global_load_dwordx4 v[180:183], v234, s[34:35]
	global_load_dwordx4 v[184:187], v234, s[36:37]
	global_load_dwordx4 v[188:191], v234, s[38:39]
	global_load_dwordx4 v[192:195], v234, s[40:41]
	global_load_dwordx4 v[196:199], v234, s[42:43]
	global_load_dwordx4 v[200:203], v234, s[44:45]
	global_load_dwordx4 v[204:207], v234, s[46:47]
	s_waitcnt vmcnt(8)
	v_cvt_pk_f32_fp8_e32 v[214:215], v144
	v_cvt_pk_f32_fp8_sdwa v[216:217], v144 src0_sel:WORD_1
	v_cvt_pk_f32_fp8_e32 v[218:219], v145
	v_cvt_pk_f32_fp8_sdwa v[220:221], v145 src0_sel:WORD_1
	v_pk_mul_f32 v[222:223], v[64:65], v[214:215]
	v_pk_mul_f32 v[224:225], v[66:67], v[216:217]
	v_cvt_pk_f32_fp8_e32 v[214:215], v146
	v_cvt_pk_f32_fp8_sdwa v[216:217], v146 src0_sel:WORD_1
	v_pk_fma_f32 v[222:223], v[68:69], v[218:219], v[222:223]
	v_pk_fma_f32 v[224:225], v[70:71], v[220:221], v[224:225]
	v_cvt_pk_f32_fp8_e32 v[218:219], v147
	v_cvt_pk_f32_fp8_sdwa v[220:221], v147 src0_sel:WORD_1
	v_pk_fma_f32 v[222:223], v[72:73], v[214:215], v[222:223]
	v_pk_fma_f32 v[224:225], v[74:75], v[216:217], v[224:225]
	v_pk_fma_f32 v[222:223], v[76:77], v[218:219], v[222:223]
	v_pk_fma_f32 v[224:225], v[78:79], v[220:221], v[224:225]
	v_pk_add_f32 v[222:223], v[222:223], v[224:225]
	s_nop 0
	v_add_f32_e32 v226, v222, v223
	v_cvt_pk_f32_fp8_e32 v[214:215], v148
	v_cvt_pk_f32_fp8_sdwa v[216:217], v148 src0_sel:WORD_1
	v_cvt_pk_f32_fp8_e32 v[218:219], v149
	v_cvt_pk_f32_fp8_sdwa v[220:221], v149 src0_sel:WORD_1
	v_pk_mul_f32 v[222:223], v[64:65], v[214:215]
	v_pk_mul_f32 v[224:225], v[66:67], v[216:217]
	v_cvt_pk_f32_fp8_e32 v[214:215], v150
	v_cvt_pk_f32_fp8_sdwa v[216:217], v150 src0_sel:WORD_1
	v_pk_fma_f32 v[222:223], v[68:69], v[218:219], v[222:223]
	v_pk_fma_f32 v[224:225], v[70:71], v[220:221], v[224:225]
	v_cvt_pk_f32_fp8_e32 v[218:219], v151
	v_cvt_pk_f32_fp8_sdwa v[220:221], v151 src0_sel:WORD_1
	v_pk_fma_f32 v[222:223], v[72:73], v[214:215], v[222:223]
	v_pk_fma_f32 v[224:225], v[74:75], v[216:217], v[224:225]
	v_pk_fma_f32 v[222:223], v[76:77], v[218:219], v[222:223]
	v_pk_fma_f32 v[224:225], v[78:79], v[220:221], v[224:225]
	v_pk_add_f32 v[222:223], v[222:223], v[224:225]
	s_nop 0
	v_add_f32_e32 v227, v222, v223
	v_cvt_pk_f32_fp8_e32 v[214:215], v152
	v_cvt_pk_f32_fp8_sdwa v[216:217], v152 src0_sel:WORD_1
	v_cvt_pk_f32_fp8_e32 v[218:219], v153
	v_cvt_pk_f32_fp8_sdwa v[220:221], v153 src0_sel:WORD_1
	v_pk_mul_f32 v[222:223], v[64:65], v[214:215]
	v_pk_mul_f32 v[224:225], v[66:67], v[216:217]
	v_cvt_pk_f32_fp8_e32 v[214:215], v154
	v_cvt_pk_f32_fp8_sdwa v[216:217], v154 src0_sel:WORD_1
	v_pk_fma_f32 v[222:223], v[68:69], v[218:219], v[222:223]
	v_pk_fma_f32 v[224:225], v[70:71], v[220:221], v[224:225]
	v_cvt_pk_f32_fp8_e32 v[218:219], v155
	v_cvt_pk_f32_fp8_sdwa v[220:221], v155 src0_sel:WORD_1
	v_pk_fma_f32 v[222:223], v[72:73], v[214:215], v[222:223]
	v_pk_fma_f32 v[224:225], v[74:75], v[216:217], v[224:225]
	v_pk_fma_f32 v[222:223], v[76:77], v[218:219], v[222:223]
	v_pk_fma_f32 v[224:225], v[78:79], v[220:221], v[224:225]
	v_pk_add_f32 v[222:223], v[222:223], v[224:225]
	s_nop 0
	v_add_f32_e32 v228, v222, v223
	v_cvt_pk_f32_fp8_e32 v[214:215], v156
	v_cvt_pk_f32_fp8_sdwa v[216:217], v156 src0_sel:WORD_1
	v_cvt_pk_f32_fp8_e32 v[218:219], v157
	v_cvt_pk_f32_fp8_sdwa v[220:221], v157 src0_sel:WORD_1
	v_pk_mul_f32 v[222:223], v[64:65], v[214:215]
	v_pk_mul_f32 v[224:225], v[66:67], v[216:217]
	v_cvt_pk_f32_fp8_e32 v[214:215], v158
	v_cvt_pk_f32_fp8_sdwa v[216:217], v158 src0_sel:WORD_1
	v_pk_fma_f32 v[222:223], v[68:69], v[218:219], v[222:223]
	v_pk_fma_f32 v[224:225], v[70:71], v[220:221], v[224:225]
	v_cvt_pk_f32_fp8_e32 v[218:219], v159
	v_cvt_pk_f32_fp8_sdwa v[220:221], v159 src0_sel:WORD_1
	v_pk_fma_f32 v[222:223], v[72:73], v[214:215], v[222:223]
	v_pk_fma_f32 v[224:225], v[74:75], v[216:217], v[224:225]
	v_pk_fma_f32 v[222:223], v[76:77], v[218:219], v[222:223]
	v_pk_fma_f32 v[224:225], v[78:79], v[220:221], v[224:225]
	v_pk_add_f32 v[222:223], v[222:223], v[224:225]
	s_nop 0
	v_add_f32_e32 v229, v222, v223
	v_cvt_pk_f32_fp8_e32 v[214:215], v160
	v_cvt_pk_f32_fp8_sdwa v[216:217], v160 src0_sel:WORD_1
	v_cvt_pk_f32_fp8_e32 v[218:219], v161
	v_cvt_pk_f32_fp8_sdwa v[220:221], v161 src0_sel:WORD_1
	v_pk_mul_f32 v[222:223], v[64:65], v[214:215]
	v_pk_mul_f32 v[224:225], v[66:67], v[216:217]
	v_cvt_pk_f32_fp8_e32 v[214:215], v162
	v_cvt_pk_f32_fp8_sdwa v[216:217], v162 src0_sel:WORD_1
; template <bool STORE>
; DI void peer_item(const Params& p, int item, char* smem) {
;     ...
;       for (int u = 0; u < 8; ++u) {
;         int e = e_s[tl * 128 + k + u];
;         uq[u] = *(const u32x4*)(U8 + (size_t)e * 1024 + lane * 16);
;       }
;       float part[8];
; #pragma unroll
;       for (int u = 0; u < 8; ++u) {
;         float d = 0.f;
; #pragma unroll
;         for (int i = 0; i < 4; ++i) {
;           f32x2_t lo = __builtin_amdgcn_cvt_pk_f32_fp8((int)uq[u][i], false);
;           f32x2_t hi = __builtin_amdgcn_cvt_pk_f32_fp8((int)uq[u][i], true);
;           d += xf[4 * i] * lo.x + xf[4 * i + 1] * lo.y + xf[4 * i + 2] * hi.x + xf[4 * i + 3] * hi.y;
;         }
;         part[u] = d;
;       }
;       float q4[4], r2[2], h;
; #pragma unroll
;       for (int j = 0; j < 4; ++j) {
;         float mine = b5 ? part[j + 4] : part[j];
;         float other = b5 ? part[j] : part[j + 4];
;         q4[j] = mine + __shfl_xor(other, 32);
;       }
; #pragma unroll
;       for (int j = 0; j < 2; ++j) {
;         float mine = b4 ? q4[j + 2] : q4[j];
;         float other = b4 ? q4[j] : q4[j + 2];
;         r2[j] = mine + __shfl_xor(other, 16);
;       }
;       {
;         float mine = b3 ? r2[1] : r2[0];
;         float other = b3 ? r2[0] : r2[1];
;         h = mine + __shfl_xor(other, 8);
;       }
;       h += __shfl_xor(h, 4);
;       h += __shfl_xor(h, 2);
;       h += __shfl_xor(h, 1);
	v_pk_fma_f32 v[222:223], v[68:69], v[218:219], v[222:223]
	v_pk_fma_f32 v[224:225], v[70:71], v[220:221], v[224:225]
	v_cvt_pk_f32_fp8_e32 v[218:219], v163
	v_cvt_pk_f32_fp8_sdwa v[220:221], v163 src0_sel:WORD_1
	v_pk_fma_f32 v[222:223], v[72:73], v[214:215], v[222:223]
	v_pk_fma_f32 v[224:225], v[74:75], v[216:217], v[224:225]
	v_pk_fma_f32 v[222:223], v[76:77], v[218:219], v[222:223]
	v_pk_fma_f32 v[224:225], v[78:79], v[220:221], v[224:225]
	v_pk_add_f32 v[222:223], v[222:223], v[224:225]
	s_nop 0
	v_add_f32_e32 v230, v222, v223
	v_cvt_pk_f32_fp8_e32 v[214:215], v164
	v_cvt_pk_f32_fp8_sdwa v[216:217], v164 src0_sel:WORD_1
	v_cvt_pk_f32_fp8_e32 v[218:219], v165
	v_cvt_pk_f32_fp8_sdwa v[220:221], v165 src0_sel:WORD_1
	v_pk_mul_f32 v[222:223], v[64:65], v[214:215]
	v_pk_mul_f32 v[224:225], v[66:67], v[216:217]
	v_cvt_pk_f32_fp8_e32 v[214:215], v166
	v_cvt_pk_f32_fp8_sdwa v[216:217], v166 src0_sel:WORD_1
	v_pk_fma_f32 v[222:223], v[68:69], v[218:219], v[222:223]
	v_pk_fma_f32 v[224:225], v[70:71], v[220:221], v[224:225]
	v_cvt_pk_f32_fp8_e32 v[218:219], v167
	v_cvt_pk_f32_fp8_sdwa v[220:221], v167 src0_sel:WORD_1
	v_pk_fma_f32 v[222:223], v[72:73], v[214:215], v[222:223]
	v_pk_fma_f32 v[224:225], v[74:75], v[216:217], v[224:225]
	v_pk_fma_f32 v[222:223], v[76:77], v[218:219], v[222:223]
	v_pk_fma_f32 v[224:225], v[78:79], v[220:221], v[224:225]
	v_pk_add_f32 v[222:223], v[222:223], v[224:225]
	s_nop 0
	v_add_f32_e32 v231, v222, v223
	v_cvt_pk_f32_fp8_e32 v[214:215], v168
	v_cvt_pk_f32_fp8_sdwa v[216:217], v168 src0_sel:WORD_1
	v_cvt_pk_f32_fp8_e32 v[218:219], v169
	v_cvt_pk_f32_fp8_sdwa v[220:221], v169 src0_sel:WORD_1
	v_pk_mul_f32 v[222:223], v[64:65], v[214:215]
	v_pk_mul_f32 v[224:225], v[66:67], v[216:217]
	v_cvt_pk_f32_fp8_e32 v[214:215], v170
	v_cvt_pk_f32_fp8_sdwa v[216:217], v170 src0_sel:WORD_1
	v_pk_fma_f32 v[222:223], v[68:69], v[218:219], v[222:223]
	v_pk_fma_f32 v[224:225], v[70:71], v[220:221], v[224:225]
	v_cvt_pk_f32_fp8_e32 v[218:219], v171
	v_cvt_pk_f32_fp8_sdwa v[220:221], v171 src0_sel:WORD_1
	v_pk_fma_f32 v[222:223], v[72:73], v[214:215], v[222:223]
	v_pk_fma_f32 v[224:225], v[74:75], v[216:217], v[224:225]
	v_pk_fma_f32 v[222:223], v[76:77], v[218:219], v[222:223]
	v_pk_fma_f32 v[224:225], v[78:79], v[220:221], v[224:225]
	v_pk_add_f32 v[222:223], v[222:223], v[224:225]
	s_nop 0
	v_add_f32_e32 v232, v222, v223
	v_cvt_pk_f32_fp8_e32 v[214:215], v172
	v_cvt_pk_f32_fp8_sdwa v[216:217], v172 src0_sel:WORD_1
	v_cvt_pk_f32_fp8_e32 v[218:219], v173
	v_cvt_pk_f32_fp8_sdwa v[220:221], v173 src0_sel:WORD_1
	v_pk_mul_f32 v[222:223], v[64:65], v[214:215]
	v_pk_mul_f32 v[224:225], v[66:67], v[216:217]
	v_cvt_pk_f32_fp8_e32 v[214:215], v174
	v_cvt_pk_f32_fp8_sdwa v[216:217], v174 src0_sel:WORD_1
	v_pk_fma_f32 v[222:223], v[68:69], v[218:219], v[222:223]
	v_pk_fma_f32 v[224:225], v[70:71], v[220:221], v[224:225]
	v_cvt_pk_f32_fp8_e32 v[218:219], v175
	v_cvt_pk_f32_fp8_sdwa v[220:221], v175 src0_sel:WORD_1
	v_pk_fma_f32 v[222:223], v[72:73], v[214:215], v[222:223]
	v_pk_fma_f32 v[224:225], v[74:75], v[216:217], v[224:225]
	v_pk_fma_f32 v[222:223], v[76:77], v[218:219], v[222:223]
	v_pk_fma_f32 v[224:225], v[78:79], v[220:221], v[224:225]
	v_pk_add_f32 v[222:223], v[222:223], v[224:225]
	s_nop 0
	v_add_f32_e32 v233, v222, v223
	v_permlane32_swap_b32_e32 v226, v230
	v_permlane32_swap_b32_e32 v227, v231
	v_permlane32_swap_b32_e32 v228, v232
	v_permlane32_swap_b32_e32 v229, v233
	v_add_f32_e32 v226, v226, v230
	v_add_f32_e32 v228, v228, v232
	v_add_f32_e32 v227, v227, v231
	v_add_f32_e32 v229, v229, v233
	s_nop 1
	v_permlane16_swap_b32_e32 v226, v228
	v_permlane16_swap_b32_e32 v227, v229
	v_add_f32_e32 v226, v226, v228
	v_add_f32_e32 v227, v227, v229
	s_nop 0
	v_cndmask_b32_e64 v230, v226, v227, s[24:25]
	v_cndmask_b32_e64 v231, v227, v226, s[24:25]
	s_nop 1
	v_add_f32_dpp v232, v231, v230 row_ror:8 row_mask:0xf bank_mask:0xf
	s_nop 1
	v_add_f32_dpp v233, v232, v232 quad_perm:[1,0,3,2] row_mask:0xf bank_mask:0xf
	s_nop 1
	v_add_f32_dpp v232, v233, v233 quad_perm:[2,3,0,1] row_mask:0xf bank_mask:0xf
	s_nop 1
	v_add_f32_dpp v233, v232, v232 row_half_mirror row_mask:0xf bank_mask:0xf
	ds_write_b32 v235, v233 offset:34848
	v_readlane_b32 s48, v141, s72
	v_readlane_b32 s49, v141, s73
	v_readlane_b32 s50, v141, s74
	v_readlane_b32 s51, v141, s75
	v_readlane_b32 s52, v141, s76
	v_readlane_b32 s53, v141, s77
	v_readlane_b32 s54, v141, s78
	v_readlane_b32 s55, v141, s79
	s_add_u32 s32, s0, s48
	s_addc_u32 s33, s1, 0
	s_add_u32 s34, s0, s49
	s_addc_u32 s35, s1, 0
	s_add_u32 s36, s0, s50
	s_addc_u32 s37, s1, 0
	s_add_u32 s38, s0, s51
	s_addc_u32 s39, s1, 0
	s_add_u32 s40, s0, s52
	s_addc_u32 s41, s1, 0
	s_add_u32 s42, s0, s53
	s_addc_u32 s43, s1, 0
	s_add_u32 s44, s0, s54
	s_addc_u32 s45, s1, 0
	s_add_u32 s46, s0, s55
	s_addc_u32 s47, s1, 0
	global_load_dwordx4 v[144:147], v234, s[32:33]
	global_load_dwordx4 v[148:151], v234, s[34:35]
	global_load_dwordx4 v[152:155], v234, s[36:37]
	global_load_dwordx4 v[156:159], v234, s[38:39]
	global_load_dwordx4 v[160:163], v234, s[40:41]
	global_load_dwordx4 v[164:167], v234, s[42:43]
	global_load_dwordx4 v[168:171], v234, s[44:45]
	global_load_dwordx4 v[172:175], v234, s[46:47]
	s_waitcnt vmcnt(8)
; template <bool STORE>
; DI void peer_item(const Params& p, int item, char* smem) {
;     ...
; #pragma unroll
;       for (int u = 0; u < 8; ++u) {
;         float d = 0.f;
; #pragma unroll
;         for (int i = 0; i < 4; ++i) {
;           f32x2_t lo = __builtin_amdgcn_cvt_pk_f32_fp8((int)uq[u][i], false);
;           f32x2_t hi = __builtin_amdgcn_cvt_pk_f32_fp8((int)uq[u][i], true);
;           d += xf[4 * i] * lo.x + xf[4 * i + 1] * lo.y + xf[4 * i + 2] * hi.x + xf[4 * i + 3] * hi.y;
;         }
;         part[u] = d;
;       }
;       float q4[4], r2[2], h;
	v_cvt_pk_f32_fp8_e32 v[214:215], v176
	v_cvt_pk_f32_fp8_sdwa v[216:217], v176 src0_sel:WORD_1
	v_cvt_pk_f32_fp8_e32 v[218:219], v177
	v_cvt_pk_f32_fp8_sdwa v[220:221], v177 src0_sel:WORD_1
	v_pk_mul_f32 v[222:223], v[80:81], v[214:215]
	v_pk_mul_f32 v[224:225], v[82:83], v[216:217]
	v_cvt_pk_f32_fp8_e32 v[214:215], v178
	v_cvt_pk_f32_fp8_sdwa v[216:217], v178 src0_sel:WORD_1
	v_pk_fma_f32 v[222:223], v[84:85], v[218:219], v[222:223]
	v_pk_fma_f32 v[224:225], v[86:87], v[220:221], v[224:225]
	v_cvt_pk_f32_fp8_e32 v[218:219], v179
	v_cvt_pk_f32_fp8_sdwa v[220:221], v179 src0_sel:WORD_1
	v_pk_fma_f32 v[222:223], v[88:89], v[214:215], v[222:223]
	v_pk_fma_f32 v[224:225], v[90:91], v[216:217], v[224:225]
	v_pk_fma_f32 v[222:223], v[92:93], v[218:219], v[222:223]
	v_pk_fma_f32 v[224:225], v[94:95], v[220:221], v[224:225]
	v_pk_add_f32 v[222:223], v[222:223], v[224:225]
	s_nop 0
	v_add_f32_e32 v226, v222, v223
	v_cvt_pk_f32_fp8_e32 v[214:215], v180
	v_cvt_pk_f32_fp8_sdwa v[216:217], v180 src0_sel:WORD_1
	v_cvt_pk_f32_fp8_e32 v[218:219], v181
	v_cvt_pk_f32_fp8_sdwa v[220:221], v181 src0_sel:WORD_1
	v_pk_mul_f32 v[222:223], v[80:81], v[214:215]
	v_pk_mul_f32 v[224:225], v[82:83], v[216:217]
	v_cvt_pk_f32_fp8_e32 v[214:215], v182
	v_cvt_pk_f32_fp8_sdwa v[216:217], v182 src0_sel:WORD_1
	v_pk_fma_f32 v[222:223], v[84:85], v[218:219], v[222:223]
	v_pk_fma_f32 v[224:225], v[86:87], v[220:221], v[224:225]
	v_cvt_pk_f32_fp8_e32 v[218:219], v183
	v_cvt_pk_f32_fp8_sdwa v[220:221], v183 src0_sel:WORD_1
	v_pk_fma_f32 v[222:223], v[88:89], v[214:215], v[222:223]
	v_pk_fma_f32 v[224:225], v[90:91], v[216:217], v[224:225]
	v_pk_fma_f32 v[222:223], v[92:93], v[218:219], v[222:223]
	v_pk_fma_f32 v[224:225], v[94:95], v[220:221], v[224:225]
	v_pk_add_f32 v[222:223], v[222:223], v[224:225]
	s_nop 0
	v_add_f32_e32 v227, v222, v223
	v_cvt_pk_f32_fp8_e32 v[214:215], v184
	v_cvt_pk_f32_fp8_sdwa v[216:217], v184 src0_sel:WORD_1
	v_cvt_pk_f32_fp8_e32 v[218:219], v185
	v_cvt_pk_f32_fp8_sdwa v[220:221], v185 src0_sel:WORD_1
	v_pk_mul_f32 v[222:223], v[80:81], v[214:215]
	v_pk_mul_f32 v[224:225], v[82:83], v[216:217]
	v_cvt_pk_f32_fp8_e32 v[214:215], v186
	v_cvt_pk_f32_fp8_sdwa v[216:217], v186 src0_sel:WORD_1
	v_pk_fma_f32 v[222:223], v[84:85], v[218:219], v[222:223]
	v_pk_fma_f32 v[224:225], v[86:87], v[220:221], v[224:225]
	v_cvt_pk_f32_fp8_e32 v[218:219], v187
	v_cvt_pk_f32_fp8_sdwa v[220:221], v187 src0_sel:WORD_1
	v_pk_fma_f32 v[222:223], v[88:89], v[214:215], v[222:223]
	v_pk_fma_f32 v[224:225], v[90:91], v[216:217], v[224:225]
	v_pk_fma_f32 v[222:223], v[92:93], v[218:219], v[222:223]
	v_pk_fma_f32 v[224:225], v[94:95], v[220:221], v[224:225]
	v_pk_add_f32 v[222:223], v[222:223], v[224:225]
	s_nop 0
	v_add_f32_e32 v228, v222, v223
	v_cvt_pk_f32_fp8_e32 v[214:215], v188
	v_cvt_pk_f32_fp8_sdwa v[216:217], v188 src0_sel:WORD_1
	v_cvt_pk_f32_fp8_e32 v[218:219], v189
	v_cvt_pk_f32_fp8_sdwa v[220:221], v189 src0_sel:WORD_1
	v_pk_mul_f32 v[222:223], v[80:81], v[214:215]
	v_pk_mul_f32 v[224:225], v[82:83], v[216:217]
	v_cvt_pk_f32_fp8_e32 v[214:215], v190
	v_cvt_pk_f32_fp8_sdwa v[216:217], v190 src0_sel:WORD_1
	v_pk_fma_f32 v[222:223], v[84:85], v[218:219], v[222:223]
	v_pk_fma_f32 v[224:225], v[86:87], v[220:221], v[224:225]
	v_cvt_pk_f32_fp8_e32 v[218:219], v191
	v_cvt_pk_f32_fp8_sdwa v[220:221], v191 src0_sel:WORD_1
	v_pk_fma_f32 v[222:223], v[88:89], v[214:215], v[222:223]
	v_pk_fma_f32 v[224:225], v[90:91], v[216:217], v[224:225]
	v_pk_fma_f32 v[222:223], v[92:93], v[218:219], v[222:223]
	v_pk_fma_f32 v[224:225], v[94:95], v[220:221], v[224:225]
	v_pk_add_f32 v[222:223], v[222:223], v[224:225]
	s_nop 0
	v_add_f32_e32 v229, v222, v223
	v_cvt_pk_f32_fp8_e32 v[214:215], v192
	v_cvt_pk_f32_fp8_sdwa v[216:217], v192 src0_sel:WORD_1
	v_cvt_pk_f32_fp8_e32 v[218:219], v193
	v_cvt_pk_f32_fp8_sdwa v[220:221], v193 src0_sel:WORD_1
	v_pk_mul_f32 v[222:223], v[80:81], v[214:215]
	v_pk_mul_f32 v[224:225], v[82:83], v[216:217]
	v_cvt_pk_f32_fp8_e32 v[214:215], v194
	v_cvt_pk_f32_fp8_sdwa v[216:217], v194 src0_sel:WORD_1
	v_pk_fma_f32 v[222:223], v[84:85], v[218:219], v[222:223]
	v_pk_fma_f32 v[224:225], v[86:87], v[220:221], v[224:225]
	v_cvt_pk_f32_fp8_e32 v[218:219], v195
	v_cvt_pk_f32_fp8_sdwa v[220:221], v195 src0_sel:WORD_1
	v_pk_fma_f32 v[222:223], v[88:89], v[214:215], v[222:223]
	v_pk_fma_f32 v[224:225], v[90:91], v[216:217], v[224:225]
	v_pk_fma_f32 v[222:223], v[92:93], v[218:219], v[222:223]
	v_pk_fma_f32 v[224:225], v[94:95], v[220:221], v[224:225]
	v_pk_add_f32 v[222:223], v[222:223], v[224:225]
	s_nop 0
	v_add_f32_e32 v230, v222, v223
	v_cvt_pk_f32_fp8_e32 v[214:215], v196
	v_cvt_pk_f32_fp8_sdwa v[216:217], v196 src0_sel:WORD_1
	v_cvt_pk_f32_fp8_e32 v[218:219], v197
	v_cvt_pk_f32_fp8_sdwa v[220:221], v197 src0_sel:WORD_1
	v_pk_mul_f32 v[222:223], v[80:81], v[214:215]
	v_pk_mul_f32 v[224:225], v[82:83], v[216:217]
	v_cvt_pk_f32_fp8_e32 v[214:215], v198
	v_cvt_pk_f32_fp8_sdwa v[216:217], v198 src0_sel:WORD_1
	v_pk_fma_f32 v[222:223], v[84:85], v[218:219], v[222:223]
	v_pk_fma_f32 v[224:225], v[86:87], v[220:221], v[224:225]
	v_cvt_pk_f32_fp8_e32 v[218:219], v199
	v_cvt_pk_f32_fp8_sdwa v[220:221], v199 src0_sel:WORD_1
	v_pk_fma_f32 v[222:223], v[88:89], v[214:215], v[222:223]
	v_pk_fma_f32 v[224:225], v[90:91], v[216:217], v[224:225]
	v_pk_fma_f32 v[222:223], v[92:93], v[218:219], v[222:223]
	v_pk_fma_f32 v[224:225], v[94:95], v[220:221], v[224:225]
	v_pk_add_f32 v[222:223], v[222:223], v[224:225]
	s_nop 0
	v_add_f32_e32 v231, v222, v223
	v_cvt_pk_f32_fp8_e32 v[214:215], v200
	v_cvt_pk_f32_fp8_sdwa v[216:217], v200 src0_sel:WORD_1
	v_cvt_pk_f32_fp8_e32 v[218:219], v201
; template <bool STORE>
; DI void peer_item(const Params& p, int item, char* smem) {
;     ...
; #pragma unroll
;       for (int u = 0; u < 8; ++u) {
;         int e = e_s[tl * 128 + k + u];
;         uq[u] = *(const u32x4*)(U8 + (size_t)e * 1024 + lane * 16);
;     ...
; #pragma unroll
;       for (int u = 0; u < 8; ++u) {
;         float d = 0.f;
; #pragma unroll
;         for (int i = 0; i < 4; ++i) {
;           f32x2_t lo = __builtin_amdgcn_cvt_pk_f32_fp8((int)uq[u][i], false);
;           f32x2_t hi = __builtin_amdgcn_cvt_pk_f32_fp8((int)uq[u][i], true);
;           d += xf[4 * i] * lo.x + xf[4 * i + 1] * lo.y + xf[4 * i + 2] * hi.x + xf[4 * i + 3] * hi.y;
;         }
;         part[u] = d;
;       }
;       float q4[4], r2[2], h;
; #pragma unroll
;       for (int j = 0; j < 4; ++j) {
;         float mine = b5 ? part[j + 4] : part[j];
;         float other = b5 ? part[j] : part[j + 4];
;         q4[j] = mine + __shfl_xor(other, 32);
;       }
; #pragma unroll
;       for (int j = 0; j < 2; ++j) {
;         float mine = b4 ? q4[j + 2] : q4[j];
;         float other = b4 ? q4[j] : q4[j + 2];
;         r2[j] = mine + __shfl_xor(other, 16);
;       }
;       {
;         float mine = b3 ? r2[1] : r2[0];
;         float other = b3 ? r2[0] : r2[1];
;         h = mine + __shfl_xor(other, 8);
;       }
;       h += __shfl_xor(h, 4);
;       h += __shfl_xor(h, 2);
;       h += __shfl_xor(h, 1);
	v_cvt_pk_f32_fp8_sdwa v[220:221], v201 src0_sel:WORD_1
	v_pk_mul_f32 v[222:223], v[80:81], v[214:215]
	v_pk_mul_f32 v[224:225], v[82:83], v[216:217]
	v_cvt_pk_f32_fp8_e32 v[214:215], v202
	v_cvt_pk_f32_fp8_sdwa v[216:217], v202 src0_sel:WORD_1
	v_pk_fma_f32 v[222:223], v[84:85], v[218:219], v[222:223]
	v_pk_fma_f32 v[224:225], v[86:87], v[220:221], v[224:225]
	v_cvt_pk_f32_fp8_e32 v[218:219], v203
	v_cvt_pk_f32_fp8_sdwa v[220:221], v203 src0_sel:WORD_1
	v_pk_fma_f32 v[222:223], v[88:89], v[214:215], v[222:223]
	v_pk_fma_f32 v[224:225], v[90:91], v[216:217], v[224:225]
	v_pk_fma_f32 v[222:223], v[92:93], v[218:219], v[222:223]
	v_pk_fma_f32 v[224:225], v[94:95], v[220:221], v[224:225]
	v_pk_add_f32 v[222:223], v[222:223], v[224:225]
	s_nop 0
	v_add_f32_e32 v232, v222, v223
	v_cvt_pk_f32_fp8_e32 v[214:215], v204
	v_cvt_pk_f32_fp8_sdwa v[216:217], v204 src0_sel:WORD_1
	v_cvt_pk_f32_fp8_e32 v[218:219], v205
	v_cvt_pk_f32_fp8_sdwa v[220:221], v205 src0_sel:WORD_1
	v_pk_mul_f32 v[222:223], v[80:81], v[214:215]
	v_pk_mul_f32 v[224:225], v[82:83], v[216:217]
	v_cvt_pk_f32_fp8_e32 v[214:215], v206
	v_cvt_pk_f32_fp8_sdwa v[216:217], v206 src0_sel:WORD_1
	v_pk_fma_f32 v[222:223], v[84:85], v[218:219], v[222:223]
	v_pk_fma_f32 v[224:225], v[86:87], v[220:221], v[224:225]
	v_cvt_pk_f32_fp8_e32 v[218:219], v207
	v_cvt_pk_f32_fp8_sdwa v[220:221], v207 src0_sel:WORD_1
	v_pk_fma_f32 v[222:223], v[88:89], v[214:215], v[222:223]
	v_pk_fma_f32 v[224:225], v[90:91], v[216:217], v[224:225]
	v_pk_fma_f32 v[222:223], v[92:93], v[218:219], v[222:223]
	v_pk_fma_f32 v[224:225], v[94:95], v[220:221], v[224:225]
	v_pk_add_f32 v[222:223], v[222:223], v[224:225]
	s_nop 0
	v_add_f32_e32 v233, v222, v223
	v_permlane32_swap_b32_e32 v226, v230
	v_permlane32_swap_b32_e32 v227, v231
	v_permlane32_swap_b32_e32 v228, v232
	v_permlane32_swap_b32_e32 v229, v233
	v_add_f32_e32 v226, v226, v230
	v_add_f32_e32 v228, v228, v232
	v_add_f32_e32 v227, v227, v231
	v_add_f32_e32 v229, v229, v233
	s_nop 1
	v_permlane16_swap_b32_e32 v226, v228
	v_permlane16_swap_b32_e32 v227, v229
	v_add_f32_e32 v226, v226, v228
	v_add_f32_e32 v227, v227, v229
	s_nop 0
	v_cndmask_b32_e64 v230, v226, v227, s[24:25]
	v_cndmask_b32_e64 v231, v227, v226, s[24:25]
	s_nop 1
	v_add_f32_dpp v232, v231, v230 row_ror:8 row_mask:0xf bank_mask:0xf
	s_nop 1
	v_add_f32_dpp v233, v232, v232 quad_perm:[1,0,3,2] row_mask:0xf bank_mask:0xf
	s_nop 1
	v_add_f32_dpp v232, v233, v233 quad_perm:[2,3,0,1] row_mask:0xf bank_mask:0xf
	s_nop 1
	v_add_f32_dpp v233, v232, v232 row_half_mirror row_mask:0xf bank_mask:0xf
	ds_write_b32 v235, v233 offset:35360
	v_readlane_b32 s48, v143, s72
	v_readlane_b32 s49, v143, s73
	v_readlane_b32 s50, v143, s74
	v_readlane_b32 s51, v143, s75
	v_readlane_b32 s52, v143, s76
	v_readlane_b32 s53, v143, s77
	v_readlane_b32 s54, v143, s78
	v_readlane_b32 s55, v143, s79
	s_add_u32 s32, s0, s48
	s_addc_u32 s33, s1, 0
	s_add_u32 s34, s0, s49
	s_addc_u32 s35, s1, 0
	s_add_u32 s36, s0, s50
	s_addc_u32 s37, s1, 0
	s_add_u32 s38, s0, s51
	s_addc_u32 s39, s1, 0
	s_add_u32 s40, s0, s52
	s_addc_u32 s41, s1, 0
	s_add_u32 s42, s0, s53
	s_addc_u32 s43, s1, 0
	s_add_u32 s44, s0, s54
	s_addc_u32 s45, s1, 0
	s_add_u32 s46, s0, s55
	s_addc_u32 s47, s1, 0
	global_load_dwordx4 v[176:179], v234, s[32:33]
	global_load_dwordx4 v[180:183], v234, s[34:35]
	global_load_dwordx4 v[184:187], v234, s[36:37]
	global_load_dwordx4 v[188:191], v234, s[38:39]
	global_load_dwordx4 v[192:195], v234, s[40:41]
	global_load_dwordx4 v[196:199], v234, s[42:43]
	global_load_dwordx4 v[200:203], v234, s[44:45]
	global_load_dwordx4 v[204:207], v234, s[46:47]
	s_waitcnt vmcnt(8)
	v_cvt_pk_f32_fp8_e32 v[214:215], v144
	v_cvt_pk_f32_fp8_sdwa v[216:217], v144 src0_sel:WORD_1
	v_cvt_pk_f32_fp8_e32 v[218:219], v145
	v_cvt_pk_f32_fp8_sdwa v[220:221], v145 src0_sel:WORD_1
	v_pk_mul_f32 v[222:223], v[96:97], v[214:215]
	v_pk_mul_f32 v[224:225], v[98:99], v[216:217]
	v_cvt_pk_f32_fp8_e32 v[214:215], v146
	v_cvt_pk_f32_fp8_sdwa v[216:217], v146 src0_sel:WORD_1
	v_pk_fma_f32 v[222:223], v[100:101], v[218:219], v[222:223]
	v_pk_fma_f32 v[224:225], v[102:103], v[220:221], v[224:225]
	v_cvt_pk_f32_fp8_e32 v[218:219], v147
	v_cvt_pk_f32_fp8_sdwa v[220:221], v147 src0_sel:WORD_1
	v_pk_fma_f32 v[222:223], v[104:105], v[214:215], v[222:223]
	v_pk_fma_f32 v[224:225], v[106:107], v[216:217], v[224:225]
	v_pk_fma_f32 v[222:223], v[108:109], v[218:219], v[222:223]
	v_pk_fma_f32 v[224:225], v[110:111], v[220:221], v[224:225]
	v_pk_add_f32 v[222:223], v[222:223], v[224:225]
	s_nop 0
	v_add_f32_e32 v226, v222, v223
	v_cvt_pk_f32_fp8_e32 v[214:215], v148
	v_cvt_pk_f32_fp8_sdwa v[216:217], v148 src0_sel:WORD_1
	v_cvt_pk_f32_fp8_e32 v[218:219], v149
	v_cvt_pk_f32_fp8_sdwa v[220:221], v149 src0_sel:WORD_1
	v_pk_mul_f32 v[222:223], v[96:97], v[214:215]
	v_pk_mul_f32 v[224:225], v[98:99], v[216:217]
	v_cvt_pk_f32_fp8_e32 v[214:215], v150
	v_cvt_pk_f32_fp8_sdwa v[216:217], v150 src0_sel:WORD_1
	v_pk_fma_f32 v[222:223], v[100:101], v[218:219], v[222:223]
	v_pk_fma_f32 v[224:225], v[102:103], v[220:221], v[224:225]
	v_cvt_pk_f32_fp8_e32 v[218:219], v151
	v_cvt_pk_f32_fp8_sdwa v[220:221], v151 src0_sel:WORD_1
	v_pk_fma_f32 v[222:223], v[104:105], v[214:215], v[222:223]
	v_pk_fma_f32 v[224:225], v[106:107], v[216:217], v[224:225]
	v_pk_fma_f32 v[222:223], v[108:109], v[218:219], v[222:223]
	v_pk_fma_f32 v[224:225], v[110:111], v[220:221], v[224:225]
	v_pk_add_f32 v[222:223], v[222:223], v[224:225]
	s_nop 0
	v_add_f32_e32 v227, v222, v223
	v_cvt_pk_f32_fp8_e32 v[214:215], v152
	v_cvt_pk_f32_fp8_sdwa v[216:217], v152 src0_sel:WORD_1
	v_cvt_pk_f32_fp8_e32 v[218:219], v153
; template <bool STORE>
; DI void peer_item(const Params& p, int item, char* smem) {
;     ...
; #pragma unroll
;       for (int u = 0; u < 8; ++u) {
;         float d = 0.f;
; #pragma unroll
;         for (int i = 0; i < 4; ++i) {
;           f32x2_t lo = __builtin_amdgcn_cvt_pk_f32_fp8((int)uq[u][i], false);
;           f32x2_t hi = __builtin_amdgcn_cvt_pk_f32_fp8((int)uq[u][i], true);
;           d += xf[4 * i] * lo.x + xf[4 * i + 1] * lo.y + xf[4 * i + 2] * hi.x + xf[4 * i + 3] * hi.y;
;         }
;         part[u] = d;
;       }
;       float q4[4], r2[2], h;
; #pragma unroll
;       for (int j = 0; j < 4; ++j) {
;         float mine = b5 ? part[j + 4] : part[j];
;         float other = b5 ? part[j] : part[j + 4];
;         q4[j] = mine + __shfl_xor(other, 32);
;       }
; #pragma unroll
;       for (int j = 0; j < 2; ++j) {
;         float mine = b4 ? q4[j + 2] : q4[j];
;         float other = b4 ? q4[j] : q4[j + 2];
;         r2[j] = mine + __shfl_xor(other, 16);
;       }
;       {
;         float mine = b3 ? r2[1] : r2[0];
;         float other = b3 ? r2[0] : r2[1];
;         h = mine + __shfl_xor(other, 8);
;       }
;       h += __shfl_xor(h, 4);
;       h += __shfl_xor(h, 2);
;       h += __shfl_xor(h, 1);
	v_cvt_pk_f32_fp8_sdwa v[220:221], v153 src0_sel:WORD_1
	v_pk_mul_f32 v[222:223], v[96:97], v[214:215]
	v_pk_mul_f32 v[224:225], v[98:99], v[216:217]
	v_cvt_pk_f32_fp8_e32 v[214:215], v154
	v_cvt_pk_f32_fp8_sdwa v[216:217], v154 src0_sel:WORD_1
	v_pk_fma_f32 v[222:223], v[100:101], v[218:219], v[222:223]
	v_pk_fma_f32 v[224:225], v[102:103], v[220:221], v[224:225]
	v_cvt_pk_f32_fp8_e32 v[218:219], v155
	v_cvt_pk_f32_fp8_sdwa v[220:221], v155 src0_sel:WORD_1
	v_pk_fma_f32 v[222:223], v[104:105], v[214:215], v[222:223]
	v_pk_fma_f32 v[224:225], v[106:107], v[216:217], v[224:225]
	v_pk_fma_f32 v[222:223], v[108:109], v[218:219], v[222:223]
	v_pk_fma_f32 v[224:225], v[110:111], v[220:221], v[224:225]
	v_pk_add_f32 v[222:223], v[222:223], v[224:225]
	s_nop 0
	v_add_f32_e32 v228, v222, v223
	v_cvt_pk_f32_fp8_e32 v[214:215], v156
	v_cvt_pk_f32_fp8_sdwa v[216:217], v156 src0_sel:WORD_1
	v_cvt_pk_f32_fp8_e32 v[218:219], v157
	v_cvt_pk_f32_fp8_sdwa v[220:221], v157 src0_sel:WORD_1
	v_pk_mul_f32 v[222:223], v[96:97], v[214:215]
	v_pk_mul_f32 v[224:225], v[98:99], v[216:217]
	v_cvt_pk_f32_fp8_e32 v[214:215], v158
	v_cvt_pk_f32_fp8_sdwa v[216:217], v158 src0_sel:WORD_1
	v_pk_fma_f32 v[222:223], v[100:101], v[218:219], v[222:223]
	v_pk_fma_f32 v[224:225], v[102:103], v[220:221], v[224:225]
	v_cvt_pk_f32_fp8_e32 v[218:219], v159
	v_cvt_pk_f32_fp8_sdwa v[220:221], v159 src0_sel:WORD_1
	v_pk_fma_f32 v[222:223], v[104:105], v[214:215], v[222:223]
	v_pk_fma_f32 v[224:225], v[106:107], v[216:217], v[224:225]
	v_pk_fma_f32 v[222:223], v[108:109], v[218:219], v[222:223]
	v_pk_fma_f32 v[224:225], v[110:111], v[220:221], v[224:225]
	v_pk_add_f32 v[222:223], v[222:223], v[224:225]
	s_nop 0
	v_add_f32_e32 v229, v222, v223
	v_cvt_pk_f32_fp8_e32 v[214:215], v160
	v_cvt_pk_f32_fp8_sdwa v[216:217], v160 src0_sel:WORD_1
	v_cvt_pk_f32_fp8_e32 v[218:219], v161
	v_cvt_pk_f32_fp8_sdwa v[220:221], v161 src0_sel:WORD_1
	v_pk_mul_f32 v[222:223], v[96:97], v[214:215]
	v_pk_mul_f32 v[224:225], v[98:99], v[216:217]
	v_cvt_pk_f32_fp8_e32 v[214:215], v162
	v_cvt_pk_f32_fp8_sdwa v[216:217], v162 src0_sel:WORD_1
	v_pk_fma_f32 v[222:223], v[100:101], v[218:219], v[222:223]
	v_pk_fma_f32 v[224:225], v[102:103], v[220:221], v[224:225]
	v_cvt_pk_f32_fp8_e32 v[218:219], v163
	v_cvt_pk_f32_fp8_sdwa v[220:221], v163 src0_sel:WORD_1
	v_pk_fma_f32 v[222:223], v[104:105], v[214:215], v[222:223]
	v_pk_fma_f32 v[224:225], v[106:107], v[216:217], v[224:225]
	v_pk_fma_f32 v[222:223], v[108:109], v[218:219], v[222:223]
	v_pk_fma_f32 v[224:225], v[110:111], v[220:221], v[224:225]
	v_pk_add_f32 v[222:223], v[222:223], v[224:225]
	s_nop 0
	v_add_f32_e32 v230, v222, v223
	v_cvt_pk_f32_fp8_e32 v[214:215], v164
	v_cvt_pk_f32_fp8_sdwa v[216:217], v164 src0_sel:WORD_1
	v_cvt_pk_f32_fp8_e32 v[218:219], v165
	v_cvt_pk_f32_fp8_sdwa v[220:221], v165 src0_sel:WORD_1
	v_pk_mul_f32 v[222:223], v[96:97], v[214:215]
	v_pk_mul_f32 v[224:225], v[98:99], v[216:217]
	v_cvt_pk_f32_fp8_e32 v[214:215], v166
	v_cvt_pk_f32_fp8_sdwa v[216:217], v166 src0_sel:WORD_1
	v_pk_fma_f32 v[222:223], v[100:101], v[218:219], v[222:223]
	v_pk_fma_f32 v[224:225], v[102:103], v[220:221], v[224:225]
	v_cvt_pk_f32_fp8_e32 v[218:219], v167
	v_cvt_pk_f32_fp8_sdwa v[220:221], v167 src0_sel:WORD_1
	v_pk_fma_f32 v[222:223], v[104:105], v[214:215], v[222:223]
	v_pk_fma_f32 v[224:225], v[106:107], v[216:217], v[224:225]
	v_pk_fma_f32 v[222:223], v[108:109], v[218:219], v[222:223]
	v_pk_fma_f32 v[224:225], v[110:111], v[220:221], v[224:225]
	v_pk_add_f32 v[222:223], v[222:223], v[224:225]
	s_nop 0
	v_add_f32_e32 v231, v222, v223
	v_cvt_pk_f32_fp8_e32 v[214:215], v168
	v_cvt_pk_f32_fp8_sdwa v[216:217], v168 src0_sel:WORD_1
	v_cvt_pk_f32_fp8_e32 v[218:219], v169
	v_cvt_pk_f32_fp8_sdwa v[220:221], v169 src0_sel:WORD_1
	v_pk_mul_f32 v[222:223], v[96:97], v[214:215]
	v_pk_mul_f32 v[224:225], v[98:99], v[216:217]
	v_cvt_pk_f32_fp8_e32 v[214:215], v170
	v_cvt_pk_f32_fp8_sdwa v[216:217], v170 src0_sel:WORD_1
	v_pk_fma_f32 v[222:223], v[100:101], v[218:219], v[222:223]
	v_pk_fma_f32 v[224:225], v[102:103], v[220:221], v[224:225]
	v_cvt_pk_f32_fp8_e32 v[218:219], v171
	v_cvt_pk_f32_fp8_sdwa v[220:221], v171 src0_sel:WORD_1
	v_pk_fma_f32 v[222:223], v[104:105], v[214:215], v[222:223]
	v_pk_fma_f32 v[224:225], v[106:107], v[216:217], v[224:225]
	v_pk_fma_f32 v[222:223], v[108:109], v[218:219], v[222:223]
	v_pk_fma_f32 v[224:225], v[110:111], v[220:221], v[224:225]
	v_pk_add_f32 v[222:223], v[222:223], v[224:225]
	s_nop 0
	v_add_f32_e32 v232, v222, v223
	v_cvt_pk_f32_fp8_e32 v[214:215], v172
	v_cvt_pk_f32_fp8_sdwa v[216:217], v172 src0_sel:WORD_1
	v_cvt_pk_f32_fp8_e32 v[218:219], v173
	v_cvt_pk_f32_fp8_sdwa v[220:221], v173 src0_sel:WORD_1
	v_pk_mul_f32 v[222:223], v[96:97], v[214:215]
	v_pk_mul_f32 v[224:225], v[98:99], v[216:217]
	v_cvt_pk_f32_fp8_e32 v[214:215], v174
	v_cvt_pk_f32_fp8_sdwa v[216:217], v174 src0_sel:WORD_1
	v_pk_fma_f32 v[222:223], v[100:101], v[218:219], v[222:223]
	v_pk_fma_f32 v[224:225], v[102:103], v[220:221], v[224:225]
	v_cvt_pk_f32_fp8_e32 v[218:219], v175
	v_cvt_pk_f32_fp8_sdwa v[220:221], v175 src0_sel:WORD_1
	v_pk_fma_f32 v[222:223], v[104:105], v[214:215], v[222:223]
	v_pk_fma_f32 v[224:225], v[106:107], v[216:217], v[224:225]
	v_pk_fma_f32 v[222:223], v[108:109], v[218:219], v[222:223]
	v_pk_fma_f32 v[224:225], v[110:111], v[220:221], v[224:225]
	v_pk_add_f32 v[222:223], v[222:223], v[224:225]
	s_nop 0
	v_add_f32_e32 v233, v222, v223
	v_permlane32_swap_b32_e32 v226, v230
	v_permlane32_swap_b32_e32 v227, v231
	v_permlane32_swap_b32_e32 v228, v232
	v_permlane32_swap_b32_e32 v229, v233
	v_add_f32_e32 v226, v226, v230
; template <bool STORE>
; DI void peer_item(const Params& p, int item, char* smem) {
;     ...
;     for (int k = 0; k < 128; k += 8) {
;       u32x4 uq[8];
;       const int emine = e_s[tl * 128 + k + (lane >> 3)];
;       const float gmine = g_s[tl * 128 + k + (lane >> 3)];
;       const float su = SU[emine], sv = SV[emine];
; #pragma unroll
;       for (int u = 0; u < 8; ++u) {
;         int e = e_s[tl * 128 + k + u];
;         uq[u] = *(const u32x4*)(U8 + (size_t)e * 1024 + lane * 16);
;     ...
;       for (int j = 0; j < 4; ++j) {
;         float mine = b5 ? part[j + 4] : part[j];
;         float other = b5 ? part[j] : part[j + 4];
;         q4[j] = mine + __shfl_xor(other, 32);
;       }
; #pragma unroll
;       for (int j = 0; j < 2; ++j) {
;         float mine = b4 ? q4[j + 2] : q4[j];
;         float other = b4 ? q4[j] : q4[j + 2];
;         r2[j] = mine + __shfl_xor(other, 16);
;       }
;       {
;         float mine = b3 ? r2[1] : r2[0];
;         float other = b3 ? r2[0] : r2[1];
;         h = mine + __shfl_xor(other, 8);
;       }
;       h += __shfl_xor(h, 4);
;       h += __shfl_xor(h, 2);
;       h += __shfl_xor(h, 1);
	v_add_f32_e32 v228, v228, v232
	v_add_f32_e32 v227, v227, v231
	v_add_f32_e32 v229, v229, v233
	s_nop 1
	v_permlane16_swap_b32_e32 v226, v228
	v_permlane16_swap_b32_e32 v227, v229
	v_add_f32_e32 v226, v226, v228
	v_add_f32_e32 v227, v227, v229
	s_nop 0
	v_cndmask_b32_e64 v230, v226, v227, s[24:25]
	v_cndmask_b32_e64 v231, v227, v226, s[24:25]
	s_nop 1
	v_add_f32_dpp v232, v231, v230 row_ror:8 row_mask:0xf bank_mask:0xf
	s_nop 1
	v_add_f32_dpp v233, v232, v232 quad_perm:[1,0,3,2] row_mask:0xf bank_mask:0xf
	s_nop 1
	v_add_f32_dpp v232, v233, v233 quad_perm:[2,3,0,1] row_mask:0xf bank_mask:0xf
	s_nop 1
	v_add_f32_dpp v233, v232, v232 row_half_mirror row_mask:0xf bank_mask:0xf
	ds_write_b32 v235, v233 offset:35872
	s_add_u32 s72, s72, 8
	s_add_u32 s73, s73, 8
	s_add_u32 s74, s74, 8
	s_add_u32 s75, s75, 8
	s_add_u32 s76, s76, 8
	s_add_u32 s77, s77, 8
	s_add_u32 s78, s78, 8
	s_add_u32 s79, s79, 8
	s_and_b32 s72, s72, 63
	s_and_b32 s73, s73, 63
	s_and_b32 s74, s74, 63
	s_and_b32 s75, s75, 63
	s_and_b32 s76, s76, 63
	s_and_b32 s77, s77, 63
	s_and_b32 s78, s78, 63
	s_and_b32 s79, s79, 63
	v_readlane_b32 s48, v128, s72
	v_readlane_b32 s49, v128, s73
	v_readlane_b32 s50, v128, s74
	v_readlane_b32 s51, v128, s75
	v_readlane_b32 s52, v128, s76
	v_readlane_b32 s53, v128, s77
	v_readlane_b32 s54, v128, s78
	v_readlane_b32 s55, v128, s79
	s_add_u32 s32, s0, s48
	s_addc_u32 s33, s1, 0
	s_add_u32 s34, s0, s49
	s_addc_u32 s35, s1, 0
	s_add_u32 s36, s0, s50
	s_addc_u32 s37, s1, 0
	s_add_u32 s38, s0, s51
	s_addc_u32 s39, s1, 0
	s_add_u32 s40, s0, s52
	s_addc_u32 s41, s1, 0
	s_add_u32 s42, s0, s53
	s_addc_u32 s43, s1, 0
	s_add_u32 s44, s0, s54
	s_addc_u32 s45, s1, 0
	s_add_u32 s46, s0, s55
	s_addc_u32 s47, s1, 0
	global_load_dwordx4 v[144:147], v234, s[32:33]
	global_load_dwordx4 v[148:151], v234, s[34:35]
	global_load_dwordx4 v[152:155], v234, s[36:37]
	global_load_dwordx4 v[156:159], v234, s[38:39]
	global_load_dwordx4 v[160:163], v234, s[40:41]
	global_load_dwordx4 v[164:167], v234, s[42:43]
	global_load_dwordx4 v[168:171], v234, s[44:45]
	global_load_dwordx4 v[172:175], v234, s[46:47]
	s_waitcnt vmcnt(8)
	v_cvt_pk_f32_fp8_e32 v[214:215], v176
	v_cvt_pk_f32_fp8_sdwa v[216:217], v176 src0_sel:WORD_1
	v_cvt_pk_f32_fp8_e32 v[218:219], v177
	v_cvt_pk_f32_fp8_sdwa v[220:221], v177 src0_sel:WORD_1
	v_pk_mul_f32 v[222:223], v[112:113], v[214:215]
	v_pk_mul_f32 v[224:225], v[114:115], v[216:217]
	v_cvt_pk_f32_fp8_e32 v[214:215], v178
	v_cvt_pk_f32_fp8_sdwa v[216:217], v178 src0_sel:WORD_1
	v_pk_fma_f32 v[222:223], v[116:117], v[218:219], v[222:223]
	v_pk_fma_f32 v[224:225], v[118:119], v[220:221], v[224:225]
	v_cvt_pk_f32_fp8_e32 v[218:219], v179
	v_cvt_pk_f32_fp8_sdwa v[220:221], v179 src0_sel:WORD_1
	v_pk_fma_f32 v[222:223], v[120:121], v[214:215], v[222:223]
	v_pk_fma_f32 v[224:225], v[122:123], v[216:217], v[224:225]
	v_pk_fma_f32 v[222:223], v[124:125], v[218:219], v[222:223]
	v_pk_fma_f32 v[224:225], v[126:127], v[220:221], v[224:225]
	v_pk_add_f32 v[222:223], v[222:223], v[224:225]
	s_nop 0
	v_add_f32_e32 v226, v222, v223
	v_cvt_pk_f32_fp8_e32 v[214:215], v180
	v_cvt_pk_f32_fp8_sdwa v[216:217], v180 src0_sel:WORD_1
	v_cvt_pk_f32_fp8_e32 v[218:219], v181
	v_cvt_pk_f32_fp8_sdwa v[220:221], v181 src0_sel:WORD_1
	v_pk_mul_f32 v[222:223], v[112:113], v[214:215]
	v_pk_mul_f32 v[224:225], v[114:115], v[216:217]
	v_cvt_pk_f32_fp8_e32 v[214:215], v182
	v_cvt_pk_f32_fp8_sdwa v[216:217], v182 src0_sel:WORD_1
	v_pk_fma_f32 v[222:223], v[116:117], v[218:219], v[222:223]
	v_pk_fma_f32 v[224:225], v[118:119], v[220:221], v[224:225]
	v_cvt_pk_f32_fp8_e32 v[218:219], v183
	v_cvt_pk_f32_fp8_sdwa v[220:221], v183 src0_sel:WORD_1
	v_pk_fma_f32 v[222:223], v[120:121], v[214:215], v[222:223]
	v_pk_fma_f32 v[224:225], v[122:123], v[216:217], v[224:225]
	v_pk_fma_f32 v[222:223], v[124:125], v[218:219], v[222:223]
	v_pk_fma_f32 v[224:225], v[126:127], v[220:221], v[224:225]
	v_pk_add_f32 v[222:223], v[222:223], v[224:225]
	s_nop 0
	v_add_f32_e32 v227, v222, v223
	v_cvt_pk_f32_fp8_e32 v[214:215], v184
	v_cvt_pk_f32_fp8_sdwa v[216:217], v184 src0_sel:WORD_1
	v_cvt_pk_f32_fp8_e32 v[218:219], v185
	v_cvt_pk_f32_fp8_sdwa v[220:221], v185 src0_sel:WORD_1
	v_pk_mul_f32 v[222:223], v[112:113], v[214:215]
	v_pk_mul_f32 v[224:225], v[114:115], v[216:217]
	v_cvt_pk_f32_fp8_e32 v[214:215], v186
	v_cvt_pk_f32_fp8_sdwa v[216:217], v186 src0_sel:WORD_1
	v_pk_fma_f32 v[222:223], v[116:117], v[218:219], v[222:223]
	v_pk_fma_f32 v[224:225], v[118:119], v[220:221], v[224:225]
	v_cvt_pk_f32_fp8_e32 v[218:219], v187
	v_cvt_pk_f32_fp8_sdwa v[220:221], v187 src0_sel:WORD_1
	v_pk_fma_f32 v[222:223], v[120:121], v[214:215], v[222:223]
	v_pk_fma_f32 v[224:225], v[122:123], v[216:217], v[224:225]
	v_pk_fma_f32 v[222:223], v[124:125], v[218:219], v[222:223]
	v_pk_fma_f32 v[224:225], v[126:127], v[220:221], v[224:225]
	v_pk_add_f32 v[222:223], v[222:223], v[224:225]
	s_nop 0
	v_add_f32_e32 v228, v222, v223
	v_cvt_pk_f32_fp8_e32 v[214:215], v188
	v_cvt_pk_f32_fp8_sdwa v[216:217], v188 src0_sel:WORD_1
	v_cvt_pk_f32_fp8_e32 v[218:219], v189
	v_cvt_pk_f32_fp8_sdwa v[220:221], v189 src0_sel:WORD_1
	v_pk_mul_f32 v[222:223], v[112:113], v[214:215]
	v_pk_mul_f32 v[224:225], v[114:115], v[216:217]
	v_cvt_pk_f32_fp8_e32 v[214:215], v190
	v_cvt_pk_f32_fp8_sdwa v[216:217], v190 src0_sel:WORD_1
	v_pk_fma_f32 v[222:223], v[116:117], v[218:219], v[222:223]
	v_pk_fma_f32 v[224:225], v[118:119], v[220:221], v[224:225]
	v_cvt_pk_f32_fp8_e32 v[218:219], v191
	v_cvt_pk_f32_fp8_sdwa v[220:221], v191 src0_sel:WORD_1
	v_pk_fma_f32 v[222:223], v[120:121], v[214:215], v[222:223]
	v_pk_fma_f32 v[224:225], v[122:123], v[216:217], v[224:225]
; template <bool STORE>
; DI void peer_item(const Params& p, int item, char* smem) {
;     ...
;     for (int k = 0; k < 128; k += 8) {
;     ...
; #pragma unroll
;       for (int u = 0; u < 8; ++u) {
;         float d = 0.f;
; #pragma unroll
;         for (int i = 0; i < 4; ++i) {
;           f32x2_t lo = __builtin_amdgcn_cvt_pk_f32_fp8((int)uq[u][i], false);
;           f32x2_t hi = __builtin_amdgcn_cvt_pk_f32_fp8((int)uq[u][i], true);
;           d += xf[4 * i] * lo.x + xf[4 * i + 1] * lo.y + xf[4 * i + 2] * hi.x + xf[4 * i + 3] * hi.y;
;         }
;         part[u] = d;
;       }
;       float q4[4], r2[2], h;
; #pragma unroll
;       for (int j = 0; j < 4; ++j) {
;         float mine = b5 ? part[j + 4] : part[j];
;         float other = b5 ? part[j] : part[j + 4];
;         q4[j] = mine + __shfl_xor(other, 32);
;       }
; #pragma unroll
;       for (int j = 0; j < 2; ++j) {
;         float mine = b4 ? q4[j + 2] : q4[j];
;         float other = b4 ? q4[j] : q4[j + 2];
;         r2[j] = mine + __shfl_xor(other, 16);
;       }
;       {
;         float mine = b3 ? r2[1] : r2[0];
;         float other = b3 ? r2[0] : r2[1];
;         h = mine + __shfl_xor(other, 8);
;       }
;       h += __shfl_xor(h, 4);
;       h += __shfl_xor(h, 2);
;       h += __shfl_xor(h, 1);
	v_pk_fma_f32 v[222:223], v[124:125], v[218:219], v[222:223]
	v_pk_fma_f32 v[224:225], v[126:127], v[220:221], v[224:225]
	v_pk_add_f32 v[222:223], v[222:223], v[224:225]
	s_nop 0
	v_add_f32_e32 v229, v222, v223
	v_cvt_pk_f32_fp8_e32 v[214:215], v192
	v_cvt_pk_f32_fp8_sdwa v[216:217], v192 src0_sel:WORD_1
	v_cvt_pk_f32_fp8_e32 v[218:219], v193
	v_cvt_pk_f32_fp8_sdwa v[220:221], v193 src0_sel:WORD_1
	v_pk_mul_f32 v[222:223], v[112:113], v[214:215]
	v_pk_mul_f32 v[224:225], v[114:115], v[216:217]
	v_cvt_pk_f32_fp8_e32 v[214:215], v194
	v_cvt_pk_f32_fp8_sdwa v[216:217], v194 src0_sel:WORD_1
	v_pk_fma_f32 v[222:223], v[116:117], v[218:219], v[222:223]
	v_pk_fma_f32 v[224:225], v[118:119], v[220:221], v[224:225]
	v_cvt_pk_f32_fp8_e32 v[218:219], v195
	v_cvt_pk_f32_fp8_sdwa v[220:221], v195 src0_sel:WORD_1
	v_pk_fma_f32 v[222:223], v[120:121], v[214:215], v[222:223]
	v_pk_fma_f32 v[224:225], v[122:123], v[216:217], v[224:225]
	v_pk_fma_f32 v[222:223], v[124:125], v[218:219], v[222:223]
	v_pk_fma_f32 v[224:225], v[126:127], v[220:221], v[224:225]
	v_pk_add_f32 v[222:223], v[222:223], v[224:225]
	s_nop 0
	v_add_f32_e32 v230, v222, v223
	v_cvt_pk_f32_fp8_e32 v[214:215], v196
	v_cvt_pk_f32_fp8_sdwa v[216:217], v196 src0_sel:WORD_1
	v_cvt_pk_f32_fp8_e32 v[218:219], v197
	v_cvt_pk_f32_fp8_sdwa v[220:221], v197 src0_sel:WORD_1
	v_pk_mul_f32 v[222:223], v[112:113], v[214:215]
	v_pk_mul_f32 v[224:225], v[114:115], v[216:217]
	v_cvt_pk_f32_fp8_e32 v[214:215], v198
	v_cvt_pk_f32_fp8_sdwa v[216:217], v198 src0_sel:WORD_1
	v_pk_fma_f32 v[222:223], v[116:117], v[218:219], v[222:223]
	v_pk_fma_f32 v[224:225], v[118:119], v[220:221], v[224:225]
	v_cvt_pk_f32_fp8_e32 v[218:219], v199
	v_cvt_pk_f32_fp8_sdwa v[220:221], v199 src0_sel:WORD_1
	v_pk_fma_f32 v[222:223], v[120:121], v[214:215], v[222:223]
	v_pk_fma_f32 v[224:225], v[122:123], v[216:217], v[224:225]
	v_pk_fma_f32 v[222:223], v[124:125], v[218:219], v[222:223]
	v_pk_fma_f32 v[224:225], v[126:127], v[220:221], v[224:225]
	v_pk_add_f32 v[222:223], v[222:223], v[224:225]
	s_nop 0
	v_add_f32_e32 v231, v222, v223
	v_cvt_pk_f32_fp8_e32 v[214:215], v200
	v_cvt_pk_f32_fp8_sdwa v[216:217], v200 src0_sel:WORD_1
	v_cvt_pk_f32_fp8_e32 v[218:219], v201
	v_cvt_pk_f32_fp8_sdwa v[220:221], v201 src0_sel:WORD_1
	v_pk_mul_f32 v[222:223], v[112:113], v[214:215]
	v_pk_mul_f32 v[224:225], v[114:115], v[216:217]
	v_cvt_pk_f32_fp8_e32 v[214:215], v202
	v_cvt_pk_f32_fp8_sdwa v[216:217], v202 src0_sel:WORD_1
	v_pk_fma_f32 v[222:223], v[116:117], v[218:219], v[222:223]
	v_pk_fma_f32 v[224:225], v[118:119], v[220:221], v[224:225]
	v_cvt_pk_f32_fp8_e32 v[218:219], v203
	v_cvt_pk_f32_fp8_sdwa v[220:221], v203 src0_sel:WORD_1
	v_pk_fma_f32 v[222:223], v[120:121], v[214:215], v[222:223]
	v_pk_fma_f32 v[224:225], v[122:123], v[216:217], v[224:225]
	v_pk_fma_f32 v[222:223], v[124:125], v[218:219], v[222:223]
	v_pk_fma_f32 v[224:225], v[126:127], v[220:221], v[224:225]
	v_pk_add_f32 v[222:223], v[222:223], v[224:225]
	s_nop 0
	v_add_f32_e32 v232, v222, v223
	v_cvt_pk_f32_fp8_e32 v[214:215], v204
	v_cvt_pk_f32_fp8_sdwa v[216:217], v204 src0_sel:WORD_1
	v_cvt_pk_f32_fp8_e32 v[218:219], v205
	v_cvt_pk_f32_fp8_sdwa v[220:221], v205 src0_sel:WORD_1
	v_pk_mul_f32 v[222:223], v[112:113], v[214:215]
	v_pk_mul_f32 v[224:225], v[114:115], v[216:217]
	v_cvt_pk_f32_fp8_e32 v[214:215], v206
	v_cvt_pk_f32_fp8_sdwa v[216:217], v206 src0_sel:WORD_1
	v_pk_fma_f32 v[222:223], v[116:117], v[218:219], v[222:223]
	v_pk_fma_f32 v[224:225], v[118:119], v[220:221], v[224:225]
	v_cvt_pk_f32_fp8_e32 v[218:219], v207
	v_cvt_pk_f32_fp8_sdwa v[220:221], v207 src0_sel:WORD_1
	v_pk_fma_f32 v[222:223], v[120:121], v[214:215], v[222:223]
	v_pk_fma_f32 v[224:225], v[122:123], v[216:217], v[224:225]
	v_pk_fma_f32 v[222:223], v[124:125], v[218:219], v[222:223]
	v_pk_fma_f32 v[224:225], v[126:127], v[220:221], v[224:225]
	v_pk_add_f32 v[222:223], v[222:223], v[224:225]
	s_nop 0
	v_add_f32_e32 v233, v222, v223
	v_permlane32_swap_b32_e32 v226, v230
	v_permlane32_swap_b32_e32 v227, v231
	v_permlane32_swap_b32_e32 v228, v232
	v_permlane32_swap_b32_e32 v229, v233
	v_add_f32_e32 v226, v226, v230
	v_add_f32_e32 v228, v228, v232
	v_add_f32_e32 v227, v227, v231
	v_add_f32_e32 v229, v229, v233
	s_nop 1
	v_permlane16_swap_b32_e32 v226, v228
	v_permlane16_swap_b32_e32 v227, v229
	v_add_f32_e32 v226, v226, v228
	v_add_f32_e32 v227, v227, v229
	s_nop 0
	v_cndmask_b32_e64 v230, v226, v227, s[24:25]
	v_cndmask_b32_e64 v231, v227, v226, s[24:25]
	s_nop 1
	v_add_f32_dpp v232, v231, v230 row_ror:8 row_mask:0xf bank_mask:0xf
	s_nop 1
	v_add_f32_dpp v233, v232, v232 quad_perm:[1,0,3,2] row_mask:0xf bank_mask:0xf
	s_nop 1
	v_add_f32_dpp v232, v233, v233 quad_perm:[2,3,0,1] row_mask:0xf bank_mask:0xf
	s_nop 1
	v_add_f32_dpp v233, v232, v232 row_half_mirror row_mask:0xf bank_mask:0xf
	ds_write_b32 v235, v233 offset:36384
	v_add_u32_e32 v235, 64, v235
	s_add_u32 s12, s12, 1
	s_cmp_lt_u32 s12, 8
	s_cbranch_scc1 .Lup_k
; DI float gelu_exact(float x) { return 0.5f * x * (1.f + erff(x * 0.7071067811865476f)); }
; template <bool STORE>
; DI void peer_item(const Params& p, int item, char* smem) {
;     ...
;       const int emine = e_s[tl * 128 + k + (lane >> 3)];
;       const float gmine = g_s[tl * 128 + k + (lane >> 3)];
;       const float su = SU[emine], sv = SV[emine];
;     ...
;       const float amine = gelu_exact(h * su) * gmine * sv;
;       if ((lane & 7) == 0) {
;         EG[tok * 128 + k + (lane >> 3)] = emine;
;         AG[tok * 128 + k + (lane >> 3)] = amine;
;       }
	s_waitcnt vmcnt(0) lgkmcnt(0)
	s_lshl_b32 s13, s14, 9
	s_add_u32 s26, s4, s13
	s_addc_u32 s27, s5, 0
	s_add_u32 s28, s6, s13
	s_addc_u32 s29, s7, 0
	ds_read_b32 v0, v237 offset:32768
	ds_read_b32 v1, v237 offset:33024
	ds_read_b32 v2, v237 offset:0
	ds_read_b32 v3, v237 offset:256
	ds_read_b32 v4, v237 offset:16384
	ds_read_b32 v5, v237 offset:16640
	ds_read_b32 v16, v237 offset:33280
	ds_read_b32 v17, v237 offset:33536
	ds_read_b32 v18, v237 offset:512
	ds_read_b32 v19, v237 offset:768
	ds_read_b32 v20, v237 offset:16896
	ds_read_b32 v21, v237 offset:17152
	ds_read_b32 v32, v237 offset:33792
	ds_read_b32 v33, v237 offset:34048
	ds_read_b32 v34, v237 offset:1024
	ds_read_b32 v35, v237 offset:1280
	ds_read_b32 v36, v237 offset:17408
	ds_read_b32 v37, v237 offset:17664
	ds_read_b32 v48, v237 offset:34304
	ds_read_b32 v49, v237 offset:34560
	ds_read_b32 v50, v237 offset:1536
	ds_read_b32 v51, v237 offset:1792
	ds_read_b32 v52, v237 offset:17920
	ds_read_b32 v53, v237 offset:18176
	ds_read_b32 v64, v237 offset:34816
	ds_read_b32 v65, v237 offset:35072
	ds_read_b32 v66, v237 offset:2048
	ds_read_b32 v67, v237 offset:2304
	ds_read_b32 v68, v237 offset:18432
	ds_read_b32 v69, v237 offset:18688
	ds_read_b32 v80, v237 offset:35328
	ds_read_b32 v81, v237 offset:35584
	ds_read_b32 v82, v237 offset:2560
	ds_read_b32 v83, v237 offset:2816
	ds_read_b32 v84, v237 offset:18944
	ds_read_b32 v85, v237 offset:19200
	ds_read_b32 v96, v237 offset:35840
	ds_read_b32 v97, v237 offset:36096
	ds_read_b32 v98, v237 offset:3072
	ds_read_b32 v99, v237 offset:3328
	ds_read_b32 v100, v237 offset:19456
	ds_read_b32 v101, v237 offset:19712
	ds_read_b32 v112, v237 offset:36352
	ds_read_b32 v113, v237 offset:36608
	ds_read_b32 v114, v237 offset:3584
	ds_read_b32 v115, v237 offset:3840
	ds_read_b32 v116, v237 offset:19968
	ds_read_b32 v117, v237 offset:20224
	s_lshl_b32 s13, s14, 5
	s_add_u32 s32, s56, 0x9a80200
	s_addc_u32 s33, s57, 0
	s_add_u32 s32, s32, s13
	s_addc_u32 s33, s33, 0
	v_mov_b32_e32 v208, 0
	global_load_dwordx4 v[12:15], v208, s[32:33] offset:0
	global_load_dwordx4 v[152:155], v208, s[32:33] offset:16
	global_load_dwordx4 v[28:31], v208, s[32:33] offset:32
	global_load_dwordx4 v[156:159], v208, s[32:33] offset:48
	global_load_dwordx4 v[44:47], v208, s[32:33] offset:64
	global_load_dwordx4 v[160:163], v208, s[32:33] offset:80
	global_load_dwordx4 v[60:63], v208, s[32:33] offset:96
	global_load_dwordx4 v[164:167], v208, s[32:33] offset:112
	global_load_dwordx4 v[76:79], v208, s[32:33] offset:128
	global_load_dwordx4 v[168:171], v208, s[32:33] offset:144
	global_load_dwordx4 v[92:95], v208, s[32:33] offset:160
	global_load_dwordx4 v[172:175], v208, s[32:33] offset:176
	global_load_dwordx4 v[108:111], v208, s[32:33] offset:192
	global_load_dwordx4 v[176:179], v208, s[32:33] offset:208
	global_load_dwordx4 v[124:127], v208, s[32:33] offset:224
	global_load_dwordx4 v[180:183], v208, s[32:33] offset:240
	s_waitcnt lgkmcnt(15)
	v_lshlrev_b32_e32 v10, 3, v2
	v_lshlrev_b32_e32 v11, 3, v3
	global_load_dwordx2 v[6:7], v10, s[8:9]
	global_load_dwordx2 v[8:9], v11, s[8:9]
	s_waitcnt lgkmcnt(15)
	v_lshlrev_b32_e32 v26, 3, v18
	v_lshlrev_b32_e32 v27, 3, v19
	global_load_dwordx2 v[22:23], v26, s[8:9]
	global_load_dwordx2 v[24:25], v27, s[8:9]
	s_waitcnt lgkmcnt(15)
	v_lshlrev_b32_e32 v42, 3, v34
	v_lshlrev_b32_e32 v43, 3, v35
	global_load_dwordx2 v[38:39], v42, s[8:9]
	global_load_dwordx2 v[40:41], v43, s[8:9]
	s_waitcnt lgkmcnt(15)
	v_lshlrev_b32_e32 v58, 3, v50
	v_lshlrev_b32_e32 v59, 3, v51
	global_load_dwordx2 v[54:55], v58, s[8:9]
	global_load_dwordx2 v[56:57], v59, s[8:9]
	s_waitcnt lgkmcnt(15)
	v_lshlrev_b32_e32 v74, 3, v66
	v_lshlrev_b32_e32 v75, 3, v67
	global_load_dwordx2 v[70:71], v74, s[8:9]
	global_load_dwordx2 v[72:73], v75, s[8:9]
	s_waitcnt lgkmcnt(12)
	v_lshlrev_b32_e32 v90, 3, v82
	v_lshlrev_b32_e32 v91, 3, v83
	global_load_dwordx2 v[86:87], v90, s[8:9]
	global_load_dwordx2 v[88:89], v91, s[8:9]
	s_waitcnt lgkmcnt(6)
	v_lshlrev_b32_e32 v106, 3, v98
	v_lshlrev_b32_e32 v107, 3, v99
	global_load_dwordx2 v[102:103], v106, s[8:9]
	global_load_dwordx2 v[104:105], v107, s[8:9]
	s_waitcnt lgkmcnt(0)
	v_lshlrev_b32_e32 v122, 3, v114
	v_lshlrev_b32_e32 v123, 3, v115
	global_load_dwordx2 v[118:119], v122, s[8:9]
	global_load_dwordx2 v[120:121], v123, s[8:9]
	s_waitcnt vmcnt(14)
; DI float gelu_exact(float x) { return 0.5f * x * (1.f + erff(x * 0.7071067811865476f)); }
; template <bool STORE>
; DI void peer_item(const Params& p, int item, char* smem) {
;     ...
;       const float amine = gelu_exact(h * su) * gmine * sv;
;       if ((lane & 7) == 0) {
;         EG[tok * 128 + k + (lane >> 3)] = emine;
;         AG[tok * 128 + k + (lane >> 3)] = amine;
;       }
	v_pk_add_f32 v[12:13], v[12:13], v[14:15]
	v_pk_add_f32 v[152:153], v[152:153], v[154:155]
	v_mov_b32_e32 v14, 0x358637bd
	v_pk_add_f32 v[12:13], v[12:13], v[152:153]
	s_nop 0
	v_add_f32_e32 v12, v12, v13
	s_nop 0
	v_fmamk_f32 v12, v12, 0x3a800000, v14
	s_nop 0
	v_rsq_f32_e32 v12, v12
	s_nop 1
	v_mul_f32_e32 v6, v6, v12
	v_mul_f32_e32 v8, v8, v12
	v_mul_f32_e32 v144, v6, v0
	v_mul_f32_e32 v145, 0x3f3504f3, v144
	v_mov_b32_e32 v146, 0xb9c68948
	v_fma_f32 v146, |v145|, s80, v146
	v_fma_f32 v146, |v145|, v146, s81
	v_fma_f32 v146, |v145|, v146, s82
	v_fma_f32 v146, |v145|, v146, s83
	v_fma_f32 v146, |v145|, v146, s84
	v_fma_f32 v146, |v145|, v146, s85
	v_fma_f32 v146, |v145|, v146, |v145|
	v_mul_f32_e32 v147, 0xbfb8aa3b, v146
	v_fma_f32 v148, v146, s86, -v147
	v_rndne_f32_e32 v149, v147
	v_fmac_f32_e32 v148, 0xb2a5705f, v146
	v_sub_f32_e32 v147, v147, v149
	v_add_f32_e32 v147, v147, v148
	v_cvt_i32_f32_e32 v148, v149
	v_exp_f32_e32 v147, v147
	v_cmp_nlt_f32_e32 vcc, s87, v146
	v_ldexp_f32 v147, v147, v148
	s_nop 0
	v_cndmask_b32_e32 v147, 0, v147, vcc
	v_cmp_ngt_f32_e32 vcc, s88, v146
	v_mov_b32_e32 v148, 0x7f800000
	s_nop 0
	v_cndmask_b32_e32 v147, v148, v147, vcc
	v_sub_f32_e32 v147, 1.0, v147
	v_mul_f32_e32 v148, v145, v145
	v_mov_b32_e32 v149, 0x3ba10414
	v_fmamk_f32 v149, v148, 0xba1345e1, v149
	v_fmaak_f32 v149, v148, v149, 0xbcdac9b8
	v_fmaak_f32 v149, v148, v149, 0x3de703be
	v_fmaak_f32 v149, v148, v149, 0xbec09330
	v_fmaak_f32 v149, v148, v149, 0x3e0375d0
	v_fma_f32 v149, |v145|, v149, |v145|
	v_cmp_nlt_f32_e64 vcc, |v145|, 1.0
	s_nop 1
	v_cndmask_b32_e32 v147, v149, v147, vcc
	v_bfi_b32 v147, s89, v147, v145
	v_mul_f32_e32 v144, 0.5, v144
	v_add_f32_e32 v147, 1.0, v147
	v_mul_f32_e32 v144, v144, v147
	v_mul_f32_e32 v144, v4, v144
	v_mul_f32_e32 v0, v7, v144
	v_mul_f32_e32 v144, v8, v1
	v_mul_f32_e32 v145, 0x3f3504f3, v144
	v_mov_b32_e32 v146, 0xb9c68948
	v_fma_f32 v146, |v145|, s80, v146
	v_fma_f32 v146, |v145|, v146, s81
	v_fma_f32 v146, |v145|, v146, s82
	v_fma_f32 v146, |v145|, v146, s83
	v_fma_f32 v146, |v145|, v146, s84
	v_fma_f32 v146, |v145|, v146, s85
	v_fma_f32 v146, |v145|, v146, |v145|
	v_mul_f32_e32 v147, 0xbfb8aa3b, v146
	v_fma_f32 v148, v146, s86, -v147
	v_rndne_f32_e32 v149, v147
	v_fmac_f32_e32 v148, 0xb2a5705f, v146
	v_sub_f32_e32 v147, v147, v149
	v_add_f32_e32 v147, v147, v148
	v_cvt_i32_f32_e32 v148, v149
	v_exp_f32_e32 v147, v147
	v_cmp_nlt_f32_e32 vcc, s87, v146
	v_ldexp_f32 v147, v147, v148
	s_nop 0
	v_cndmask_b32_e32 v147, 0, v147, vcc
	v_cmp_ngt_f32_e32 vcc, s88, v146
	v_mov_b32_e32 v148, 0x7f800000
	s_nop 0
	v_cndmask_b32_e32 v147, v148, v147, vcc
	v_sub_f32_e32 v147, 1.0, v147
	v_mul_f32_e32 v148, v145, v145
	v_mov_b32_e32 v149, 0x3ba10414
	v_fmamk_f32 v149, v148, 0xba1345e1, v149
	v_fmaak_f32 v149, v148, v149, 0xbcdac9b8
	v_fmaak_f32 v149, v148, v149, 0x3de703be
	v_fmaak_f32 v149, v148, v149, 0xbec09330
	v_fmaak_f32 v149, v148, v149, 0x3e0375d0
	v_fma_f32 v149, |v145|, v149, |v145|
	v_cmp_nlt_f32_e64 vcc, |v145|, 1.0
	s_nop 1
	v_cndmask_b32_e32 v147, v149, v147, vcc
	v_bfi_b32 v147, s89, v147, v145
	v_mul_f32_e32 v144, 0.5, v144
	v_add_f32_e32 v147, 1.0, v147
	v_mul_f32_e32 v144, v144, v147
	v_mul_f32_e32 v144, v5, v144
	v_mul_f32_e32 v1, v9, v144
	global_store_dword v238, v2, s[26:27] offset:0
	global_store_dword v238, v3, s[26:27] offset:256
	global_store_dword v238, v0, s[28:29] offset:0
	global_store_dword v238, v1, s[28:29] offset:256
	s_waitcnt vmcnt(16)
	v_pk_add_f32 v[28:29], v[28:29], v[30:31]
	v_pk_add_f32 v[156:157], v[156:157], v[158:159]
	v_mov_b32_e32 v30, 0x358637bd
	v_pk_add_f32 v[28:29], v[28:29], v[156:157]
	s_nop 0
	v_add_f32_e32 v28, v28, v29
	s_nop 0
	v_fmamk_f32 v28, v28, 0x3a800000, v30
	s_nop 0
	v_rsq_f32_e32 v28, v28
	s_nop 1
	v_mul_f32_e32 v22, v22, v28
	v_mul_f32_e32 v24, v24, v28
	v_mul_f32_e32 v144, v22, v16
	v_mul_f32_e32 v145, 0x3f3504f3, v144
	v_mov_b32_e32 v146, 0xb9c68948
	v_fma_f32 v146, |v145|, s80, v146
	v_fma_f32 v146, |v145|, v146, s81
	v_fma_f32 v146, |v145|, v146, s82
	v_fma_f32 v146, |v145|, v146, s83
	v_fma_f32 v146, |v145|, v146, s84
	v_fma_f32 v146, |v145|, v146, s85
	v_fma_f32 v146, |v145|, v146, |v145|
	v_mul_f32_e32 v147, 0xbfb8aa3b, v146
	v_fma_f32 v148, v146, s86, -v147
	v_rndne_f32_e32 v149, v147
	v_fmac_f32_e32 v148, 0xb2a5705f, v146
	v_sub_f32_e32 v147, v147, v149
	v_add_f32_e32 v147, v147, v148
	v_cvt_i32_f32_e32 v148, v149
	v_exp_f32_e32 v147, v147
	v_cmp_nlt_f32_e32 vcc, s87, v146
	v_ldexp_f32 v147, v147, v148
	s_nop 0
	v_cndmask_b32_e32 v147, 0, v147, vcc
	v_cmp_ngt_f32_e32 vcc, s88, v146
	v_mov_b32_e32 v148, 0x7f800000
	s_nop 0
	v_cndmask_b32_e32 v147, v148, v147, vcc
	v_sub_f32_e32 v147, 1.0, v147
	v_mul_f32_e32 v148, v145, v145
	v_mov_b32_e32 v149, 0x3ba10414
	v_fmamk_f32 v149, v148, 0xba1345e1, v149
	v_fmaak_f32 v149, v148, v149, 0xbcdac9b8
	v_fmaak_f32 v149, v148, v149, 0x3de703be
	v_fmaak_f32 v149, v148, v149, 0xbec09330
	v_fmaak_f32 v149, v148, v149, 0x3e0375d0
	v_fma_f32 v149, |v145|, v149, |v145|
	v_cmp_nlt_f32_e64 vcc, |v145|, 1.0
	s_nop 1
	v_cndmask_b32_e32 v147, v149, v147, vcc
	v_bfi_b32 v147, s89, v147, v145
	v_mul_f32_e32 v144, 0.5, v144
	v_add_f32_e32 v147, 1.0, v147
	v_mul_f32_e32 v144, v144, v147
	v_mul_f32_e32 v144, v20, v144
	v_mul_f32_e32 v16, v23, v144
	v_mul_f32_e32 v144, v24, v17
	v_mul_f32_e32 v145, 0x3f3504f3, v144
	v_mov_b32_e32 v146, 0xb9c68948
	v_fma_f32 v146, |v145|, s80, v146
	v_fma_f32 v146, |v145|, v146, s81
	v_fma_f32 v146, |v145|, v146, s82
	v_fma_f32 v146, |v145|, v146, s83
	v_fma_f32 v146, |v145|, v146, s84
	v_fma_f32 v146, |v145|, v146, s85
	v_fma_f32 v146, |v145|, v146, |v145|
	v_mul_f32_e32 v147, 0xbfb8aa3b, v146
	v_fma_f32 v148, v146, s86, -v147
	v_rndne_f32_e32 v149, v147
	v_fmac_f32_e32 v148, 0xb2a5705f, v146
	v_sub_f32_e32 v147, v147, v149
	v_add_f32_e32 v147, v147, v148
	v_cvt_i32_f32_e32 v148, v149
	v_exp_f32_e32 v147, v147
	v_cmp_nlt_f32_e32 vcc, s87, v146
	v_ldexp_f32 v147, v147, v148
	s_nop 0
	v_cndmask_b32_e32 v147, 0, v147, vcc
	v_cmp_ngt_f32_e32 vcc, s88, v146
	v_mov_b32_e32 v148, 0x7f800000
	s_nop 0
	v_cndmask_b32_e32 v147, v148, v147, vcc
	v_sub_f32_e32 v147, 1.0, v147
	v_mul_f32_e32 v148, v145, v145
	v_mov_b32_e32 v149, 0x3ba10414
	v_fmamk_f32 v149, v148, 0xba1345e1, v149
	v_fmaak_f32 v149, v148, v149, 0xbcdac9b8
	v_fmaak_f32 v149, v148, v149, 0x3de703be
	v_fmaak_f32 v149, v148, v149, 0xbec09330
	v_fmaak_f32 v149, v148, v149, 0x3e0375d0
	v_fma_f32 v149, |v145|, v149, |v145|
	v_cmp_nlt_f32_e64 vcc, |v145|, 1.0
	s_nop 1
	v_cndmask_b32_e32 v147, v149, v147, vcc
	v_bfi_b32 v147, s89, v147, v145
	v_mul_f32_e32 v144, 0.5, v144
	v_add_f32_e32 v147, 1.0, v147
	v_mul_f32_e32 v144, v144, v147
	v_mul_f32_e32 v144, v21, v144
	v_mul_f32_e32 v17, v25, v144
	global_store_dword v238, v18, s[26:27] offset:512
	global_store_dword v238, v19, s[26:27] offset:768
	global_store_dword v238, v16, s[28:29] offset:512
	global_store_dword v238, v17, s[28:29] offset:768
	s_waitcnt vmcnt(18)
; DI float gelu_exact(float x) { return 0.5f * x * (1.f + erff(x * 0.7071067811865476f)); }
; template <bool STORE>
; DI void peer_item(const Params& p, int item, char* smem) {
;     ...
;       const float amine = gelu_exact(h * su) * gmine * sv;
;       if ((lane & 7) == 0) {
;         EG[tok * 128 + k + (lane >> 3)] = emine;
;         AG[tok * 128 + k + (lane >> 3)] = amine;
;       }
	v_pk_add_f32 v[44:45], v[44:45], v[46:47]
	v_pk_add_f32 v[160:161], v[160:161], v[162:163]
	v_mov_b32_e32 v46, 0x358637bd
	v_pk_add_f32 v[44:45], v[44:45], v[160:161]
	s_nop 0
	v_add_f32_e32 v44, v44, v45
	s_nop 0
	v_fmamk_f32 v44, v44, 0x3a800000, v46
	s_nop 0
	v_rsq_f32_e32 v44, v44
	s_nop 1
	v_mul_f32_e32 v38, v38, v44
	v_mul_f32_e32 v40, v40, v44
	v_mul_f32_e32 v144, v38, v32
	v_mul_f32_e32 v145, 0x3f3504f3, v144
	v_mov_b32_e32 v146, 0xb9c68948
	v_fma_f32 v146, |v145|, s80, v146
	v_fma_f32 v146, |v145|, v146, s81
	v_fma_f32 v146, |v145|, v146, s82
	v_fma_f32 v146, |v145|, v146, s83
	v_fma_f32 v146, |v145|, v146, s84
	v_fma_f32 v146, |v145|, v146, s85
	v_fma_f32 v146, |v145|, v146, |v145|
	v_mul_f32_e32 v147, 0xbfb8aa3b, v146
	v_fma_f32 v148, v146, s86, -v147
	v_rndne_f32_e32 v149, v147
	v_fmac_f32_e32 v148, 0xb2a5705f, v146
	v_sub_f32_e32 v147, v147, v149
	v_add_f32_e32 v147, v147, v148
	v_cvt_i32_f32_e32 v148, v149
	v_exp_f32_e32 v147, v147
	v_cmp_nlt_f32_e32 vcc, s87, v146
	v_ldexp_f32 v147, v147, v148
	s_nop 0
	v_cndmask_b32_e32 v147, 0, v147, vcc
	v_cmp_ngt_f32_e32 vcc, s88, v146
	v_mov_b32_e32 v148, 0x7f800000
	s_nop 0
	v_cndmask_b32_e32 v147, v148, v147, vcc
	v_sub_f32_e32 v147, 1.0, v147
	v_mul_f32_e32 v148, v145, v145
	v_mov_b32_e32 v149, 0x3ba10414
	v_fmamk_f32 v149, v148, 0xba1345e1, v149
	v_fmaak_f32 v149, v148, v149, 0xbcdac9b8
	v_fmaak_f32 v149, v148, v149, 0x3de703be
	v_fmaak_f32 v149, v148, v149, 0xbec09330
	v_fmaak_f32 v149, v148, v149, 0x3e0375d0
	v_fma_f32 v149, |v145|, v149, |v145|
	v_cmp_nlt_f32_e64 vcc, |v145|, 1.0
	s_nop 1
	v_cndmask_b32_e32 v147, v149, v147, vcc
	v_bfi_b32 v147, s89, v147, v145
	v_mul_f32_e32 v144, 0.5, v144
	v_add_f32_e32 v147, 1.0, v147
	v_mul_f32_e32 v144, v144, v147
	v_mul_f32_e32 v144, v36, v144
	v_mul_f32_e32 v32, v39, v144
	v_mul_f32_e32 v144, v40, v33
	v_mul_f32_e32 v145, 0x3f3504f3, v144
	v_mov_b32_e32 v146, 0xb9c68948
	v_fma_f32 v146, |v145|, s80, v146
	v_fma_f32 v146, |v145|, v146, s81
	v_fma_f32 v146, |v145|, v146, s82
	v_fma_f32 v146, |v145|, v146, s83
	v_fma_f32 v146, |v145|, v146, s84
	v_fma_f32 v146, |v145|, v146, s85
	v_fma_f32 v146, |v145|, v146, |v145|
	v_mul_f32_e32 v147, 0xbfb8aa3b, v146
	v_fma_f32 v148, v146, s86, -v147
	v_rndne_f32_e32 v149, v147
	v_fmac_f32_e32 v148, 0xb2a5705f, v146
	v_sub_f32_e32 v147, v147, v149
	v_add_f32_e32 v147, v147, v148
	v_cvt_i32_f32_e32 v148, v149
	v_exp_f32_e32 v147, v147
	v_cmp_nlt_f32_e32 vcc, s87, v146
	v_ldexp_f32 v147, v147, v148
	s_nop 0
	v_cndmask_b32_e32 v147, 0, v147, vcc
	v_cmp_ngt_f32_e32 vcc, s88, v146
	v_mov_b32_e32 v148, 0x7f800000
	s_nop 0
	v_cndmask_b32_e32 v147, v148, v147, vcc
	v_sub_f32_e32 v147, 1.0, v147
	v_mul_f32_e32 v148, v145, v145
	v_mov_b32_e32 v149, 0x3ba10414
	v_fmamk_f32 v149, v148, 0xba1345e1, v149
	v_fmaak_f32 v149, v148, v149, 0xbcdac9b8
	v_fmaak_f32 v149, v148, v149, 0x3de703be
	v_fmaak_f32 v149, v148, v149, 0xbec09330
	v_fmaak_f32 v149, v148, v149, 0x3e0375d0
	v_fma_f32 v149, |v145|, v149, |v145|
	v_cmp_nlt_f32_e64 vcc, |v145|, 1.0
	s_nop 1
	v_cndmask_b32_e32 v147, v149, v147, vcc
	v_bfi_b32 v147, s89, v147, v145
	v_mul_f32_e32 v144, 0.5, v144
	v_add_f32_e32 v147, 1.0, v147
	v_mul_f32_e32 v144, v144, v147
	v_mul_f32_e32 v144, v37, v144
	v_mul_f32_e32 v33, v41, v144
	global_store_dword v238, v34, s[26:27] offset:1024
	global_store_dword v238, v35, s[26:27] offset:1280
	global_store_dword v238, v32, s[28:29] offset:1024
	global_store_dword v238, v33, s[28:29] offset:1280
	s_waitcnt vmcnt(20)
	v_pk_add_f32 v[60:61], v[60:61], v[62:63]
	v_pk_add_f32 v[164:165], v[164:165], v[166:167]
	v_mov_b32_e32 v62, 0x358637bd
	v_pk_add_f32 v[60:61], v[60:61], v[164:165]
	s_nop 0
	v_add_f32_e32 v60, v60, v61
	s_nop 0
	v_fmamk_f32 v60, v60, 0x3a800000, v62
	s_nop 0
	v_rsq_f32_e32 v60, v60
	s_nop 1
	v_mul_f32_e32 v54, v54, v60
	v_mul_f32_e32 v56, v56, v60
	v_mul_f32_e32 v144, v54, v48
	v_mul_f32_e32 v145, 0x3f3504f3, v144
	v_mov_b32_e32 v146, 0xb9c68948
	v_fma_f32 v146, |v145|, s80, v146
	v_fma_f32 v146, |v145|, v146, s81
	v_fma_f32 v146, |v145|, v146, s82
	v_fma_f32 v146, |v145|, v146, s83
	v_fma_f32 v146, |v145|, v146, s84
	v_fma_f32 v146, |v145|, v146, s85
	v_fma_f32 v146, |v145|, v146, |v145|
	v_mul_f32_e32 v147, 0xbfb8aa3b, v146
	v_fma_f32 v148, v146, s86, -v147
	v_rndne_f32_e32 v149, v147
	v_fmac_f32_e32 v148, 0xb2a5705f, v146
	v_sub_f32_e32 v147, v147, v149
	v_add_f32_e32 v147, v147, v148
	v_cvt_i32_f32_e32 v148, v149
	v_exp_f32_e32 v147, v147
	v_cmp_nlt_f32_e32 vcc, s87, v146
	v_ldexp_f32 v147, v147, v148
	s_nop 0
	v_cndmask_b32_e32 v147, 0, v147, vcc
	v_cmp_ngt_f32_e32 vcc, s88, v146
	v_mov_b32_e32 v148, 0x7f800000
	s_nop 0
	v_cndmask_b32_e32 v147, v148, v147, vcc
	v_sub_f32_e32 v147, 1.0, v147
	v_mul_f32_e32 v148, v145, v145
	v_mov_b32_e32 v149, 0x3ba10414
	v_fmamk_f32 v149, v148, 0xba1345e1, v149
	v_fmaak_f32 v149, v148, v149, 0xbcdac9b8
	v_fmaak_f32 v149, v148, v149, 0x3de703be
	v_fmaak_f32 v149, v148, v149, 0xbec09330
	v_fmaak_f32 v149, v148, v149, 0x3e0375d0
	v_fma_f32 v149, |v145|, v149, |v145|
	v_cmp_nlt_f32_e64 vcc, |v145|, 1.0
	s_nop 1
	v_cndmask_b32_e32 v147, v149, v147, vcc
	v_bfi_b32 v147, s89, v147, v145
	v_mul_f32_e32 v144, 0.5, v144
	v_add_f32_e32 v147, 1.0, v147
	v_mul_f32_e32 v144, v144, v147
	v_mul_f32_e32 v144, v52, v144
	v_mul_f32_e32 v48, v55, v144
	v_mul_f32_e32 v144, v56, v49
	v_mul_f32_e32 v145, 0x3f3504f3, v144
	v_mov_b32_e32 v146, 0xb9c68948
	v_fma_f32 v146, |v145|, s80, v146
	v_fma_f32 v146, |v145|, v146, s81
	v_fma_f32 v146, |v145|, v146, s82
	v_fma_f32 v146, |v145|, v146, s83
	v_fma_f32 v146, |v145|, v146, s84
	v_fma_f32 v146, |v145|, v146, s85
	v_fma_f32 v146, |v145|, v146, |v145|
	v_mul_f32_e32 v147, 0xbfb8aa3b, v146
	v_fma_f32 v148, v146, s86, -v147
	v_rndne_f32_e32 v149, v147
	v_fmac_f32_e32 v148, 0xb2a5705f, v146
	v_sub_f32_e32 v147, v147, v149
	v_add_f32_e32 v147, v147, v148
	v_cvt_i32_f32_e32 v148, v149
	v_exp_f32_e32 v147, v147
	v_cmp_nlt_f32_e32 vcc, s87, v146
	v_ldexp_f32 v147, v147, v148
	s_nop 0
	v_cndmask_b32_e32 v147, 0, v147, vcc
	v_cmp_ngt_f32_e32 vcc, s88, v146
	v_mov_b32_e32 v148, 0x7f800000
	s_nop 0
	v_cndmask_b32_e32 v147, v148, v147, vcc
	v_sub_f32_e32 v147, 1.0, v147
	v_mul_f32_e32 v148, v145, v145
	v_mov_b32_e32 v149, 0x3ba10414
	v_fmamk_f32 v149, v148, 0xba1345e1, v149
	v_fmaak_f32 v149, v148, v149, 0xbcdac9b8
	v_fmaak_f32 v149, v148, v149, 0x3de703be
	v_fmaak_f32 v149, v148, v149, 0xbec09330
	v_fmaak_f32 v149, v148, v149, 0x3e0375d0
	v_fma_f32 v149, |v145|, v149, |v145|
	v_cmp_nlt_f32_e64 vcc, |v145|, 1.0
	s_nop 1
	v_cndmask_b32_e32 v147, v149, v147, vcc
	v_bfi_b32 v147, s89, v147, v145
	v_mul_f32_e32 v144, 0.5, v144
	v_add_f32_e32 v147, 1.0, v147
	v_mul_f32_e32 v144, v144, v147
	v_mul_f32_e32 v144, v53, v144
	v_mul_f32_e32 v49, v57, v144
	global_store_dword v238, v50, s[26:27] offset:1536
	global_store_dword v238, v51, s[26:27] offset:1792
	global_store_dword v238, v48, s[28:29] offset:1536
	global_store_dword v238, v49, s[28:29] offset:1792
	s_waitcnt vmcnt(22)
; DI float gelu_exact(float x) { return 0.5f * x * (1.f + erff(x * 0.7071067811865476f)); }
; template <bool STORE>
; DI void peer_item(const Params& p, int item, char* smem) {
;     ...
;       const float amine = gelu_exact(h * su) * gmine * sv;
;       if ((lane & 7) == 0) {
;         EG[tok * 128 + k + (lane >> 3)] = emine;
;         AG[tok * 128 + k + (lane >> 3)] = amine;
;       }
	v_pk_add_f32 v[76:77], v[76:77], v[78:79]
	v_pk_add_f32 v[168:169], v[168:169], v[170:171]
	v_mov_b32_e32 v78, 0x358637bd
	v_pk_add_f32 v[76:77], v[76:77], v[168:169]
	s_nop 0
	v_add_f32_e32 v76, v76, v77
	s_nop 0
	v_fmamk_f32 v76, v76, 0x3a800000, v78
	s_nop 0
	v_rsq_f32_e32 v76, v76
	s_nop 1
	v_mul_f32_e32 v70, v70, v76
	v_mul_f32_e32 v72, v72, v76
	v_mul_f32_e32 v144, v70, v64
	v_mul_f32_e32 v145, 0x3f3504f3, v144
	v_mov_b32_e32 v146, 0xb9c68948
	v_fma_f32 v146, |v145|, s80, v146
	v_fma_f32 v146, |v145|, v146, s81
	v_fma_f32 v146, |v145|, v146, s82
	v_fma_f32 v146, |v145|, v146, s83
	v_fma_f32 v146, |v145|, v146, s84
	v_fma_f32 v146, |v145|, v146, s85
	v_fma_f32 v146, |v145|, v146, |v145|
	v_mul_f32_e32 v147, 0xbfb8aa3b, v146
	v_fma_f32 v148, v146, s86, -v147
	v_rndne_f32_e32 v149, v147
	v_fmac_f32_e32 v148, 0xb2a5705f, v146
	v_sub_f32_e32 v147, v147, v149
	v_add_f32_e32 v147, v147, v148
	v_cvt_i32_f32_e32 v148, v149
	v_exp_f32_e32 v147, v147
	v_cmp_nlt_f32_e32 vcc, s87, v146
	v_ldexp_f32 v147, v147, v148
	s_nop 0
	v_cndmask_b32_e32 v147, 0, v147, vcc
	v_cmp_ngt_f32_e32 vcc, s88, v146
	v_mov_b32_e32 v148, 0x7f800000
	s_nop 0
	v_cndmask_b32_e32 v147, v148, v147, vcc
	v_sub_f32_e32 v147, 1.0, v147
	v_mul_f32_e32 v148, v145, v145
	v_mov_b32_e32 v149, 0x3ba10414
	v_fmamk_f32 v149, v148, 0xba1345e1, v149
	v_fmaak_f32 v149, v148, v149, 0xbcdac9b8
	v_fmaak_f32 v149, v148, v149, 0x3de703be
	v_fmaak_f32 v149, v148, v149, 0xbec09330
	v_fmaak_f32 v149, v148, v149, 0x3e0375d0
	v_fma_f32 v149, |v145|, v149, |v145|
	v_cmp_nlt_f32_e64 vcc, |v145|, 1.0
	s_nop 1
	v_cndmask_b32_e32 v147, v149, v147, vcc
	v_bfi_b32 v147, s89, v147, v145
	v_mul_f32_e32 v144, 0.5, v144
	v_add_f32_e32 v147, 1.0, v147
	v_mul_f32_e32 v144, v144, v147
	v_mul_f32_e32 v144, v68, v144
	v_mul_f32_e32 v64, v71, v144
	v_mul_f32_e32 v144, v72, v65
	v_mul_f32_e32 v145, 0x3f3504f3, v144
	v_mov_b32_e32 v146, 0xb9c68948
	v_fma_f32 v146, |v145|, s80, v146
	v_fma_f32 v146, |v145|, v146, s81
	v_fma_f32 v146, |v145|, v146, s82
	v_fma_f32 v146, |v145|, v146, s83
	v_fma_f32 v146, |v145|, v146, s84
	v_fma_f32 v146, |v145|, v146, s85
	v_fma_f32 v146, |v145|, v146, |v145|
	v_mul_f32_e32 v147, 0xbfb8aa3b, v146
	v_fma_f32 v148, v146, s86, -v147
	v_rndne_f32_e32 v149, v147
	v_fmac_f32_e32 v148, 0xb2a5705f, v146
	v_sub_f32_e32 v147, v147, v149
	v_add_f32_e32 v147, v147, v148
	v_cvt_i32_f32_e32 v148, v149
	v_exp_f32_e32 v147, v147
	v_cmp_nlt_f32_e32 vcc, s87, v146
	v_ldexp_f32 v147, v147, v148
	s_nop 0
	v_cndmask_b32_e32 v147, 0, v147, vcc
	v_cmp_ngt_f32_e32 vcc, s88, v146
	v_mov_b32_e32 v148, 0x7f800000
	s_nop 0
	v_cndmask_b32_e32 v147, v148, v147, vcc
	v_sub_f32_e32 v147, 1.0, v147
	v_mul_f32_e32 v148, v145, v145
	v_mov_b32_e32 v149, 0x3ba10414
	v_fmamk_f32 v149, v148, 0xba1345e1, v149
	v_fmaak_f32 v149, v148, v149, 0xbcdac9b8
	v_fmaak_f32 v149, v148, v149, 0x3de703be
	v_fmaak_f32 v149, v148, v149, 0xbec09330
	v_fmaak_f32 v149, v148, v149, 0x3e0375d0
	v_fma_f32 v149, |v145|, v149, |v145|
	v_cmp_nlt_f32_e64 vcc, |v145|, 1.0
	s_nop 1
	v_cndmask_b32_e32 v147, v149, v147, vcc
	v_bfi_b32 v147, s89, v147, v145
	v_mul_f32_e32 v144, 0.5, v144
	v_add_f32_e32 v147, 1.0, v147
	v_mul_f32_e32 v144, v144, v147
	v_mul_f32_e32 v144, v69, v144
	v_mul_f32_e32 v65, v73, v144
	global_store_dword v238, v66, s[26:27] offset:2048
	global_store_dword v238, v67, s[26:27] offset:2304
	global_store_dword v238, v64, s[28:29] offset:2048
	global_store_dword v238, v65, s[28:29] offset:2304
	s_waitcnt vmcnt(24)
	v_pk_add_f32 v[92:93], v[92:93], v[94:95]
	v_pk_add_f32 v[172:173], v[172:173], v[174:175]
	v_mov_b32_e32 v94, 0x358637bd
	v_pk_add_f32 v[92:93], v[92:93], v[172:173]
	s_nop 0
	v_add_f32_e32 v92, v92, v93
	s_nop 0
	v_fmamk_f32 v92, v92, 0x3a800000, v94
	s_nop 0
	v_rsq_f32_e32 v92, v92
	s_nop 1
	v_mul_f32_e32 v86, v86, v92
	v_mul_f32_e32 v88, v88, v92
	v_mul_f32_e32 v144, v86, v80
	v_mul_f32_e32 v145, 0x3f3504f3, v144
	v_mov_b32_e32 v146, 0xb9c68948
	v_fma_f32 v146, |v145|, s80, v146
	v_fma_f32 v146, |v145|, v146, s81
	v_fma_f32 v146, |v145|, v146, s82
	v_fma_f32 v146, |v145|, v146, s83
	v_fma_f32 v146, |v145|, v146, s84
	v_fma_f32 v146, |v145|, v146, s85
	v_fma_f32 v146, |v145|, v146, |v145|
	v_mul_f32_e32 v147, 0xbfb8aa3b, v146
	v_fma_f32 v148, v146, s86, -v147
	v_rndne_f32_e32 v149, v147
	v_fmac_f32_e32 v148, 0xb2a5705f, v146
	v_sub_f32_e32 v147, v147, v149
	v_add_f32_e32 v147, v147, v148
	v_cvt_i32_f32_e32 v148, v149
	v_exp_f32_e32 v147, v147
	v_cmp_nlt_f32_e32 vcc, s87, v146
	v_ldexp_f32 v147, v147, v148
	s_nop 0
	v_cndmask_b32_e32 v147, 0, v147, vcc
	v_cmp_ngt_f32_e32 vcc, s88, v146
	v_mov_b32_e32 v148, 0x7f800000
	s_nop 0
	v_cndmask_b32_e32 v147, v148, v147, vcc
	v_sub_f32_e32 v147, 1.0, v147
	v_mul_f32_e32 v148, v145, v145
	v_mov_b32_e32 v149, 0x3ba10414
	v_fmamk_f32 v149, v148, 0xba1345e1, v149
	v_fmaak_f32 v149, v148, v149, 0xbcdac9b8
	v_fmaak_f32 v149, v148, v149, 0x3de703be
	v_fmaak_f32 v149, v148, v149, 0xbec09330
	v_fmaak_f32 v149, v148, v149, 0x3e0375d0
	v_fma_f32 v149, |v145|, v149, |v145|
	v_cmp_nlt_f32_e64 vcc, |v145|, 1.0
	s_nop 1
	v_cndmask_b32_e32 v147, v149, v147, vcc
	v_bfi_b32 v147, s89, v147, v145
	v_mul_f32_e32 v144, 0.5, v144
	v_add_f32_e32 v147, 1.0, v147
	v_mul_f32_e32 v144, v144, v147
	v_mul_f32_e32 v144, v84, v144
	v_mul_f32_e32 v80, v87, v144
	v_mul_f32_e32 v144, v88, v81
	v_mul_f32_e32 v145, 0x3f3504f3, v144
	v_mov_b32_e32 v146, 0xb9c68948
	v_fma_f32 v146, |v145|, s80, v146
	v_fma_f32 v146, |v145|, v146, s81
	v_fma_f32 v146, |v145|, v146, s82
	v_fma_f32 v146, |v145|, v146, s83
	v_fma_f32 v146, |v145|, v146, s84
	v_fma_f32 v146, |v145|, v146, s85
	v_fma_f32 v146, |v145|, v146, |v145|
	v_mul_f32_e32 v147, 0xbfb8aa3b, v146
	v_fma_f32 v148, v146, s86, -v147
	v_rndne_f32_e32 v149, v147
	v_fmac_f32_e32 v148, 0xb2a5705f, v146
	v_sub_f32_e32 v147, v147, v149
	v_add_f32_e32 v147, v147, v148
	v_cvt_i32_f32_e32 v148, v149
	v_exp_f32_e32 v147, v147
	v_cmp_nlt_f32_e32 vcc, s87, v146
	v_ldexp_f32 v147, v147, v148
	s_nop 0
	v_cndmask_b32_e32 v147, 0, v147, vcc
	v_cmp_ngt_f32_e32 vcc, s88, v146
	v_mov_b32_e32 v148, 0x7f800000
	s_nop 0
	v_cndmask_b32_e32 v147, v148, v147, vcc
	v_sub_f32_e32 v147, 1.0, v147
	v_mul_f32_e32 v148, v145, v145
	v_mov_b32_e32 v149, 0x3ba10414
	v_fmamk_f32 v149, v148, 0xba1345e1, v149
	v_fmaak_f32 v149, v148, v149, 0xbcdac9b8
	v_fmaak_f32 v149, v148, v149, 0x3de703be
	v_fmaak_f32 v149, v148, v149, 0xbec09330
	v_fmaak_f32 v149, v148, v149, 0x3e0375d0
	v_fma_f32 v149, |v145|, v149, |v145|
	v_cmp_nlt_f32_e64 vcc, |v145|, 1.0
	s_nop 1
	v_cndmask_b32_e32 v147, v149, v147, vcc
	v_bfi_b32 v147, s89, v147, v145
	v_mul_f32_e32 v144, 0.5, v144
	v_add_f32_e32 v147, 1.0, v147
	v_mul_f32_e32 v144, v144, v147
	v_mul_f32_e32 v144, v85, v144
	v_mul_f32_e32 v81, v89, v144
	global_store_dword v238, v82, s[26:27] offset:2560
	global_store_dword v238, v83, s[26:27] offset:2816
	global_store_dword v238, v80, s[28:29] offset:2560
	global_store_dword v238, v81, s[28:29] offset:2816
	s_waitcnt vmcnt(26)
; DI float gelu_exact(float x) { return 0.5f * x * (1.f + erff(x * 0.7071067811865476f)); }
; template <bool STORE>
; DI void peer_item(const Params& p, int item, char* smem) {
;     ...
;       const float amine = gelu_exact(h * su) * gmine * sv;
;       if ((lane & 7) == 0) {
;         EG[tok * 128 + k + (lane >> 3)] = emine;
;         AG[tok * 128 + k + (lane >> 3)] = amine;
;       }
	v_pk_add_f32 v[108:109], v[108:109], v[110:111]
	v_pk_add_f32 v[176:177], v[176:177], v[178:179]
	v_mov_b32_e32 v110, 0x358637bd
	v_pk_add_f32 v[108:109], v[108:109], v[176:177]
	s_nop 0
	v_add_f32_e32 v108, v108, v109
	s_nop 0
	v_fmamk_f32 v108, v108, 0x3a800000, v110
	s_nop 0
	v_rsq_f32_e32 v108, v108
	s_nop 1
	v_mul_f32_e32 v102, v102, v108
	v_mul_f32_e32 v104, v104, v108
	v_mul_f32_e32 v144, v102, v96
	v_mul_f32_e32 v145, 0x3f3504f3, v144
	v_mov_b32_e32 v146, 0xb9c68948
	v_fma_f32 v146, |v145|, s80, v146
	v_fma_f32 v146, |v145|, v146, s81
	v_fma_f32 v146, |v145|, v146, s82
	v_fma_f32 v146, |v145|, v146, s83
	v_fma_f32 v146, |v145|, v146, s84
	v_fma_f32 v146, |v145|, v146, s85
	v_fma_f32 v146, |v145|, v146, |v145|
	v_mul_f32_e32 v147, 0xbfb8aa3b, v146
	v_fma_f32 v148, v146, s86, -v147
	v_rndne_f32_e32 v149, v147
	v_fmac_f32_e32 v148, 0xb2a5705f, v146
	v_sub_f32_e32 v147, v147, v149
	v_add_f32_e32 v147, v147, v148
	v_cvt_i32_f32_e32 v148, v149
	v_exp_f32_e32 v147, v147
	v_cmp_nlt_f32_e32 vcc, s87, v146
	v_ldexp_f32 v147, v147, v148
	s_nop 0
	v_cndmask_b32_e32 v147, 0, v147, vcc
	v_cmp_ngt_f32_e32 vcc, s88, v146
	v_mov_b32_e32 v148, 0x7f800000
	s_nop 0
	v_cndmask_b32_e32 v147, v148, v147, vcc
	v_sub_f32_e32 v147, 1.0, v147
	v_mul_f32_e32 v148, v145, v145
	v_mov_b32_e32 v149, 0x3ba10414
	v_fmamk_f32 v149, v148, 0xba1345e1, v149
	v_fmaak_f32 v149, v148, v149, 0xbcdac9b8
	v_fmaak_f32 v149, v148, v149, 0x3de703be
	v_fmaak_f32 v149, v148, v149, 0xbec09330
	v_fmaak_f32 v149, v148, v149, 0x3e0375d0
	v_fma_f32 v149, |v145|, v149, |v145|
	v_cmp_nlt_f32_e64 vcc, |v145|, 1.0
	s_nop 1
	v_cndmask_b32_e32 v147, v149, v147, vcc
	v_bfi_b32 v147, s89, v147, v145
	v_mul_f32_e32 v144, 0.5, v144
	v_add_f32_e32 v147, 1.0, v147
	v_mul_f32_e32 v144, v144, v147
	v_mul_f32_e32 v144, v100, v144
	v_mul_f32_e32 v96, v103, v144
	v_mul_f32_e32 v144, v104, v97
	v_mul_f32_e32 v145, 0x3f3504f3, v144
	v_mov_b32_e32 v146, 0xb9c68948
	v_fma_f32 v146, |v145|, s80, v146
	v_fma_f32 v146, |v145|, v146, s81
	v_fma_f32 v146, |v145|, v146, s82
	v_fma_f32 v146, |v145|, v146, s83
	v_fma_f32 v146, |v145|, v146, s84
	v_fma_f32 v146, |v145|, v146, s85
	v_fma_f32 v146, |v145|, v146, |v145|
	v_mul_f32_e32 v147, 0xbfb8aa3b, v146
	v_fma_f32 v148, v146, s86, -v147
	v_rndne_f32_e32 v149, v147
	v_fmac_f32_e32 v148, 0xb2a5705f, v146
	v_sub_f32_e32 v147, v147, v149
	v_add_f32_e32 v147, v147, v148
	v_cvt_i32_f32_e32 v148, v149
	v_exp_f32_e32 v147, v147
	v_cmp_nlt_f32_e32 vcc, s87, v146
	v_ldexp_f32 v147, v147, v148
	s_nop 0
	v_cndmask_b32_e32 v147, 0, v147, vcc
	v_cmp_ngt_f32_e32 vcc, s88, v146
	v_mov_b32_e32 v148, 0x7f800000
	s_nop 0
	v_cndmask_b32_e32 v147, v148, v147, vcc
	v_sub_f32_e32 v147, 1.0, v147
	v_mul_f32_e32 v148, v145, v145
	v_mov_b32_e32 v149, 0x3ba10414
	v_fmamk_f32 v149, v148, 0xba1345e1, v149
	v_fmaak_f32 v149, v148, v149, 0xbcdac9b8
	v_fmaak_f32 v149, v148, v149, 0x3de703be
	v_fmaak_f32 v149, v148, v149, 0xbec09330
	v_fmaak_f32 v149, v148, v149, 0x3e0375d0
	v_fma_f32 v149, |v145|, v149, |v145|
	v_cmp_nlt_f32_e64 vcc, |v145|, 1.0
	s_nop 1
	v_cndmask_b32_e32 v147, v149, v147, vcc
	v_bfi_b32 v147, s89, v147, v145
	v_mul_f32_e32 v144, 0.5, v144
	v_add_f32_e32 v147, 1.0, v147
	v_mul_f32_e32 v144, v144, v147
	v_mul_f32_e32 v144, v101, v144
	v_mul_f32_e32 v97, v105, v144
	global_store_dword v238, v98, s[26:27] offset:3072
	global_store_dword v238, v99, s[26:27] offset:3328
	global_store_dword v238, v96, s[28:29] offset:3072
	global_store_dword v238, v97, s[28:29] offset:3328
	s_waitcnt vmcnt(28)
; DI float gelu_exact(float x) { return 0.5f * x * (1.f + erff(x * 0.7071067811865476f)); }
; template <bool STORE>
; DI void peer_item(const Params& p, int item, char* smem) {
;     ...
;       const float amine = gelu_exact(h * su) * gmine * sv;
;       if ((lane & 7) == 0) {
;         EG[tok * 128 + k + (lane >> 3)] = emine;
;         AG[tok * 128 + k + (lane >> 3)] = amine;
;       }
	v_pk_add_f32 v[124:125], v[124:125], v[126:127]
	v_pk_add_f32 v[180:181], v[180:181], v[182:183]
	v_mov_b32_e32 v126, 0x358637bd
	v_pk_add_f32 v[124:125], v[124:125], v[180:181]
	s_nop 0
	v_add_f32_e32 v124, v124, v125
	s_nop 0
	v_fmamk_f32 v124, v124, 0x3a800000, v126
	s_nop 0
	v_rsq_f32_e32 v124, v124
	s_nop 1
	v_mul_f32_e32 v118, v118, v124
	v_mul_f32_e32 v120, v120, v124
	v_mul_f32_e32 v144, v118, v112
	v_mul_f32_e32 v145, 0x3f3504f3, v144
	v_mov_b32_e32 v146, 0xb9c68948
	v_fma_f32 v146, |v145|, s80, v146
	v_fma_f32 v146, |v145|, v146, s81
	v_fma_f32 v146, |v145|, v146, s82
	v_fma_f32 v146, |v145|, v146, s83
	v_fma_f32 v146, |v145|, v146, s84
	v_fma_f32 v146, |v145|, v146, s85
	v_fma_f32 v146, |v145|, v146, |v145|
	v_mul_f32_e32 v147, 0xbfb8aa3b, v146
	v_fma_f32 v148, v146, s86, -v147
	v_rndne_f32_e32 v149, v147
	v_fmac_f32_e32 v148, 0xb2a5705f, v146
	v_sub_f32_e32 v147, v147, v149
	v_add_f32_e32 v147, v147, v148
	v_cvt_i32_f32_e32 v148, v149
	v_exp_f32_e32 v147, v147
	v_cmp_nlt_f32_e32 vcc, s87, v146
	v_ldexp_f32 v147, v147, v148
	s_nop 0
	v_cndmask_b32_e32 v147, 0, v147, vcc
	v_cmp_ngt_f32_e32 vcc, s88, v146
	v_mov_b32_e32 v148, 0x7f800000
	s_nop 0
	v_cndmask_b32_e32 v147, v148, v147, vcc
	v_sub_f32_e32 v147, 1.0, v147
	v_mul_f32_e32 v148, v145, v145
	v_mov_b32_e32 v149, 0x3ba10414
	v_fmamk_f32 v149, v148, 0xba1345e1, v149
	v_fmaak_f32 v149, v148, v149, 0xbcdac9b8
	v_fmaak_f32 v149, v148, v149, 0x3de703be
	v_fmaak_f32 v149, v148, v149, 0xbec09330
	v_fmaak_f32 v149, v148, v149, 0x3e0375d0
	v_fma_f32 v149, |v145|, v149, |v145|
	v_cmp_nlt_f32_e64 vcc, |v145|, 1.0
	s_nop 1
	v_cndmask_b32_e32 v147, v149, v147, vcc
	v_bfi_b32 v147, s89, v147, v145
	v_mul_f32_e32 v144, 0.5, v144
	v_add_f32_e32 v147, 1.0, v147
	v_mul_f32_e32 v144, v144, v147
	v_mul_f32_e32 v144, v116, v144
	v_mul_f32_e32 v112, v119, v144
	v_mul_f32_e32 v144, v120, v113
	v_mul_f32_e32 v145, 0x3f3504f3, v144
	v_mov_b32_e32 v146, 0xb9c68948
	v_fma_f32 v146, |v145|, s80, v146
	v_fma_f32 v146, |v145|, v146, s81
	v_fma_f32 v146, |v145|, v146, s82
	v_fma_f32 v146, |v145|, v146, s83
	v_fma_f32 v146, |v145|, v146, s84
	v_fma_f32 v146, |v145|, v146, s85
	v_fma_f32 v146, |v145|, v146, |v145|
	v_mul_f32_e32 v147, 0xbfb8aa3b, v146
	v_fma_f32 v148, v146, s86, -v147
	v_rndne_f32_e32 v149, v147
	v_fmac_f32_e32 v148, 0xb2a5705f, v146
	v_sub_f32_e32 v147, v147, v149
	v_add_f32_e32 v147, v147, v148
	v_cvt_i32_f32_e32 v148, v149
	v_exp_f32_e32 v147, v147
	v_cmp_nlt_f32_e32 vcc, s87, v146
	v_ldexp_f32 v147, v147, v148
	s_nop 0
	v_cndmask_b32_e32 v147, 0, v147, vcc
	v_cmp_ngt_f32_e32 vcc, s88, v146
	v_mov_b32_e32 v148, 0x7f800000
	s_nop 0
	v_cndmask_b32_e32 v147, v148, v147, vcc
	v_sub_f32_e32 v147, 1.0, v147
	v_mul_f32_e32 v148, v145, v145
	v_mov_b32_e32 v149, 0x3ba10414
	v_fmamk_f32 v149, v148, 0xba1345e1, v149
	v_fmaak_f32 v149, v148, v149, 0xbcdac9b8
	v_fmaak_f32 v149, v148, v149, 0x3de703be
	v_fmaak_f32 v149, v148, v149, 0xbec09330
	v_fmaak_f32 v149, v148, v149, 0x3e0375d0
	v_fma_f32 v149, |v145|, v149, |v145|
	v_cmp_nlt_f32_e64 vcc, |v145|, 1.0
	s_nop 1
	v_cndmask_b32_e32 v147, v149, v147, vcc
	v_bfi_b32 v147, s89, v147, v145
	v_mul_f32_e32 v144, 0.5, v144
	v_add_f32_e32 v147, 1.0, v147
	v_mul_f32_e32 v144, v144, v147
	v_mul_f32_e32 v144, v117, v144
	v_mul_f32_e32 v113, v121, v144
	global_store_dword v238, v114, s[26:27] offset:3584
	global_store_dword v238, v115, s[26:27] offset:3840
	global_store_dword v238, v112, s[28:29] offset:3584
	global_store_dword v238, v113, s[28:29] offset:3840
	ds_read_b32 v3, v236 offset:512
	ds_read_b32 v53, v236 offset:768
	ds_read_b32 v64, v236 offset:1024
	ds_read_b32 v65, v236 offset:1280
	ds_read_b32 v66, v236 offset:1536
	ds_read_b32 v67, v236 offset:1792
	ds_read_b32 v68, v236 offset:2048
	ds_read_b32 v69, v236 offset:2304
	ds_read_b32 v70, v236 offset:2560
	ds_read_b32 v71, v236 offset:2816
	ds_read_b32 v72, v236 offset:3072
	ds_read_b32 v73, v236 offset:3328
	ds_read_b32 v74, v236 offset:3584
	ds_read_b32 v75, v236 offset:3840
	ds_read_b32 v76, v236 offset:4096
	ds_read_b32 v77, v236 offset:4352
	ds_read_b32 v78, v236 offset:4608
	ds_read_b32 v79, v236 offset:4864
	ds_read_b32 v80, v236 offset:5120
	ds_read_b32 v81, v236 offset:5376
	ds_read_b32 v82, v236 offset:5632
	ds_read_b32 v83, v236 offset:5888
	ds_read_b32 v96, v236 offset:6144
	ds_read_b32 v210, v236 offset:6400
	ds_read_b32 v211, v236 offset:6656
	ds_read_b32 v212, v236 offset:6912
	v_readlane_b32 s6, v254, 0
	v_readlane_b32 s7, v254, 1
	v_readlane_b32 s12, v254, 2
	v_readlane_b32 s13, v254, 3
	v_readlane_b32 s14, v254, 4
	v_readlane_b32 s15, v254, 5
	v_readlane_b32 s16, v254, 6
	v_readlane_b32 s17, v254, 7
	v_readlane_b32 s18, v254, 8
	v_readlane_b32 s19, v254, 9
	v_readlane_b32 s20, v254, 10
	v_readlane_b32 s21, v254, 11
	v_readlane_b32 s22, v254, 12
	v_readlane_b32 s23, v254, 13
	v_readlane_b32 s24, v254, 14
	v_readlane_b32 s25, v254, 15
	v_readlane_b32 s26, v254, 16
	v_readlane_b32 s27, v254, 17
	v_readlane_b32 s28, v254, 18
	v_readlane_b32 s29, v254, 19
	v_readlane_b32 s30, v254, 20
	v_readlane_b32 s31, v254, 21
	v_readlane_b32 s33, v254, 22
	v_readlane_b32 s34, v254, 23
	v_readlane_b32 s35, v254, 24
	v_readlane_b32 s36, v254, 25
	v_readlane_b32 s37, v254, 26
	v_readlane_b32 s38, v254, 27
	v_readlane_b32 s39, v254, 28
	v_readlane_b32 s40, v254, 29
	v_readlane_b32 s41, v254, 30
	v_readlane_b32 s42, v254, 31
	v_readlane_b32 s44, v254, 32
	v_readlane_b32 s45, v254, 33
	v_readlane_b32 s48, v254, 34
	v_readlane_b32 s49, v254, 35
	v_readlane_b32 s50, v254, 36
	v_readlane_b32 s51, v254, 37
	v_readlane_b32 s52, v254, 38
	v_readlane_b32 s53, v254, 39
	v_readlane_b32 s55, v254, 40
	v_readlane_b32 s60, v254, 41
	v_readlane_b32 s61, v254, 42
	v_readlane_b32 s62, v254, 43
	v_readlane_b32 s63, v254, 44
	v_readlane_b32 s66, v254, 45
	v_readlane_b32 s67, v254, 46
	v_readlane_b32 s68, v254, 47
	v_readlane_b32 s69, v254, 48
	v_readlane_b32 s74, v254, 49
	v_readlane_b32 s75, v254, 50
	v_readlane_b32 s76, v254, 51
	v_readlane_b32 s77, v254, 52
	v_readlane_b32 s78, v254, 53
	v_readlane_b32 s79, v254, 54
	v_readlane_b32 s88, v254, 55
	s_waitcnt lgkmcnt(0)
	s_nop 3
